# adds: UP header wait dropped; redundant lgkmcnt(0) behind the K-loop barriers dropped
# speedup vs baseline: 1.0138x; 1.0026x over previous
; #define PG8_STAGE(bufoff, gbase, voff) do { _Pragma("unroll") for (int _i = 0; _i < 2; ++_i) \
;         __builtin_amdgcn_global_load_lds((const unsigned*)((const char*)(gbase) + (voff)[_i]), (PG8_LAS unsigned*)(lds + (bufoff) + ldsw + _i * 8192), 16, 0, 0); } while (0)
; #define PG8_LDA(dst, b, h) do { _Pragma("unroll") for (int m = 0; m < 4; ++m) _Pragma("unroll") for (int k = 0; k < 2; ++k) dst[m][k] = *(const PG8_LAS bf16x8*)(lds + PG8_SA(b, h) + aoff + m * 2048 + k * 1024); } while (0)
; #define PG8_LDB(dst, b, h) do { _Pragma("unroll") for (int n = 0; n < 2; ++n) _Pragma("unroll") for (int k = 0; k < 2; ++k) dst[n][k] = *(const PG8_LAS bf16x8*)(lds + PG8_SB(b, h) + boff + n * 2048 + k * 1024); } while (0)
; #define PG8_MMA(ai, bj, At, Bt) do { __builtin_amdgcn_s_setprio(1); _Pragma("unroll") for (int m = 0; m < 4; ++m) _Pragma("unroll") for (int n = 0; n < 2; ++n) _Pragma("unroll") for (int k = 0; k < 2; ++k) \
;         acc[ai][bj][m][n] = __builtin_amdgcn_mfma_f32_16x16x32_bf16(Bt[n][k], At[m][k], acc[ai][bj][m][n], 0, 0, 0); __builtin_amdgcn_s_setprio(0); } while (0)
; #define PG8_WAIT_V(n) asm volatile("s_waitcnt vmcnt(" #n ")" ::: "memory")
; #define PG8_WAIT_L(n) asm volatile("s_waitcnt lgkmcnt(" #n ")" ::: "memory")
; #define PG8_BAR __builtin_amdgcn_s_barrier()
; #define PG8_SCHED __builtin_amdgcn_sched_barrier(0)
; template <class Epi, class Sched, bool ALIGN_EPI = false, bool SP2 = false, bool ACHUNK = false>
; __device__ __forceinline__ void gemm_phase(PG8_LAS unsigned char* lds, const Gemm g, const Sched& S, const Epi& E) {
;     ...
;             PG8_LDB(B0, 0, 0); PG8_LDB(B1, 0, 1); PG8_SCHED; PG8_LDA(At, 0, 0); PG8_STAGE(PG8_SA(1, 1), a1 + hstepA, voffA);
;             PG8_WAIT_V(8); PG8_WAIT_L(0); PG8_BAR; PG8_MMA(0, 0, At, B0); PG8_MMA(0, 1, At, B1); PG8_BAR; PG8_SCHED;
;             PG8_LDA(At, 0, 1); PG8_STAGE(PG8_SB(0, 0), b2, voffB); PG8_STAGE(PG8_SB(0, 1), b2 + hstepB, voffB); PG8_STAGE(PG8_SA(0, 0), a2, voffA);
.Lnl_dn:
	s_add_i32 s47, 0, 0x14000
	ds_read_b128 v[142:145], v151
	ds_read_b128 v[152:155], v151 offset:1024
	ds_read_b128 v[156:159], v151 offset:2048
	ds_read_b128 v[160:163], v151 offset:3072
	v_add_u32_e32 v151, s47, v147
	ds_read_b128 v[164:167], v151
	ds_read_b128 v[168:171], v151 offset:1024
	ds_read_b128 v[172:175], v151 offset:2048
	ds_read_b128 v[176:179], v151 offset:3072
	v_lshl_add_u64 v[192:193], s[20:21], 0, v[138:139]
	s_add_i32 m0, s23, 0xc000
	ds_read_b128 v[180:183], v150
	ds_read_b128 v[184:187], v150 offset:1024
	ds_read_b128 v[188:191], v150 offset:2048
	ds_read_b128 v[198:201], v150 offset:3072
	ds_read_b128 v[202:205], v150 offset:4096
	ds_read_b128 v[206:209], v150 offset:5120
	ds_read_b128 v[210:213], v150 offset:6144
	ds_read_b128 v[214:217], v150 offset:7168
	global_load_lds_dwordx4 v[192:193], off
	v_lshl_add_u64 v[192:193], s[20:21], 0, v[140:141]
	s_add_i32 m0, s23, 0xe000
	s_nop 0
	global_load_lds_dwordx4 v[192:193], off
	s_waitcnt vmcnt(8)
	s_waitcnt lgkmcnt(0)
	s_barrier
	s_setprio 1
	v_mfma_f32_16x16x32_bf16 v[120:123], v[142:145], v[180:183], v[120:123]
	v_mfma_f32_16x16x32_bf16 v[128:131], v[156:159], v[180:183], v[128:131]
	v_mfma_f32_16x16x32_bf16 v[104:107], v[142:145], v[188:191], v[104:107]
	v_mfma_f32_16x16x32_bf16 v[112:115], v[156:159], v[188:191], v[112:115]
	v_mfma_f32_16x16x32_bf16 v[88:91], v[142:145], v[202:205], v[88:91]
	v_mfma_f32_16x16x32_bf16 v[96:99], v[156:159], v[202:205], v[96:99]
	v_mfma_f32_16x16x32_bf16 v[72:75], v[142:145], v[210:213], v[72:75]
	v_mfma_f32_16x16x32_bf16 v[80:83], v[156:159], v[210:213], v[80:83]
	v_mfma_f32_16x16x32_bf16 v[120:123], v[152:155], v[184:187], v[120:123]
	v_mfma_f32_16x16x32_bf16 v[128:131], v[160:163], v[184:187], v[128:131]
	v_mfma_f32_16x16x32_bf16 v[104:107], v[152:155], v[198:201], v[104:107]
	v_mfma_f32_16x16x32_bf16 v[112:115], v[160:163], v[198:201], v[112:115]
	v_mfma_f32_16x16x32_bf16 v[88:91], v[152:155], v[206:209], v[88:91]
	v_mfma_f32_16x16x32_bf16 v[96:99], v[160:163], v[206:209], v[96:99]
	v_mfma_f32_16x16x32_bf16 v[72:75], v[152:155], v[214:217], v[72:75]
	v_mfma_f32_16x16x32_bf16 v[80:83], v[160:163], v[214:217], v[80:83]
	s_setprio 0
	s_setprio 1
	v_mfma_f32_16x16x32_bf16 v[116:119], v[164:167], v[180:183], v[116:119]
	v_mfma_f32_16x16x32_bf16 v[124:127], v[172:175], v[180:183], v[124:127]
	v_mfma_f32_16x16x32_bf16 v[100:103], v[164:167], v[188:191], v[100:103]
	v_mfma_f32_16x16x32_bf16 v[108:111], v[172:175], v[188:191], v[108:111]
	v_mfma_f32_16x16x32_bf16 v[84:87], v[164:167], v[202:205], v[84:87]
	v_mfma_f32_16x16x32_bf16 v[92:95], v[172:175], v[202:205], v[92:95]
	v_mfma_f32_16x16x32_bf16 v[68:71], v[164:167], v[210:213], v[68:71]
	v_mfma_f32_16x16x32_bf16 v[76:79], v[172:175], v[210:213], v[76:79]
	v_mfma_f32_16x16x32_bf16 v[116:119], v[168:171], v[184:187], v[116:119]
	v_mfma_f32_16x16x32_bf16 v[124:127], v[176:179], v[184:187], v[124:127]
	v_mfma_f32_16x16x32_bf16 v[100:103], v[168:171], v[198:201], v[100:103]
	v_mfma_f32_16x16x32_bf16 v[108:111], v[176:179], v[198:201], v[108:111]
	v_mfma_f32_16x16x32_bf16 v[84:87], v[168:171], v[206:209], v[84:87]
	v_mfma_f32_16x16x32_bf16 v[92:95], v[176:179], v[206:209], v[92:95]
	v_mfma_f32_16x16x32_bf16 v[68:71], v[168:171], v[214:217], v[68:71]
	v_mfma_f32_16x16x32_bf16 v[76:79], v[176:179], v[214:217], v[76:79]
	s_setprio 0
	s_barrier
	s_add_i32 s50, s50, s22
	v_lshl_add_u64 v[192:193], s[48:49], 0, v[2:3]
	s_mov_b32 m0, s50
	ds_read_b128 v[180:183], v150 offset:16384
	ds_read_b128 v[184:187], v150 offset:17408
	ds_read_b128 v[188:191], v150 offset:18432
	ds_read_b128 v[198:201], v150 offset:19456
	ds_read_b128 v[202:205], v150 offset:20480
	ds_read_b128 v[206:209], v150 offset:21504
	ds_read_b128 v[210:213], v150 offset:22528
	ds_read_b128 v[214:217], v150 offset:23552
	global_load_lds_dwordx4 v[192:193], off
	s_add_i32 m0, s50, 0x2000
	v_lshl_add_u64 v[218:219], s[48:49], 0, v[136:137]
	s_add_u32 s48, s48, s2
	s_addc_u32 s49, s49, s3
	s_add_i32 s47, s47, s22
	global_load_lds_dwordx4 v[218:219], off
	v_lshl_add_u64 v[220:221], s[48:49], 0, v[2:3]
	s_mov_b32 m0, s47
	v_lshl_add_u64 v[222:223], s[48:49], 0, v[136:137]
	global_load_lds_dwordx4 v[220:221], off
	s_add_i32 m0, s47, 0x2000
	v_lshl_add_u64 v[224:225], s[18:19], 0, v[132:133]
	global_load_lds_dwordx4 v[222:223], off
	s_mov_b32 m0, s23
	v_lshl_add_u64 v[232:233], s[18:19], 0, v[134:135]
	global_load_lds_dwordx4 v[224:225], off
	s_mov_b32 m0, s24
	s_nop 0
	global_load_lds_dwordx4 v[232:233], off
	s_waitcnt vmcnt(8)
	s_waitcnt lgkmcnt(0)
	s_barrier
; #define PG8_STAGE(bufoff, gbase, voff) do { _Pragma("unroll") for (int _i = 0; _i < 2; ++_i) \
;         __builtin_amdgcn_global_load_lds((const unsigned*)((const char*)(gbase) + (voff)[_i]), (PG8_LAS unsigned*)(lds + (bufoff) + ldsw + _i * 8192), 16, 0, 0); } while (0)
; #define PG8_LDA(dst, b, h) do { _Pragma("unroll") for (int m = 0; m < 4; ++m) _Pragma("unroll") for (int k = 0; k < 2; ++k) dst[m][k] = *(const PG8_LAS bf16x8*)(lds + PG8_SA(b, h) + aoff + m * 2048 + k * 1024); } while (0)
; #define PG8_LDB(dst, b, h) do { _Pragma("unroll") for (int n = 0; n < 2; ++n) _Pragma("unroll") for (int k = 0; k < 2; ++k) dst[n][k] = *(const PG8_LAS bf16x8*)(lds + PG8_SB(b, h) + boff + n * 2048 + k * 1024); } while (0)
; #define PG8_MMA(ai, bj, At, Bt) do { __builtin_amdgcn_s_setprio(1); _Pragma("unroll") for (int m = 0; m < 4; ++m) _Pragma("unroll") for (int n = 0; n < 2; ++n) _Pragma("unroll") for (int k = 0; k < 2; ++k) \
;         acc[ai][bj][m][n] = __builtin_amdgcn_mfma_f32_16x16x32_bf16(Bt[n][k], At[m][k], acc[ai][bj][m][n], 0, 0, 0); __builtin_amdgcn_s_setprio(0); } while (0)
; #define PG8_WAIT_V(n) asm volatile("s_waitcnt vmcnt(" #n ")" ::: "memory")
; #define PG8_WAIT_L(n) asm volatile("s_waitcnt lgkmcnt(" #n ")" ::: "memory")
; #define PG8_BAR __builtin_amdgcn_s_barrier()
; #define PG8_SCHED __builtin_amdgcn_sched_barrier(0)
; template <class Epi, class Sched, bool ALIGN_EPI = false, bool SP2 = false, bool ACHUNK = false>
; __device__ __forceinline__ void gemm_phase(PG8_LAS unsigned char* lds, const Gemm g, const Sched& S, const Epi& E) {
;     ...
;             PG8_WAIT_V(8); PG8_WAIT_L(0); PG8_BAR; PG8_MMA(1, 0, At, B0); PG8_MMA(1, 1, At, B1); PG8_BAR; PG8_SCHED;
;             PG8_LDB(B0, 1, 0); PG8_LDB(B1, 1, 1); PG8_SCHED; PG8_LDA(At, 1, 0); PG8_STAGE(PG8_SA(0, 1), a2 + hstepA, voffA);
;             PG8_WAIT_V(8); PG8_WAIT_L(0); PG8_BAR; PG8_MMA(0, 0, At, B0); PG8_MMA(0, 1, At, B1); PG8_BAR; PG8_SCHED;
	s_setprio 1
	v_mfma_f32_16x16x32_bf16 v[56:59], v[142:145], v[180:183], v[56:59]
	v_mfma_f32_16x16x32_bf16 v[64:67], v[156:159], v[180:183], v[64:67]
	v_mfma_f32_16x16x32_bf16 v[40:43], v[142:145], v[188:191], v[40:43]
	v_mfma_f32_16x16x32_bf16 v[48:51], v[156:159], v[188:191], v[48:51]
	v_mfma_f32_16x16x32_bf16 v[24:27], v[142:145], v[202:205], v[24:27]
	v_mfma_f32_16x16x32_bf16 v[32:35], v[156:159], v[202:205], v[32:35]
	v_mfma_f32_16x16x32_bf16 v[8:11], v[142:145], v[210:213], v[8:11]
	v_mfma_f32_16x16x32_bf16 v[16:19], v[156:159], v[210:213], v[16:19]
	v_mfma_f32_16x16x32_bf16 v[56:59], v[152:155], v[184:187], v[56:59]
	v_mfma_f32_16x16x32_bf16 v[64:67], v[160:163], v[184:187], v[64:67]
	v_mfma_f32_16x16x32_bf16 v[40:43], v[152:155], v[198:201], v[40:43]
	v_mfma_f32_16x16x32_bf16 v[48:51], v[160:163], v[198:201], v[48:51]
	v_mfma_f32_16x16x32_bf16 v[24:27], v[152:155], v[206:209], v[24:27]
	v_mfma_f32_16x16x32_bf16 v[32:35], v[160:163], v[206:209], v[32:35]
	v_mfma_f32_16x16x32_bf16 v[8:11], v[152:155], v[214:217], v[8:11]
	v_mfma_f32_16x16x32_bf16 v[16:19], v[160:163], v[214:217], v[16:19]
	s_setprio 0
	s_setprio 1
	v_mfma_f32_16x16x32_bf16 v[52:55], v[164:167], v[180:183], v[52:55]
	v_mfma_f32_16x16x32_bf16 v[60:63], v[172:175], v[180:183], v[60:63]
	v_mfma_f32_16x16x32_bf16 v[36:39], v[164:167], v[188:191], v[36:39]
	v_mfma_f32_16x16x32_bf16 v[44:47], v[172:175], v[188:191], v[44:47]
	v_mfma_f32_16x16x32_bf16 v[20:23], v[164:167], v[202:205], v[20:23]
	v_mfma_f32_16x16x32_bf16 v[28:31], v[172:175], v[202:205], v[28:31]
	v_mfma_f32_16x16x32_bf16 v[4:7], v[164:167], v[210:213], v[4:7]
	v_mfma_f32_16x16x32_bf16 v[12:15], v[172:175], v[210:213], v[12:15]
	v_mfma_f32_16x16x32_bf16 v[52:55], v[168:171], v[184:187], v[52:55]
	v_mfma_f32_16x16x32_bf16 v[60:63], v[176:179], v[184:187], v[60:63]
	v_mfma_f32_16x16x32_bf16 v[36:39], v[168:171], v[198:201], v[36:39]
	v_mfma_f32_16x16x32_bf16 v[44:47], v[176:179], v[198:201], v[44:47]
	v_mfma_f32_16x16x32_bf16 v[20:23], v[168:171], v[206:209], v[20:23]
	v_mfma_f32_16x16x32_bf16 v[28:31], v[176:179], v[206:209], v[28:31]
	v_mfma_f32_16x16x32_bf16 v[4:7], v[168:171], v[214:217], v[4:7]
	v_mfma_f32_16x16x32_bf16 v[12:15], v[176:179], v[214:217], v[12:15]
	s_setprio 0
	s_barrier
	s_add_i32 s47, 0, 0x18000
	v_add_u32_e32 v151, s47, v147
	s_add_i32 s48, 0, 0x1c000
	ds_read_b128 v[142:145], v151
	ds_read_b128 v[152:155], v151 offset:1024
	ds_read_b128 v[156:159], v151 offset:2048
	ds_read_b128 v[160:163], v151 offset:3072
	v_add_u32_e32 v151, s48, v147
	ds_read_b128 v[164:167], v151
	ds_read_b128 v[168:171], v151 offset:1024
	ds_read_b128 v[172:175], v151 offset:2048
	ds_read_b128 v[176:179], v151 offset:3072
	s_add_u32 s18, s18, s2
	s_addc_u32 s19, s19, s3
	s_mov_b32 m0, s25
	v_lshl_add_u64 v[234:235], s[18:19], 0, v[132:133]
	ds_read_b128 v[180:183], v150 offset:32768
	ds_read_b128 v[184:187], v150 offset:33792
	ds_read_b128 v[188:191], v150 offset:34816
	ds_read_b128 v[198:201], v150 offset:35840
	ds_read_b128 v[202:205], v150 offset:36864
	ds_read_b128 v[206:209], v150 offset:37888
	ds_read_b128 v[210:213], v150 offset:38912
	ds_read_b128 v[214:217], v150 offset:39936
	global_load_lds_dwordx4 v[234:235], off
	v_lshl_add_u64 v[234:235], s[18:19], 0, v[134:135]
	s_mov_b32 m0, s26
	s_nop 0
	global_load_lds_dwordx4 v[234:235], off
	s_waitcnt vmcnt(8)
	s_waitcnt lgkmcnt(0)
	s_barrier
	s_setprio 1
	v_mfma_f32_16x16x32_bf16 v[120:123], v[142:145], v[180:183], v[120:123]
	v_mfma_f32_16x16x32_bf16 v[128:131], v[156:159], v[180:183], v[128:131]
	v_mfma_f32_16x16x32_bf16 v[104:107], v[142:145], v[188:191], v[104:107]
	v_mfma_f32_16x16x32_bf16 v[112:115], v[156:159], v[188:191], v[112:115]
	v_mfma_f32_16x16x32_bf16 v[88:91], v[142:145], v[202:205], v[88:91]
	v_mfma_f32_16x16x32_bf16 v[96:99], v[156:159], v[202:205], v[96:99]
	v_mfma_f32_16x16x32_bf16 v[72:75], v[142:145], v[210:213], v[72:75]
	v_mfma_f32_16x16x32_bf16 v[80:83], v[156:159], v[210:213], v[80:83]
	v_mfma_f32_16x16x32_bf16 v[120:123], v[152:155], v[184:187], v[120:123]
	v_mfma_f32_16x16x32_bf16 v[128:131], v[160:163], v[184:187], v[128:131]
	v_mfma_f32_16x16x32_bf16 v[104:107], v[152:155], v[198:201], v[104:107]
	v_mfma_f32_16x16x32_bf16 v[112:115], v[160:163], v[198:201], v[112:115]
	v_mfma_f32_16x16x32_bf16 v[88:91], v[152:155], v[206:209], v[88:91]
	v_mfma_f32_16x16x32_bf16 v[96:99], v[160:163], v[206:209], v[96:99]
	v_mfma_f32_16x16x32_bf16 v[72:75], v[152:155], v[214:217], v[72:75]
	v_mfma_f32_16x16x32_bf16 v[80:83], v[160:163], v[214:217], v[80:83]
	s_setprio 0
	s_setprio 1
	v_mfma_f32_16x16x32_bf16 v[116:119], v[164:167], v[180:183], v[116:119]
	v_mfma_f32_16x16x32_bf16 v[124:127], v[172:175], v[180:183], v[124:127]
	v_mfma_f32_16x16x32_bf16 v[100:103], v[164:167], v[188:191], v[100:103]
	v_mfma_f32_16x16x32_bf16 v[108:111], v[172:175], v[188:191], v[108:111]
	v_mfma_f32_16x16x32_bf16 v[84:87], v[164:167], v[202:205], v[84:87]
	v_mfma_f32_16x16x32_bf16 v[92:95], v[172:175], v[202:205], v[92:95]
	v_mfma_f32_16x16x32_bf16 v[68:71], v[164:167], v[210:213], v[68:71]
	v_mfma_f32_16x16x32_bf16 v[76:79], v[172:175], v[210:213], v[76:79]
	v_mfma_f32_16x16x32_bf16 v[116:119], v[168:171], v[184:187], v[116:119]
	v_mfma_f32_16x16x32_bf16 v[124:127], v[176:179], v[184:187], v[124:127]
	v_mfma_f32_16x16x32_bf16 v[100:103], v[168:171], v[198:201], v[100:103]
	v_mfma_f32_16x16x32_bf16 v[108:111], v[176:179], v[198:201], v[108:111]
	v_mfma_f32_16x16x32_bf16 v[84:87], v[168:171], v[206:209], v[84:87]
	v_mfma_f32_16x16x32_bf16 v[92:95], v[176:179], v[206:209], v[92:95]
	v_mfma_f32_16x16x32_bf16 v[68:71], v[168:171], v[214:217], v[68:71]
	v_mfma_f32_16x16x32_bf16 v[76:79], v[176:179], v[214:217], v[76:79]
	s_setprio 0
	s_barrier
; #define PG8_STAGE(bufoff, gbase, voff) do { _Pragma("unroll") for (int _i = 0; _i < 2; ++_i) \
;         __builtin_amdgcn_global_load_lds((const unsigned*)((const char*)(gbase) + (voff)[_i]), (PG8_LAS unsigned*)(lds + (bufoff) + ldsw + _i * 8192), 16, 0, 0); } while (0)
; #define PG8_LDA(dst, b, h) do { _Pragma("unroll") for (int m = 0; m < 4; ++m) _Pragma("unroll") for (int k = 0; k < 2; ++k) dst[m][k] = *(const PG8_LAS bf16x8*)(lds + PG8_SA(b, h) + aoff + m * 2048 + k * 1024); } while (0)
; #define PG8_MMA(ai, bj, At, Bt) do { __builtin_amdgcn_s_setprio(1); _Pragma("unroll") for (int m = 0; m < 4; ++m) _Pragma("unroll") for (int n = 0; n < 2; ++n) _Pragma("unroll") for (int k = 0; k < 2; ++k) \
;         acc[ai][bj][m][n] = __builtin_amdgcn_mfma_f32_16x16x32_bf16(Bt[n][k], At[m][k], acc[ai][bj][m][n], 0, 0, 0); __builtin_amdgcn_s_setprio(0); } while (0)
; #define PG8_WAIT_V(n) asm volatile("s_waitcnt vmcnt(" #n ")" ::: "memory")
; #define PG8_WAIT_L(n) asm volatile("s_waitcnt lgkmcnt(" #n ")" ::: "memory")
; #define PG8_BAR __builtin_amdgcn_s_barrier()
; #define PG8_SCHED __builtin_amdgcn_sched_barrier(0)
; template <class Epi, class Sched, bool ALIGN_EPI = false, bool SP2 = false, bool ACHUNK = false>
; __device__ __forceinline__ void gemm_phase(PG8_LAS unsigned char* lds, const Gemm g, const Sched& S, const Epi& E) {
;     ...
;         for (int t = 0; t < nt; t += 2) {
;     ...
;             PG8_LDA(At, 1, 1); PG8_STAGE(PG8_SB(1, 0), b3, voffB); PG8_STAGE(PG8_SB(1, 1), b3 + hstepB, voffB); PG8_STAGE(PG8_SA(1, 0), a3, voffA);
;             PG8_WAIT_V(8); PG8_WAIT_L(0); PG8_BAR; PG8_MMA(1, 0, At, B0); PG8_MMA(1, 1, At, B1); PG8_BAR; PG8_SCHED;
	s_add_i32 s18, s47, s22
	v_lshl_add_u64 v[192:193], v[192:193], 0, s[10:11]
	s_mov_b32 m0, s18
	ds_read_b128 v[180:183], v150 offset:49152
	ds_read_b128 v[184:187], v150 offset:50176
	ds_read_b128 v[188:191], v150 offset:51200
	ds_read_b128 v[198:201], v150 offset:52224
	ds_read_b128 v[202:205], v150 offset:53248
	ds_read_b128 v[206:209], v150 offset:54272
	ds_read_b128 v[210:213], v150 offset:55296
	ds_read_b128 v[214:217], v150 offset:56320
	global_load_lds_dwordx4 v[192:193], off
	v_lshl_add_u64 v[192:193], v[218:219], 0, s[10:11]
	s_add_i32 m0, s18, 0x2000
	s_add_i32 s18, s48, s22
	global_load_lds_dwordx4 v[192:193], off
	v_lshl_add_u64 v[192:193], v[220:221], 0, s[10:11]
	s_mov_b32 m0, s18
	s_nop 0
	global_load_lds_dwordx4 v[192:193], off
	v_lshl_add_u64 v[192:193], v[222:223], 0, s[10:11]
	s_add_i32 m0, s18, 0x2000
	s_nop 0
	global_load_lds_dwordx4 v[192:193], off
	v_lshl_add_u64 v[192:193], v[224:225], 0, s[10:11]
	s_mov_b32 m0, s27
	s_nop 0
	global_load_lds_dwordx4 v[192:193], off
	v_lshl_add_u64 v[192:193], v[232:233], 0, s[10:11]
	s_mov_b32 m0, s28
	s_nop 0
	global_load_lds_dwordx4 v[192:193], off
	s_waitcnt vmcnt(8)
	s_waitcnt lgkmcnt(0)
	s_barrier
	s_setprio 1
	v_mfma_f32_16x16x32_bf16 v[56:59], v[142:145], v[180:183], v[56:59]
	v_mfma_f32_16x16x32_bf16 v[64:67], v[156:159], v[180:183], v[64:67]
	v_mfma_f32_16x16x32_bf16 v[40:43], v[142:145], v[188:191], v[40:43]
	v_mfma_f32_16x16x32_bf16 v[48:51], v[156:159], v[188:191], v[48:51]
	v_mfma_f32_16x16x32_bf16 v[24:27], v[142:145], v[202:205], v[24:27]
	v_mfma_f32_16x16x32_bf16 v[32:35], v[156:159], v[202:205], v[32:35]
	v_mfma_f32_16x16x32_bf16 v[8:11], v[142:145], v[210:213], v[8:11]
	v_mfma_f32_16x16x32_bf16 v[16:19], v[156:159], v[210:213], v[16:19]
	v_mfma_f32_16x16x32_bf16 v[56:59], v[152:155], v[184:187], v[56:59]
	v_mfma_f32_16x16x32_bf16 v[64:67], v[160:163], v[184:187], v[64:67]
	v_mfma_f32_16x16x32_bf16 v[40:43], v[152:155], v[198:201], v[40:43]
	v_mfma_f32_16x16x32_bf16 v[48:51], v[160:163], v[198:201], v[48:51]
	v_mfma_f32_16x16x32_bf16 v[24:27], v[152:155], v[206:209], v[24:27]
	v_mfma_f32_16x16x32_bf16 v[32:35], v[160:163], v[206:209], v[32:35]
	v_mfma_f32_16x16x32_bf16 v[8:11], v[152:155], v[214:217], v[8:11]
	v_mfma_f32_16x16x32_bf16 v[16:19], v[160:163], v[214:217], v[16:19]
	s_setprio 0
	s_setprio 1
	v_mfma_f32_16x16x32_bf16 v[52:55], v[164:167], v[180:183], v[52:55]
	v_mfma_f32_16x16x32_bf16 v[60:63], v[172:175], v[180:183], v[60:63]
	v_mfma_f32_16x16x32_bf16 v[36:39], v[164:167], v[188:191], v[36:39]
	v_mfma_f32_16x16x32_bf16 v[44:47], v[172:175], v[188:191], v[44:47]
	v_mfma_f32_16x16x32_bf16 v[20:23], v[164:167], v[202:205], v[20:23]
	v_mfma_f32_16x16x32_bf16 v[28:31], v[172:175], v[202:205], v[28:31]
	v_mfma_f32_16x16x32_bf16 v[4:7], v[164:167], v[210:213], v[4:7]
	v_mfma_f32_16x16x32_bf16 v[12:15], v[172:175], v[210:213], v[12:15]
	v_mfma_f32_16x16x32_bf16 v[52:55], v[168:171], v[184:187], v[52:55]
	v_mfma_f32_16x16x32_bf16 v[60:63], v[176:179], v[184:187], v[60:63]
	v_mfma_f32_16x16x32_bf16 v[36:39], v[168:171], v[198:201], v[36:39]
	v_mfma_f32_16x16x32_bf16 v[44:47], v[176:179], v[198:201], v[44:47]
	v_mfma_f32_16x16x32_bf16 v[20:23], v[168:171], v[206:209], v[20:23]
	v_mfma_f32_16x16x32_bf16 v[28:31], v[176:179], v[206:209], v[28:31]
	v_mfma_f32_16x16x32_bf16 v[4:7], v[168:171], v[214:217], v[4:7]
	v_mfma_f32_16x16x32_bf16 v[12:15], v[176:179], v[214:217], v[12:15]
	s_setprio 0
	s_barrier
	s_add_u32 s20, s20, 0x100
	s_addc_u32 s21, s21, 0
	s_add_u32 s44, s44, 0x100
	s_addc_u32 s45, s45, 0
	s_cmp_ge_i32 s46, s29
	s_mov_b32 s18, s46
	s_cbranch_scc0 .LBB0_52
	v_readlane_b32 s47, v255, 0
	s_mov_b32 s50, s94
	s_and_b64 vcc, exec, s[12:13]
	s_cbranch_vccnz .LBB0_57
	s_branch .LBB0_58

; #define PG8_STAGE(bufoff, gbase, voff) do { _Pragma("unroll") for (int _i = 0; _i < 2; ++_i) \
;         __builtin_amdgcn_global_load_lds((const unsigned*)((const char*)(gbase) + (voff)[_i]), (PG8_LAS unsigned*)(lds + (bufoff) + ldsw + _i * 8192), 16, 0, 0); } while (0)
; #define PG8_LDA(dst, b, h) do { _Pragma("unroll") for (int m = 0; m < 4; ++m) _Pragma("unroll") for (int k = 0; k < 2; ++k) dst[m][k] = *(const PG8_LAS bf16x8*)(lds + PG8_SA(b, h) + aoff + m * 2048 + k * 1024); } while (0)
; #define PG8_LDB(dst, b, h) do { _Pragma("unroll") for (int n = 0; n < 2; ++n) _Pragma("unroll") for (int k = 0; k < 2; ++k) dst[n][k] = *(const PG8_LAS bf16x8*)(lds + PG8_SB(b, h) + boff + n * 2048 + k * 1024); } while (0)
; #define PG8_SCHED __builtin_amdgcn_sched_barrier(0)
; template <class Epi, class Sched, bool ALIGN_EPI = false, bool SP2 = false, bool ACHUNK = false>
; __device__ __forceinline__ void gemm_phase(PG8_LAS unsigned char* lds, const Gemm g, const Sched& S, const Epi& E) {
;     ...
;             const bool last = (t == nt - 2);
;             if constexpr (Epi::HAS_MID) { if (t == Epi::MID_T) E.mid(acc, cur, wr, wc, fr, fq, ShflDev{}); }
;             const char* a1 = cA + (size_t)(t + 1) * kstep;
;             const char* a2 = last ? nA : cA + (size_t)(t + 2) * kstep; const char* b2 = last ? nB : cB + (size_t)(t + 2) * kstep;
;             const char* a3 = a2 + kstep; const char* b3 = b2 + kstep;
;             if (last && has_next) S.a_ready(nxt);
;             if constexpr (SP2) {
;             PG8_LDB(B0, 0, 0); PG8_LDB(B1, 0, 1); PG8_SCHED; PG8_LDA(At, 0, 0); PG8_STAGE(PG8_SA(1, 1), a1 + hstepA, voffA);
;     ...
;         else {
; #pragma unroll
;         for (int a = 0; a < 2; ++a)
; #pragma unroll
;             for (int b = 0; b < 2; ++b)
; #pragma unroll
;                 for (int m = 0; m < 4; ++m)
; #pragma unroll
;                     for (int n = 0; n < 2; ++n) acc[a][b][m][n] = (f32x4){0.f, 0.f, 0.f, 0.f};
;         }
.LBB0_106:
	s_andn2_b64 vcc, exec, s[44:45]
	s_nop 0
	s_cbranch_vccnz .LBB0_110
	s_add_u32 s8, s4, 0x100
	s_addc_u32 s9, s5, 0
	s_add_u32 s0, s6, 0x80
	v_mov_b32_e32 v4, 0
	s_addc_u32 s1, s7, 0
	s_mov_b32 s4, 0
	v_mov_b32_e32 v5, v4
	v_mov_b32_e32 v6, v4
	v_mov_b32_e32 v7, v4
	v_mov_b32_e32 v8, v4
	v_mov_b32_e32 v9, v4
	v_mov_b32_e32 v10, v4
	v_mov_b32_e32 v11, v4
	v_mov_b32_e32 v12, v4
	v_mov_b32_e32 v13, v4
	v_mov_b32_e32 v14, v4
	v_mov_b32_e32 v15, v4
	v_mov_b32_e32 v16, v4
	v_mov_b32_e32 v17, v4
	v_mov_b32_e32 v18, v4
	v_mov_b32_e32 v19, v4
	v_mov_b32_e32 v24, v4
	v_mov_b32_e32 v25, v4
	v_mov_b32_e32 v26, v4
	v_mov_b32_e32 v27, v4
	v_mov_b32_e32 v20, v4
	v_mov_b32_e32 v21, v4
	v_mov_b32_e32 v22, v4
	v_mov_b32_e32 v23, v4
	v_mov_b32_e32 v32, v4
	v_mov_b32_e32 v33, v4
	v_mov_b32_e32 v34, v4
	v_mov_b32_e32 v35, v4
	v_mov_b32_e32 v28, v4
	v_mov_b32_e32 v29, v4
	v_mov_b32_e32 v30, v4
	v_mov_b32_e32 v31, v4
	v_mov_b32_e32 v68, v4
	v_mov_b32_e32 v69, v4
	v_mov_b32_e32 v70, v4
	v_mov_b32_e32 v71, v4
	v_mov_b32_e32 v72, v4
	v_mov_b32_e32 v73, v4
	v_mov_b32_e32 v74, v4
	v_mov_b32_e32 v75, v4
	v_mov_b32_e32 v76, v4
	v_mov_b32_e32 v77, v4
	v_mov_b32_e32 v78, v4
	v_mov_b32_e32 v79, v4
	v_mov_b32_e32 v80, v4
	v_mov_b32_e32 v81, v4
	v_mov_b32_e32 v82, v4
	v_mov_b32_e32 v83, v4
	v_mov_b32_e32 v84, v4
	v_mov_b32_e32 v85, v4
	v_mov_b32_e32 v86, v4
	v_mov_b32_e32 v87, v4
	v_mov_b32_e32 v88, v4
	v_mov_b32_e32 v89, v4
	v_mov_b32_e32 v90, v4
	v_mov_b32_e32 v91, v4
	v_mov_b32_e32 v92, v4
	v_mov_b32_e32 v93, v4
	v_mov_b32_e32 v94, v4
	v_mov_b32_e32 v95, v4
	v_mov_b32_e32 v96, v4
	v_mov_b32_e32 v97, v4
	v_mov_b32_e32 v98, v4
	v_mov_b32_e32 v99, v4
	v_mov_b32_e32 v100, v4
	v_mov_b32_e32 v101, v4
	v_mov_b32_e32 v102, v4
	v_mov_b32_e32 v103, v4
	v_mov_b32_e32 v104, v4
	v_mov_b32_e32 v105, v4
	v_mov_b32_e32 v106, v4
	v_mov_b32_e32 v107, v4
	v_mov_b32_e32 v108, v4
	v_mov_b32_e32 v109, v4
	v_mov_b32_e32 v110, v4
	v_mov_b32_e32 v111, v4
	v_mov_b32_e32 v112, v4
	v_mov_b32_e32 v113, v4
	v_mov_b32_e32 v114, v4
	v_mov_b32_e32 v115, v4
	v_mov_b32_e32 v120, v4
	v_mov_b32_e32 v121, v4
	v_mov_b32_e32 v122, v4
	v_mov_b32_e32 v123, v4
	v_mov_b32_e32 v116, v4
	v_mov_b32_e32 v117, v4
	v_mov_b32_e32 v118, v4
	v_mov_b32_e32 v119, v4
	v_mov_b32_e32 v128, v4
	v_mov_b32_e32 v129, v4
	v_mov_b32_e32 v130, v4
	v_mov_b32_e32 v131, v4
	v_mov_b32_e32 v124, v4
	v_mov_b32_e32 v125, v4
	v_mov_b32_e32 v126, v4
	v_mov_b32_e32 v127, v4
	v_mov_b32_e32 v156, v4
	v_mov_b32_e32 v157, v4
	v_mov_b32_e32 v158, v4
	v_mov_b32_e32 v159, v4
	v_mov_b32_e32 v160, v4
	v_mov_b32_e32 v161, v4
	v_mov_b32_e32 v162, v4
	v_mov_b32_e32 v163, v4
	v_mov_b32_e32 v144, v4
	v_mov_b32_e32 v145, v4
	v_mov_b32_e32 v146, v4
	v_mov_b32_e32 v147, v4
	v_mov_b32_e32 v136, v4
	v_mov_b32_e32 v137, v4
	v_mov_b32_e32 v138, v4
	v_mov_b32_e32 v139, v4
	v_mov_b32_e32 v140, v4
	v_mov_b32_e32 v141, v4
	v_mov_b32_e32 v142, v4
	v_mov_b32_e32 v143, v4
	v_mov_b32_e32 v132, v4
	v_mov_b32_e32 v133, v4
	v_mov_b32_e32 v134, v4
	v_mov_b32_e32 v135, v4
	v_mov_b32_e32 v152, v4
	v_mov_b32_e32 v153, v4
	v_mov_b32_e32 v154, v4
	v_mov_b32_e32 v155, v4
	v_mov_b32_e32 v148, v4
	v_mov_b32_e32 v149, v4
	v_mov_b32_e32 v150, v4
	v_mov_b32_e32 v151, v4
.LBB0_108:
	s_add_i32 s6, s4, 2
	s_add_u32 s7, s0, 0x80
	s_addc_u32 s5, s1, 0
	s_add_i32 s77, 0, 0x10000
	s_cmp_eq_u32 s54, s4
	s_cselect_b32 s5, s49, s5
	s_cselect_b32 s4, s48, s7
	v_add_u32_e32 v2, s77, v224
	s_cselect_b32 s79, s51, s9
	s_cselect_b32 s78, s50, s8
	s_add_i32 s7, 0, 0x14000
	s_waitcnt lgkmcnt(0)
	ds_read_b128 v[36:39], v2
	ds_read_b128 v[40:43], v2 offset:1024
	ds_read_b128 v[44:47], v2 offset:2048
	ds_read_b128 v[48:51], v2 offset:3072
	v_add_u32_e32 v2, s7, v224
	ds_read_b128 v[52:55], v2
	ds_read_b128 v[56:59], v2 offset:1024
	ds_read_b128 v[60:63], v2 offset:2048
	ds_read_b128 v[64:67], v2 offset:3072
	s_add_u32 s98, s0, s28
	s_addc_u32 s99, s1, s29
	s_add_i32 m0, s25, 0xc000
	ds_read_b128 v[164:167], v238
	ds_read_b128 v[168:171], v238 offset:1024
	ds_read_b128 v[184:187], v238 offset:2048
	ds_read_b128 v[188:191], v238 offset:3072
	ds_read_b128 v[198:201], v238 offset:4096
	ds_read_b128 v[202:205], v238 offset:5120
	ds_read_b128 v[206:209], v238 offset:6144
	ds_read_b128 v[210:213], v238 offset:7168
	global_load_lds_dwordx4 v172, s[98:99]
	s_add_i32 m0, s25, 0xe000
	s_nop 0
	global_load_lds_dwordx4 v176, s[98:99]
	s_waitcnt vmcnt(8)
	s_waitcnt lgkmcnt(0)
	s_barrier
	s_setprio 1
	v_mfma_f32_16x16x32_bf16 v[148:151], v[36:39], v[164:167], v[148:151]
	v_mfma_f32_16x16x32_bf16 v[152:155], v[44:47], v[164:167], v[152:155]
	v_mfma_f32_16x16x32_bf16 v[132:135], v[36:39], v[184:187], v[132:135]
	v_mfma_f32_16x16x32_bf16 v[140:143], v[44:47], v[184:187], v[140:143]
	v_mfma_f32_16x16x32_bf16 v[136:139], v[36:39], v[198:201], v[136:139]
	v_mfma_f32_16x16x32_bf16 v[144:147], v[44:47], v[198:201], v[144:147]
	v_mfma_f32_16x16x32_bf16 v[160:163], v[36:39], v[206:209], v[160:163]
	v_mfma_f32_16x16x32_bf16 v[156:159], v[44:47], v[206:209], v[156:159]
	v_mfma_f32_16x16x32_bf16 v[148:151], v[40:43], v[168:171], v[148:151]
	v_mfma_f32_16x16x32_bf16 v[152:155], v[48:51], v[168:171], v[152:155]
	v_mfma_f32_16x16x32_bf16 v[132:135], v[40:43], v[188:191], v[132:135]
	v_mfma_f32_16x16x32_bf16 v[140:143], v[48:51], v[188:191], v[140:143]
	v_mfma_f32_16x16x32_bf16 v[136:139], v[40:43], v[202:205], v[136:139]
	v_mfma_f32_16x16x32_bf16 v[144:147], v[48:51], v[202:205], v[144:147]
	v_mfma_f32_16x16x32_bf16 v[160:163], v[40:43], v[210:213], v[160:163]
	v_mfma_f32_16x16x32_bf16 v[156:159], v[48:51], v[210:213], v[156:159]
	s_setprio 0
	s_setprio 1
	v_mfma_f32_16x16x32_bf16 v[124:127], v[52:55], v[164:167], v[124:127]
	v_mfma_f32_16x16x32_bf16 v[128:131], v[60:63], v[164:167], v[128:131]
	v_mfma_f32_16x16x32_bf16 v[116:119], v[52:55], v[184:187], v[116:119]
	v_mfma_f32_16x16x32_bf16 v[120:123], v[60:63], v[184:187], v[120:123]
	v_mfma_f32_16x16x32_bf16 v[112:115], v[52:55], v[198:201], v[112:115]
	v_mfma_f32_16x16x32_bf16 v[108:111], v[60:63], v[198:201], v[108:111]
	v_mfma_f32_16x16x32_bf16 v[104:107], v[52:55], v[206:209], v[104:107]
	v_mfma_f32_16x16x32_bf16 v[100:103], v[60:63], v[206:209], v[100:103]
	v_mfma_f32_16x16x32_bf16 v[124:127], v[56:59], v[168:171], v[124:127]
	v_mfma_f32_16x16x32_bf16 v[128:131], v[64:67], v[168:171], v[128:131]
	v_mfma_f32_16x16x32_bf16 v[116:119], v[56:59], v[188:191], v[116:119]
	v_mfma_f32_16x16x32_bf16 v[120:123], v[64:67], v[188:191], v[120:123]
	v_mfma_f32_16x16x32_bf16 v[112:115], v[56:59], v[202:205], v[112:115]
	v_mfma_f32_16x16x32_bf16 v[108:111], v[64:67], v[202:205], v[108:111]
	v_mfma_f32_16x16x32_bf16 v[104:107], v[56:59], v[210:213], v[104:107]
	v_mfma_f32_16x16x32_bf16 v[100:103], v[64:67], v[210:213], v[100:103]
	s_setprio 0
	s_barrier
; #define PG8_STAGE(bufoff, gbase, voff) do { _Pragma("unroll") for (int _i = 0; _i < 2; ++_i) \
;         __builtin_amdgcn_global_load_lds((const unsigned*)((const char*)(gbase) + (voff)[_i]), (PG8_LAS unsigned*)(lds + (bufoff) + ldsw + _i * 8192), 16, 0, 0); } while (0)
; #define PG8_LDA(dst, b, h) do { _Pragma("unroll") for (int m = 0; m < 4; ++m) _Pragma("unroll") for (int k = 0; k < 2; ++k) dst[m][k] = *(const PG8_LAS bf16x8*)(lds + PG8_SA(b, h) + aoff + m * 2048 + k * 1024); } while (0)
; #define PG8_LDB(dst, b, h) do { _Pragma("unroll") for (int n = 0; n < 2; ++n) _Pragma("unroll") for (int k = 0; k < 2; ++k) dst[n][k] = *(const PG8_LAS bf16x8*)(lds + PG8_SB(b, h) + boff + n * 2048 + k * 1024); } while (0)
; #define PG8_MMA(ai, bj, At, Bt) do { __builtin_amdgcn_s_setprio(1); _Pragma("unroll") for (int m = 0; m < 4; ++m) _Pragma("unroll") for (int n = 0; n < 2; ++n) _Pragma("unroll") for (int k = 0; k < 2; ++k) \
;         acc[ai][bj][m][n] = __builtin_amdgcn_mfma_f32_16x16x32_bf16(Bt[n][k], At[m][k], acc[ai][bj][m][n], 0, 0, 0); __builtin_amdgcn_s_setprio(0); } while (0)
; #define PG8_WAIT_V(n) asm volatile("s_waitcnt vmcnt(" #n ")" ::: "memory")
; #define PG8_WAIT_L(n) asm volatile("s_waitcnt lgkmcnt(" #n ")" ::: "memory")
; #define PG8_BAR __builtin_amdgcn_s_barrier()
; #define PG8_SCHED __builtin_amdgcn_sched_barrier(0)
; template <class Epi, class Sched, bool ALIGN_EPI = false, bool SP2 = false, bool ACHUNK = false>
; __device__ __forceinline__ void gemm_phase(PG8_LAS unsigned char* lds, const Gemm g, const Sched& S, const Epi& E) {
;     ...
;             PG8_WAIT_V(8); PG8_WAIT_L(0); PG8_BAR; PG8_MMA(0, 0, At, B0); PG8_MMA(0, 1, At, B1); PG8_BAR; PG8_SCHED;
;             PG8_LDA(At, 0, 1); PG8_STAGE(PG8_SB(0, 0), b2, voffB); PG8_STAGE(PG8_SB(0, 1), b2 + hstepB, voffB); PG8_STAGE(PG8_SA(0, 0), a2, voffA);
;             PG8_WAIT_V(8); PG8_WAIT_L(0); PG8_BAR; PG8_MMA(1, 0, At, B0); PG8_MMA(1, 1, At, B1); PG8_BAR; PG8_SCHED;
;             PG8_LDB(B0, 1, 0); PG8_LDB(B1, 1, 1); PG8_SCHED; PG8_LDA(At, 1, 0); PG8_STAGE(PG8_SA(0, 1), a2 + hstepA, voffA);
	s_add_i32 s77, s77, s17
	s_add_u32 s98, s78, s18
	s_addc_u32 s99, s79, s19
	s_mov_b32 m0, s77
	ds_read_b128 v[164:167], v238 offset:16384
	ds_read_b128 v[168:171], v238 offset:17408
	ds_read_b128 v[184:187], v238 offset:18432
	ds_read_b128 v[188:191], v238 offset:19456
	ds_read_b128 v[198:201], v238 offset:20480
	ds_read_b128 v[202:205], v238 offset:21504
	ds_read_b128 v[206:209], v238 offset:22528
	ds_read_b128 v[210:213], v238 offset:23552
	global_load_lds_dwordx4 v174, s[78:79]
	s_add_i32 m0, s77, 0x2000
	s_add_i32 s7, s7, s17
	global_load_lds_dwordx4 v178, s[78:79]
	s_mov_b32 m0, s7
	s_nop 0
	global_load_lds_dwordx4 v174, s[98:99]
	s_add_i32 m0, s7, 0x2000
	s_nop 0
	global_load_lds_dwordx4 v178, s[98:99]
	s_mov_b32 m0, s25
	s_nop 0
	global_load_lds_dwordx4 v172, s[4:5]
	s_mov_b32 m0, s26
	s_nop 0
	global_load_lds_dwordx4 v176, s[4:5]
	s_waitcnt vmcnt(8)
	s_waitcnt lgkmcnt(0)
	s_barrier
	s_setprio 1
	v_mfma_f32_16x16x32_bf16 v[96:99], v[36:39], v[164:167], v[96:99]
	v_mfma_f32_16x16x32_bf16 v[92:95], v[44:47], v[164:167], v[92:95]
	v_mfma_f32_16x16x32_bf16 v[88:91], v[36:39], v[184:187], v[88:91]
	v_mfma_f32_16x16x32_bf16 v[84:87], v[44:47], v[184:187], v[84:87]
	v_mfma_f32_16x16x32_bf16 v[80:83], v[36:39], v[198:201], v[80:83]
	v_mfma_f32_16x16x32_bf16 v[76:79], v[44:47], v[198:201], v[76:79]
	v_mfma_f32_16x16x32_bf16 v[36:39], v[36:39], v[206:209], v[72:75]
	v_mfma_f32_16x16x32_bf16 v[96:99], v[40:43], v[168:171], v[96:99]
	v_mfma_f32_16x16x32_bf16 v[92:95], v[48:51], v[168:171], v[92:95]
	v_mfma_f32_16x16x32_bf16 v[88:91], v[40:43], v[188:191], v[88:91]
	v_mfma_f32_16x16x32_bf16 v[84:87], v[48:51], v[188:191], v[84:87]
	v_mfma_f32_16x16x32_bf16 v[80:83], v[40:43], v[202:205], v[80:83]
	v_mfma_f32_16x16x32_bf16 v[76:79], v[48:51], v[202:205], v[76:79]
	v_mfma_f32_16x16x32_bf16 v[36:39], v[40:43], v[210:213], v[36:39]
	v_mfma_f32_16x16x32_bf16 v[40:43], v[44:47], v[206:209], v[68:71]
	v_mfma_f32_16x16x32_bf16 v[40:43], v[48:51], v[210:213], v[40:43]
	s_setprio 0
	s_setprio 1
	v_mfma_f32_16x16x32_bf16 v[28:31], v[52:55], v[164:167], v[28:31]
	v_mfma_f32_16x16x32_bf16 v[32:35], v[60:63], v[164:167], v[32:35]
	v_mfma_f32_16x16x32_bf16 v[20:23], v[52:55], v[184:187], v[20:23]
	v_mfma_f32_16x16x32_bf16 v[24:27], v[60:63], v[184:187], v[24:27]
	v_mfma_f32_16x16x32_bf16 v[16:19], v[52:55], v[198:201], v[16:19]
	v_mfma_f32_16x16x32_bf16 v[12:15], v[60:63], v[198:201], v[12:15]
	v_mfma_f32_16x16x32_bf16 v[8:11], v[52:55], v[206:209], v[8:11]
	v_mfma_f32_16x16x32_bf16 v[4:7], v[60:63], v[206:209], v[4:7]
	v_mfma_f32_16x16x32_bf16 v[28:31], v[56:59], v[168:171], v[28:31]
	v_mfma_f32_16x16x32_bf16 v[32:35], v[64:67], v[168:171], v[32:35]
	v_mfma_f32_16x16x32_bf16 v[20:23], v[56:59], v[188:191], v[20:23]
	v_mfma_f32_16x16x32_bf16 v[24:27], v[64:67], v[188:191], v[24:27]
	v_mfma_f32_16x16x32_bf16 v[16:19], v[56:59], v[202:205], v[16:19]
	v_mfma_f32_16x16x32_bf16 v[12:15], v[64:67], v[202:205], v[12:15]
	v_mfma_f32_16x16x32_bf16 v[8:11], v[56:59], v[210:213], v[8:11]
	v_mfma_f32_16x16x32_bf16 v[4:7], v[64:67], v[210:213], v[4:7]
	s_setprio 0
	s_barrier
	s_add_i32 s7, 0, 0x18000
	v_add_u32_e32 v2, s7, v224
	s_add_i32 s77, 0, 0x1c000
	ds_read_b128 v[44:47], v2
	ds_read_b128 v[48:51], v2 offset:1024
	ds_read_b128 v[52:55], v2 offset:2048
	ds_read_b128 v[56:59], v2 offset:3072
	v_add_u32_e32 v2, s77, v224
	ds_read_b128 v[60:63], v2
	ds_read_b128 v[64:67], v2 offset:1024
	ds_read_b128 v[164:167], v2 offset:2048
	ds_read_b128 v[168:171], v2 offset:3072
	s_add_u32 s4, s4, s28
	s_addc_u32 s5, s5, s29
	s_mov_b32 m0, s27
	ds_read_b128 v[68:71], v238 offset:32768
	ds_read_b128 v[72:75], v238 offset:33792
	ds_read_b128 v[184:187], v238 offset:34816
	ds_read_b128 v[188:191], v238 offset:35840
	ds_read_b128 v[198:201], v238 offset:36864
	ds_read_b128 v[202:205], v238 offset:37888
	ds_read_b128 v[206:209], v238 offset:38912
	ds_read_b128 v[210:213], v238 offset:39936
	global_load_lds_dwordx4 v172, s[4:5]
	s_mov_b32 m0, s36
	s_nop 0
	global_load_lds_dwordx4 v176, s[4:5]
	s_waitcnt vmcnt(8)
	s_waitcnt lgkmcnt(0)
	s_barrier
; #define PG8_STAGE(bufoff, gbase, voff) do { _Pragma("unroll") for (int _i = 0; _i < 2; ++_i) \
;         __builtin_amdgcn_global_load_lds((const unsigned*)((const char*)(gbase) + (voff)[_i]), (PG8_LAS unsigned*)(lds + (bufoff) + ldsw + _i * 8192), 16, 0, 0); } while (0)
; #define PG8_LDA(dst, b, h) do { _Pragma("unroll") for (int m = 0; m < 4; ++m) _Pragma("unroll") for (int k = 0; k < 2; ++k) dst[m][k] = *(const PG8_LAS bf16x8*)(lds + PG8_SA(b, h) + aoff + m * 2048 + k * 1024); } while (0)
; #define PG8_MMA(ai, bj, At, Bt) do { __builtin_amdgcn_s_setprio(1); _Pragma("unroll") for (int m = 0; m < 4; ++m) _Pragma("unroll") for (int n = 0; n < 2; ++n) _Pragma("unroll") for (int k = 0; k < 2; ++k) \
;         acc[ai][bj][m][n] = __builtin_amdgcn_mfma_f32_16x16x32_bf16(Bt[n][k], At[m][k], acc[ai][bj][m][n], 0, 0, 0); __builtin_amdgcn_s_setprio(0); } while (0)
; #define PG8_WAIT_V(n) asm volatile("s_waitcnt vmcnt(" #n ")" ::: "memory")
; #define PG8_WAIT_L(n) asm volatile("s_waitcnt lgkmcnt(" #n ")" ::: "memory")
; #define PG8_BAR __builtin_amdgcn_s_barrier()
; #define PG8_SCHED __builtin_amdgcn_sched_barrier(0)
; template <class Epi, class Sched, bool ALIGN_EPI = false, bool SP2 = false, bool ACHUNK = false>
; __device__ __forceinline__ void gemm_phase(PG8_LAS unsigned char* lds, const Gemm g, const Sched& S, const Epi& E) {
;     ...
;         for (int t = 0; t < nt; t += 2) {
;     ...
;             PG8_WAIT_V(8); PG8_WAIT_L(0); PG8_BAR; PG8_MMA(0, 0, At, B0); PG8_MMA(0, 1, At, B1); PG8_BAR; PG8_SCHED;
;             PG8_LDA(At, 1, 1); PG8_STAGE(PG8_SB(1, 0), b3, voffB); PG8_STAGE(PG8_SB(1, 1), b3 + hstepB, voffB); PG8_STAGE(PG8_SA(1, 0), a3, voffA);
;             PG8_WAIT_V(8); PG8_WAIT_L(0); PG8_BAR; PG8_MMA(1, 0, At, B0); PG8_MMA(1, 1, At, B1); PG8_BAR; PG8_SCHED;
	s_setprio 1
	v_mfma_f32_16x16x32_bf16 v[148:151], v[44:47], v[68:71], v[148:151]
	v_mfma_f32_16x16x32_bf16 v[152:155], v[52:55], v[68:71], v[152:155]
	v_mfma_f32_16x16x32_bf16 v[132:135], v[44:47], v[184:187], v[132:135]
	v_mfma_f32_16x16x32_bf16 v[140:143], v[52:55], v[184:187], v[140:143]
	v_mfma_f32_16x16x32_bf16 v[136:139], v[44:47], v[198:201], v[136:139]
	v_mfma_f32_16x16x32_bf16 v[144:147], v[52:55], v[198:201], v[144:147]
	v_mfma_f32_16x16x32_bf16 v[160:163], v[44:47], v[206:209], v[160:163]
	v_mfma_f32_16x16x32_bf16 v[156:159], v[52:55], v[206:209], v[156:159]
	v_mfma_f32_16x16x32_bf16 v[148:151], v[48:51], v[72:75], v[148:151]
	v_mfma_f32_16x16x32_bf16 v[152:155], v[56:59], v[72:75], v[152:155]
	v_mfma_f32_16x16x32_bf16 v[132:135], v[48:51], v[188:191], v[132:135]
	v_mfma_f32_16x16x32_bf16 v[140:143], v[56:59], v[188:191], v[140:143]
	v_mfma_f32_16x16x32_bf16 v[136:139], v[48:51], v[202:205], v[136:139]
	v_mfma_f32_16x16x32_bf16 v[144:147], v[56:59], v[202:205], v[144:147]
	v_mfma_f32_16x16x32_bf16 v[160:163], v[48:51], v[210:213], v[160:163]
	v_mfma_f32_16x16x32_bf16 v[156:159], v[56:59], v[210:213], v[156:159]
	s_setprio 0
	s_setprio 1
	v_mfma_f32_16x16x32_bf16 v[124:127], v[60:63], v[68:71], v[124:127]
	v_mfma_f32_16x16x32_bf16 v[68:71], v[164:167], v[68:71], v[128:131]
	v_mfma_f32_16x16x32_bf16 v[128:131], v[168:171], v[72:75], v[68:71]
	v_mfma_f32_16x16x32_bf16 v[68:71], v[60:63], v[184:187], v[116:119]
	v_mfma_f32_16x16x32_bf16 v[116:119], v[64:67], v[188:191], v[68:71]
	v_mfma_f32_16x16x32_bf16 v[68:71], v[164:167], v[184:187], v[120:123]
	v_mfma_f32_16x16x32_bf16 v[120:123], v[168:171], v[188:191], v[68:71]
	v_mfma_f32_16x16x32_bf16 v[68:71], v[60:63], v[198:201], v[112:115]
	v_mfma_f32_16x16x32_bf16 v[112:115], v[64:67], v[202:205], v[68:71]
	v_mfma_f32_16x16x32_bf16 v[68:71], v[164:167], v[198:201], v[108:111]
	v_mfma_f32_16x16x32_bf16 v[108:111], v[168:171], v[202:205], v[68:71]
	v_mfma_f32_16x16x32_bf16 v[68:71], v[60:63], v[206:209], v[104:107]
	v_mfma_f32_16x16x32_bf16 v[104:107], v[64:67], v[210:213], v[68:71]
	v_mfma_f32_16x16x32_bf16 v[68:71], v[164:167], v[206:209], v[100:103]
	v_mfma_f32_16x16x32_bf16 v[124:127], v[64:67], v[72:75], v[124:127]
	v_mfma_f32_16x16x32_bf16 v[100:103], v[168:171], v[210:213], v[68:71]
	s_setprio 0
	s_barrier
	s_sub_u32 s4, s4, s28
	s_subb_u32 s5, s5, s29
	s_add_u32 s4, s4, s10
	s_addc_u32 s5, s5, s11
	s_add_u32 s78, s78, s10
	s_addc_u32 s79, s79, s11
	s_add_u32 s98, s98, s10
	s_addc_u32 s99, s99, s11
	s_add_i32 m0, s7, s17
	ds_read_b128 v[184:187], v238 offset:49152
	ds_read_b128 v[188:191], v238 offset:50176
	ds_read_b128 v[198:201], v238 offset:51200
	ds_read_b128 v[202:205], v238 offset:52224
	ds_read_b128 v[206:209], v238 offset:53248
	ds_read_b128 v[210:213], v238 offset:54272
	ds_read_b128 v[214:217], v238 offset:55296
	ds_read_b128 v[218:221], v238 offset:56320
	global_load_lds_dwordx4 v174, s[78:79]
	s_add_i32 m0, m0, 0x2000
	s_nop 0
	global_load_lds_dwordx4 v178, s[78:79]
	s_add_i32 m0, s77, s17
	s_nop 0
	global_load_lds_dwordx4 v174, s[98:99]
	s_add_i32 m0, m0, 0x2000
	s_nop 0
	global_load_lds_dwordx4 v178, s[98:99]
	s_mov_b32 m0, s52
	s_nop 0
	global_load_lds_dwordx4 v172, s[4:5]
	s_mov_b32 m0, s53
	s_nop 0
	global_load_lds_dwordx4 v176, s[4:5]
	s_waitcnt vmcnt(8)
	s_waitcnt lgkmcnt(0)
	s_barrier
	s_setprio 1
	v_mfma_f32_16x16x32_bf16 v[68:71], v[44:47], v[184:187], v[96:99]
	v_mfma_f32_16x16x32_bf16 v[96:99], v[48:51], v[188:191], v[68:71]
	v_mfma_f32_16x16x32_bf16 v[68:71], v[52:55], v[184:187], v[92:95]
	v_mfma_f32_16x16x32_bf16 v[92:95], v[56:59], v[188:191], v[68:71]
	v_mfma_f32_16x16x32_bf16 v[68:71], v[44:47], v[198:201], v[88:91]
	v_mfma_f32_16x16x32_bf16 v[88:91], v[48:51], v[202:205], v[68:71]
	v_mfma_f32_16x16x32_bf16 v[68:71], v[52:55], v[198:201], v[84:87]
	v_mfma_f32_16x16x32_bf16 v[84:87], v[56:59], v[202:205], v[68:71]
	v_mfma_f32_16x16x32_bf16 v[68:71], v[44:47], v[206:209], v[80:83]
	v_mfma_f32_16x16x32_bf16 v[36:39], v[44:47], v[214:217], v[36:39]
	v_mfma_f32_16x16x32_bf16 v[80:83], v[48:51], v[210:213], v[68:71]
	v_mfma_f32_16x16x32_bf16 v[68:71], v[52:55], v[206:209], v[76:79]
	v_mfma_f32_16x16x32_bf16 v[72:75], v[48:51], v[218:221], v[36:39]
	v_mfma_f32_16x16x32_bf16 v[36:39], v[52:55], v[214:217], v[40:43]
	v_mfma_f32_16x16x32_bf16 v[76:79], v[56:59], v[210:213], v[68:71]
	v_mfma_f32_16x16x32_bf16 v[68:71], v[56:59], v[218:221], v[36:39]
	s_setprio 0
	s_setprio 1
	v_mfma_f32_16x16x32_bf16 v[28:31], v[60:63], v[184:187], v[28:31]
	v_mfma_f32_16x16x32_bf16 v[32:35], v[164:167], v[184:187], v[32:35]
	v_mfma_f32_16x16x32_bf16 v[20:23], v[60:63], v[198:201], v[20:23]
	v_mfma_f32_16x16x32_bf16 v[24:27], v[164:167], v[198:201], v[24:27]
	v_mfma_f32_16x16x32_bf16 v[16:19], v[60:63], v[206:209], v[16:19]
	v_mfma_f32_16x16x32_bf16 v[12:15], v[164:167], v[206:209], v[12:15]
	v_mfma_f32_16x16x32_bf16 v[8:11], v[60:63], v[214:217], v[8:11]
	v_mfma_f32_16x16x32_bf16 v[4:7], v[164:167], v[214:217], v[4:7]
	v_mfma_f32_16x16x32_bf16 v[28:31], v[64:67], v[188:191], v[28:31]
	v_mfma_f32_16x16x32_bf16 v[32:35], v[168:171], v[188:191], v[32:35]
	v_mfma_f32_16x16x32_bf16 v[20:23], v[64:67], v[202:205], v[20:23]
	v_mfma_f32_16x16x32_bf16 v[24:27], v[168:171], v[202:205], v[24:27]
	v_mfma_f32_16x16x32_bf16 v[16:19], v[64:67], v[210:213], v[16:19]
	v_mfma_f32_16x16x32_bf16 v[12:15], v[168:171], v[210:213], v[12:15]
	v_mfma_f32_16x16x32_bf16 v[8:11], v[64:67], v[218:221], v[8:11]
	v_mfma_f32_16x16x32_bf16 v[4:7], v[168:171], v[218:221], v[4:7]
	s_setprio 0
	s_barrier
	s_add_u32 s8, s8, 0x100
	s_addc_u32 s9, s9, 0
	s_add_u32 s0, s0, 0x100
	s_addc_u32 s1, s1, 0
	s_cmp_ge_i32 s6, s37
	s_mov_b32 s4, s6
	s_cbranch_scc0 .LBB0_108
	v_readlane_b32 s78, v254, 23
	v_readlane_b32 s79, v254, 24

; #define PG8_STAGE(bufoff, gbase, voff) do { _Pragma("unroll") for (int _i = 0; _i < 2; ++_i) \
;         __builtin_amdgcn_global_load_lds((const unsigned*)((const char*)(gbase) + (voff)[_i]), (PG8_LAS unsigned*)(lds + (bufoff) + ldsw + _i * 8192), 16, 0, 0); } while (0)
; #define PG8_LDA(dst, b, h) do { _Pragma("unroll") for (int m = 0; m < 4; ++m) _Pragma("unroll") for (int k = 0; k < 2; ++k) dst[m][k] = *(const PG8_LAS bf16x8*)(lds + PG8_SA(b, h) + aoff + m * 2048 + k * 1024); } while (0)
; #define PG8_LDB(dst, b, h) do { _Pragma("unroll") for (int n = 0; n < 2; ++n) _Pragma("unroll") for (int k = 0; k < 2; ++k) dst[n][k] = *(const PG8_LAS bf16x8*)(lds + PG8_SB(b, h) + boff + n * 2048 + k * 1024); } while (0)
; #define PG8_MMA(ai, bj, At, Bt) do { __builtin_amdgcn_s_setprio(1); _Pragma("unroll") for (int m = 0; m < 4; ++m) _Pragma("unroll") for (int n = 0; n < 2; ++n) _Pragma("unroll") for (int k = 0; k < 2; ++k) \
;         acc[ai][bj][m][n] = __builtin_amdgcn_mfma_f32_16x16x32_bf16(Bt[n][k], At[m][k], acc[ai][bj][m][n], 0, 0, 0); __builtin_amdgcn_s_setprio(0); } while (0)
; #define PG8_WAIT_V(n) asm volatile("s_waitcnt vmcnt(" #n ")" ::: "memory")
; #define PG8_WAIT_L(n) asm volatile("s_waitcnt lgkmcnt(" #n ")" ::: "memory")
; #define PG8_BAR __builtin_amdgcn_s_barrier()
; #define PG8_SCHED __builtin_amdgcn_sched_barrier(0)
; template <class Epi, class Sched, bool ALIGN_EPI = false, bool SP2 = false, bool ACHUNK = false>
; __device__ __forceinline__ void gemm_phase(PG8_LAS unsigned char* lds, const Gemm g, const Sched& S, const Epi& E) {
;     ...
;             PG8_LDB(B0, 0, 0); PG8_LDB(B1, 0, 1); PG8_SCHED; PG8_LDA(At, 0, 0); PG8_STAGE(PG8_SA(1, 1), a1 + hstepA, voffA);
;             PG8_WAIT_V(8); PG8_WAIT_L(0); PG8_BAR; PG8_MMA(0, 0, At, B0); PG8_MMA(0, 1, At, B1); PG8_BAR; PG8_SCHED;
;             PG8_LDA(At, 0, 1); PG8_STAGE(PG8_SB(0, 0), b2, voffB); PG8_STAGE(PG8_SB(0, 1), b2 + hstepB, voffB); PG8_STAGE(PG8_SA(0, 0), a2, voffA);
.Lnl_wo:
	s_add_i32 s51, 0, 0x14000
	ds_read_b128 v[142:145], v151
	ds_read_b128 v[152:155], v151 offset:1024
	ds_read_b128 v[156:159], v151 offset:2048
	ds_read_b128 v[160:163], v151 offset:3072
	v_add_u32_e32 v151, s51, v147
	ds_read_b128 v[164:167], v151
	ds_read_b128 v[168:171], v151 offset:1024
	ds_read_b128 v[172:175], v151 offset:2048
	ds_read_b128 v[176:179], v151 offset:3072
	v_lshl_add_u64 v[192:193], s[20:21], 0, v[138:139]
	s_add_i32 m0, s27, 0xc000
	ds_read_b128 v[180:183], v149
	ds_read_b128 v[184:187], v149 offset:1024
	ds_read_b128 v[188:191], v149 offset:2048
	ds_read_b128 v[198:201], v149 offset:3072
	ds_read_b128 v[202:205], v149 offset:4096
	ds_read_b128 v[206:209], v149 offset:5120
	ds_read_b128 v[210:213], v149 offset:6144
	ds_read_b128 v[214:217], v149 offset:7168
	global_load_lds_dwordx4 v[192:193], off
	v_lshl_add_u64 v[192:193], s[20:21], 0, v[140:141]
	s_add_i32 m0, s27, 0xe000
	s_nop 0
	global_load_lds_dwordx4 v[192:193], off
	s_waitcnt vmcnt(8)
	s_waitcnt lgkmcnt(0)
	s_barrier
	s_setprio 1
	v_mfma_f32_16x16x32_bf16 v[120:123], v[142:145], v[180:183], v[120:123]
	v_mfma_f32_16x16x32_bf16 v[128:131], v[156:159], v[180:183], v[128:131]
	v_mfma_f32_16x16x32_bf16 v[104:107], v[142:145], v[188:191], v[104:107]
	v_mfma_f32_16x16x32_bf16 v[112:115], v[156:159], v[188:191], v[112:115]
	v_mfma_f32_16x16x32_bf16 v[88:91], v[142:145], v[202:205], v[88:91]
	v_mfma_f32_16x16x32_bf16 v[96:99], v[156:159], v[202:205], v[96:99]
	v_mfma_f32_16x16x32_bf16 v[72:75], v[142:145], v[210:213], v[72:75]
	v_mfma_f32_16x16x32_bf16 v[80:83], v[156:159], v[210:213], v[80:83]
	v_mfma_f32_16x16x32_bf16 v[120:123], v[152:155], v[184:187], v[120:123]
	v_mfma_f32_16x16x32_bf16 v[128:131], v[160:163], v[184:187], v[128:131]
	v_mfma_f32_16x16x32_bf16 v[104:107], v[152:155], v[198:201], v[104:107]
	v_mfma_f32_16x16x32_bf16 v[112:115], v[160:163], v[198:201], v[112:115]
	v_mfma_f32_16x16x32_bf16 v[88:91], v[152:155], v[206:209], v[88:91]
	v_mfma_f32_16x16x32_bf16 v[96:99], v[160:163], v[206:209], v[96:99]
	v_mfma_f32_16x16x32_bf16 v[72:75], v[152:155], v[214:217], v[72:75]
	v_mfma_f32_16x16x32_bf16 v[80:83], v[160:163], v[214:217], v[80:83]
	s_setprio 0
	s_setprio 1
	v_mfma_f32_16x16x32_bf16 v[116:119], v[164:167], v[180:183], v[116:119]
	v_mfma_f32_16x16x32_bf16 v[124:127], v[172:175], v[180:183], v[124:127]
	v_mfma_f32_16x16x32_bf16 v[100:103], v[164:167], v[188:191], v[100:103]
	v_mfma_f32_16x16x32_bf16 v[108:111], v[172:175], v[188:191], v[108:111]
	v_mfma_f32_16x16x32_bf16 v[84:87], v[164:167], v[202:205], v[84:87]
	v_mfma_f32_16x16x32_bf16 v[92:95], v[172:175], v[202:205], v[92:95]
	v_mfma_f32_16x16x32_bf16 v[68:71], v[164:167], v[210:213], v[68:71]
	v_mfma_f32_16x16x32_bf16 v[76:79], v[172:175], v[210:213], v[76:79]
	v_mfma_f32_16x16x32_bf16 v[116:119], v[168:171], v[184:187], v[116:119]
	v_mfma_f32_16x16x32_bf16 v[124:127], v[176:179], v[184:187], v[124:127]
	v_mfma_f32_16x16x32_bf16 v[100:103], v[168:171], v[198:201], v[100:103]
	v_mfma_f32_16x16x32_bf16 v[108:111], v[176:179], v[198:201], v[108:111]
	v_mfma_f32_16x16x32_bf16 v[84:87], v[168:171], v[206:209], v[84:87]
	v_mfma_f32_16x16x32_bf16 v[92:95], v[176:179], v[206:209], v[92:95]
	v_mfma_f32_16x16x32_bf16 v[68:71], v[168:171], v[214:217], v[68:71]
	v_mfma_f32_16x16x32_bf16 v[76:79], v[176:179], v[214:217], v[76:79]
	s_setprio 0
	s_barrier
	s_add_i32 s54, s54, s26
	v_lshl_add_u64 v[192:193], s[52:53], 0, v[2:3]
	s_mov_b32 m0, s54
	ds_read_b128 v[180:183], v149 offset:16384
	ds_read_b128 v[184:187], v149 offset:17408
	ds_read_b128 v[188:191], v149 offset:18432
	ds_read_b128 v[198:201], v149 offset:19456
	ds_read_b128 v[202:205], v149 offset:20480
	ds_read_b128 v[206:209], v149 offset:21504
	ds_read_b128 v[210:213], v149 offset:22528
	ds_read_b128 v[214:217], v149 offset:23552
	global_load_lds_dwordx4 v[192:193], off
	s_add_i32 m0, s54, 0x2000
	v_lshl_add_u64 v[218:219], s[52:53], 0, v[136:137]
	s_add_u32 s52, s52, s4
	s_addc_u32 s53, s53, s5
	s_add_i32 s51, s51, s26
	global_load_lds_dwordx4 v[218:219], off
	v_lshl_add_u64 v[220:221], s[52:53], 0, v[2:3]
	s_mov_b32 m0, s51
	v_lshl_add_u64 v[222:223], s[52:53], 0, v[136:137]
	global_load_lds_dwordx4 v[220:221], off
	s_add_i32 m0, s51, 0x2000
	v_lshl_add_u64 v[224:225], s[22:23], 0, v[132:133]
	global_load_lds_dwordx4 v[222:223], off
	s_mov_b32 m0, s27
	v_lshl_add_u64 v[232:233], s[22:23], 0, v[134:135]
	global_load_lds_dwordx4 v[224:225], off
	s_mov_b32 m0, s28
	s_nop 0
	global_load_lds_dwordx4 v[232:233], off
	s_waitcnt vmcnt(8)
	s_waitcnt lgkmcnt(0)
	s_barrier
; #define PG8_STAGE(bufoff, gbase, voff) do { _Pragma("unroll") for (int _i = 0; _i < 2; ++_i) \
;         __builtin_amdgcn_global_load_lds((const unsigned*)((const char*)(gbase) + (voff)[_i]), (PG8_LAS unsigned*)(lds + (bufoff) + ldsw + _i * 8192), 16, 0, 0); } while (0)
; #define PG8_LDA(dst, b, h) do { _Pragma("unroll") for (int m = 0; m < 4; ++m) _Pragma("unroll") for (int k = 0; k < 2; ++k) dst[m][k] = *(const PG8_LAS bf16x8*)(lds + PG8_SA(b, h) + aoff + m * 2048 + k * 1024); } while (0)
; #define PG8_LDB(dst, b, h) do { _Pragma("unroll") for (int n = 0; n < 2; ++n) _Pragma("unroll") for (int k = 0; k < 2; ++k) dst[n][k] = *(const PG8_LAS bf16x8*)(lds + PG8_SB(b, h) + boff + n * 2048 + k * 1024); } while (0)
; #define PG8_MMA(ai, bj, At, Bt) do { __builtin_amdgcn_s_setprio(1); _Pragma("unroll") for (int m = 0; m < 4; ++m) _Pragma("unroll") for (int n = 0; n < 2; ++n) _Pragma("unroll") for (int k = 0; k < 2; ++k) \
;         acc[ai][bj][m][n] = __builtin_amdgcn_mfma_f32_16x16x32_bf16(Bt[n][k], At[m][k], acc[ai][bj][m][n], 0, 0, 0); __builtin_amdgcn_s_setprio(0); } while (0)
; #define PG8_WAIT_V(n) asm volatile("s_waitcnt vmcnt(" #n ")" ::: "memory")
; #define PG8_WAIT_L(n) asm volatile("s_waitcnt lgkmcnt(" #n ")" ::: "memory")
; #define PG8_BAR __builtin_amdgcn_s_barrier()
; #define PG8_SCHED __builtin_amdgcn_sched_barrier(0)
; template <class Epi, class Sched, bool ALIGN_EPI = false, bool SP2 = false, bool ACHUNK = false>
; __device__ __forceinline__ void gemm_phase(PG8_LAS unsigned char* lds, const Gemm g, const Sched& S, const Epi& E) {
;     ...
;             PG8_WAIT_V(8); PG8_WAIT_L(0); PG8_BAR; PG8_MMA(1, 0, At, B0); PG8_MMA(1, 1, At, B1); PG8_BAR; PG8_SCHED;
;             PG8_LDB(B0, 1, 0); PG8_LDB(B1, 1, 1); PG8_SCHED; PG8_LDA(At, 1, 0); PG8_STAGE(PG8_SA(0, 1), a2 + hstepA, voffA);
;             PG8_WAIT_V(8); PG8_WAIT_L(0); PG8_BAR; PG8_MMA(0, 0, At, B0); PG8_MMA(0, 1, At, B1); PG8_BAR; PG8_SCHED;
	s_setprio 1
	v_mfma_f32_16x16x32_bf16 v[56:59], v[142:145], v[180:183], v[56:59]
	v_mfma_f32_16x16x32_bf16 v[64:67], v[156:159], v[180:183], v[64:67]
	v_mfma_f32_16x16x32_bf16 v[40:43], v[142:145], v[188:191], v[40:43]
	v_mfma_f32_16x16x32_bf16 v[48:51], v[156:159], v[188:191], v[48:51]
	v_mfma_f32_16x16x32_bf16 v[24:27], v[142:145], v[202:205], v[24:27]
	v_mfma_f32_16x16x32_bf16 v[32:35], v[156:159], v[202:205], v[32:35]
	v_mfma_f32_16x16x32_bf16 v[8:11], v[142:145], v[210:213], v[8:11]
	v_mfma_f32_16x16x32_bf16 v[16:19], v[156:159], v[210:213], v[16:19]
	v_mfma_f32_16x16x32_bf16 v[56:59], v[152:155], v[184:187], v[56:59]
	v_mfma_f32_16x16x32_bf16 v[64:67], v[160:163], v[184:187], v[64:67]
	v_mfma_f32_16x16x32_bf16 v[40:43], v[152:155], v[198:201], v[40:43]
	v_mfma_f32_16x16x32_bf16 v[48:51], v[160:163], v[198:201], v[48:51]
	v_mfma_f32_16x16x32_bf16 v[24:27], v[152:155], v[206:209], v[24:27]
	v_mfma_f32_16x16x32_bf16 v[32:35], v[160:163], v[206:209], v[32:35]
	v_mfma_f32_16x16x32_bf16 v[8:11], v[152:155], v[214:217], v[8:11]
	v_mfma_f32_16x16x32_bf16 v[16:19], v[160:163], v[214:217], v[16:19]
	s_setprio 0
	s_setprio 1
	v_mfma_f32_16x16x32_bf16 v[52:55], v[164:167], v[180:183], v[52:55]
	v_mfma_f32_16x16x32_bf16 v[60:63], v[172:175], v[180:183], v[60:63]
	v_mfma_f32_16x16x32_bf16 v[36:39], v[164:167], v[188:191], v[36:39]
	v_mfma_f32_16x16x32_bf16 v[44:47], v[172:175], v[188:191], v[44:47]
	v_mfma_f32_16x16x32_bf16 v[20:23], v[164:167], v[202:205], v[20:23]
	v_mfma_f32_16x16x32_bf16 v[28:31], v[172:175], v[202:205], v[28:31]
	v_mfma_f32_16x16x32_bf16 v[4:7], v[164:167], v[210:213], v[4:7]
	v_mfma_f32_16x16x32_bf16 v[12:15], v[172:175], v[210:213], v[12:15]
	v_mfma_f32_16x16x32_bf16 v[52:55], v[168:171], v[184:187], v[52:55]
	v_mfma_f32_16x16x32_bf16 v[60:63], v[176:179], v[184:187], v[60:63]
	v_mfma_f32_16x16x32_bf16 v[36:39], v[168:171], v[198:201], v[36:39]
	v_mfma_f32_16x16x32_bf16 v[44:47], v[176:179], v[198:201], v[44:47]
	v_mfma_f32_16x16x32_bf16 v[20:23], v[168:171], v[206:209], v[20:23]
	v_mfma_f32_16x16x32_bf16 v[28:31], v[176:179], v[206:209], v[28:31]
	v_mfma_f32_16x16x32_bf16 v[4:7], v[168:171], v[214:217], v[4:7]
	v_mfma_f32_16x16x32_bf16 v[12:15], v[176:179], v[214:217], v[12:15]
	s_setprio 0
	s_barrier
	s_add_i32 s51, 0, 0x18000
	v_add_u32_e32 v151, s51, v147
	s_add_i32 s52, 0, 0x1c000
	ds_read_b128 v[142:145], v151
	ds_read_b128 v[152:155], v151 offset:1024
	ds_read_b128 v[156:159], v151 offset:2048
	ds_read_b128 v[160:163], v151 offset:3072
	v_add_u32_e32 v151, s52, v147
	ds_read_b128 v[164:167], v151
	ds_read_b128 v[168:171], v151 offset:1024
	ds_read_b128 v[172:175], v151 offset:2048
	ds_read_b128 v[176:179], v151 offset:3072
	s_add_u32 s22, s22, s4
	s_addc_u32 s23, s23, s5
	s_mov_b32 m0, s29
	v_lshl_add_u64 v[234:235], s[22:23], 0, v[132:133]
	ds_read_b128 v[180:183], v149 offset:32768
	ds_read_b128 v[184:187], v149 offset:33792
	ds_read_b128 v[188:191], v149 offset:34816
	ds_read_b128 v[198:201], v149 offset:35840
	ds_read_b128 v[202:205], v149 offset:36864
	ds_read_b128 v[206:209], v149 offset:37888
	ds_read_b128 v[210:213], v149 offset:38912
	ds_read_b128 v[214:217], v149 offset:39936
	global_load_lds_dwordx4 v[234:235], off
	v_lshl_add_u64 v[234:235], s[22:23], 0, v[134:135]
	s_mov_b32 m0, s30
	s_nop 0
	global_load_lds_dwordx4 v[234:235], off
	s_waitcnt vmcnt(8)
	s_waitcnt lgkmcnt(0)
	s_barrier
	s_setprio 1
	v_mfma_f32_16x16x32_bf16 v[120:123], v[142:145], v[180:183], v[120:123]
	v_mfma_f32_16x16x32_bf16 v[128:131], v[156:159], v[180:183], v[128:131]
	v_mfma_f32_16x16x32_bf16 v[104:107], v[142:145], v[188:191], v[104:107]
	v_mfma_f32_16x16x32_bf16 v[112:115], v[156:159], v[188:191], v[112:115]
	v_mfma_f32_16x16x32_bf16 v[88:91], v[142:145], v[202:205], v[88:91]
	v_mfma_f32_16x16x32_bf16 v[96:99], v[156:159], v[202:205], v[96:99]
	v_mfma_f32_16x16x32_bf16 v[72:75], v[142:145], v[210:213], v[72:75]
	v_mfma_f32_16x16x32_bf16 v[80:83], v[156:159], v[210:213], v[80:83]
	v_mfma_f32_16x16x32_bf16 v[120:123], v[152:155], v[184:187], v[120:123]
	v_mfma_f32_16x16x32_bf16 v[128:131], v[160:163], v[184:187], v[128:131]
	v_mfma_f32_16x16x32_bf16 v[104:107], v[152:155], v[198:201], v[104:107]
	v_mfma_f32_16x16x32_bf16 v[112:115], v[160:163], v[198:201], v[112:115]
	v_mfma_f32_16x16x32_bf16 v[88:91], v[152:155], v[206:209], v[88:91]
	v_mfma_f32_16x16x32_bf16 v[96:99], v[160:163], v[206:209], v[96:99]
	v_mfma_f32_16x16x32_bf16 v[72:75], v[152:155], v[214:217], v[72:75]
	v_mfma_f32_16x16x32_bf16 v[80:83], v[160:163], v[214:217], v[80:83]
	s_setprio 0
	s_setprio 1
	v_mfma_f32_16x16x32_bf16 v[116:119], v[164:167], v[180:183], v[116:119]
	v_mfma_f32_16x16x32_bf16 v[124:127], v[172:175], v[180:183], v[124:127]
	v_mfma_f32_16x16x32_bf16 v[100:103], v[164:167], v[188:191], v[100:103]
	v_mfma_f32_16x16x32_bf16 v[108:111], v[172:175], v[188:191], v[108:111]
	v_mfma_f32_16x16x32_bf16 v[84:87], v[164:167], v[202:205], v[84:87]
	v_mfma_f32_16x16x32_bf16 v[92:95], v[172:175], v[202:205], v[92:95]
	v_mfma_f32_16x16x32_bf16 v[68:71], v[164:167], v[210:213], v[68:71]
	v_mfma_f32_16x16x32_bf16 v[76:79], v[172:175], v[210:213], v[76:79]
	v_mfma_f32_16x16x32_bf16 v[116:119], v[168:171], v[184:187], v[116:119]
	v_mfma_f32_16x16x32_bf16 v[124:127], v[176:179], v[184:187], v[124:127]
	v_mfma_f32_16x16x32_bf16 v[100:103], v[168:171], v[198:201], v[100:103]
	v_mfma_f32_16x16x32_bf16 v[108:111], v[176:179], v[198:201], v[108:111]
	v_mfma_f32_16x16x32_bf16 v[84:87], v[168:171], v[206:209], v[84:87]
	v_mfma_f32_16x16x32_bf16 v[92:95], v[176:179], v[206:209], v[92:95]
	v_mfma_f32_16x16x32_bf16 v[68:71], v[168:171], v[214:217], v[68:71]
	v_mfma_f32_16x16x32_bf16 v[76:79], v[176:179], v[214:217], v[76:79]
	s_setprio 0
	s_barrier
; #define PG8_STAGE(bufoff, gbase, voff) do { _Pragma("unroll") for (int _i = 0; _i < 2; ++_i) \
;         __builtin_amdgcn_global_load_lds((const unsigned*)((const char*)(gbase) + (voff)[_i]), (PG8_LAS unsigned*)(lds + (bufoff) + ldsw + _i * 8192), 16, 0, 0); } while (0)
; #define PG8_LDA(dst, b, h) do { _Pragma("unroll") for (int m = 0; m < 4; ++m) _Pragma("unroll") for (int k = 0; k < 2; ++k) dst[m][k] = *(const PG8_LAS bf16x8*)(lds + PG8_SA(b, h) + aoff + m * 2048 + k * 1024); } while (0)
; #define PG8_MMA(ai, bj, At, Bt) do { __builtin_amdgcn_s_setprio(1); _Pragma("unroll") for (int m = 0; m < 4; ++m) _Pragma("unroll") for (int n = 0; n < 2; ++n) _Pragma("unroll") for (int k = 0; k < 2; ++k) \
;         acc[ai][bj][m][n] = __builtin_amdgcn_mfma_f32_16x16x32_bf16(Bt[n][k], At[m][k], acc[ai][bj][m][n], 0, 0, 0); __builtin_amdgcn_s_setprio(0); } while (0)
; #define PG8_WAIT_V(n) asm volatile("s_waitcnt vmcnt(" #n ")" ::: "memory")
; #define PG8_WAIT_L(n) asm volatile("s_waitcnt lgkmcnt(" #n ")" ::: "memory")
; #define PG8_BAR __builtin_amdgcn_s_barrier()
; #define PG8_SCHED __builtin_amdgcn_sched_barrier(0)
; template <class Epi, class Sched, bool ALIGN_EPI = false, bool SP2 = false, bool ACHUNK = false>
; __device__ __forceinline__ void gemm_phase(PG8_LAS unsigned char* lds, const Gemm g, const Sched& S, const Epi& E) {
;     ...
;             PG8_LDA(At, 1, 1); PG8_STAGE(PG8_SB(1, 0), b3, voffB); PG8_STAGE(PG8_SB(1, 1), b3 + hstepB, voffB); PG8_STAGE(PG8_SA(1, 0), a3, voffA);
;             PG8_WAIT_V(8); PG8_WAIT_L(0); PG8_BAR; PG8_MMA(1, 0, At, B0); PG8_MMA(1, 1, At, B1); PG8_BAR; PG8_SCHED;
	s_add_i32 s22, s51, s26
	v_lshl_add_u64 v[192:193], v[192:193], 0, s[10:11]
	s_mov_b32 m0, s22
	ds_read_b128 v[180:183], v149 offset:49152
	ds_read_b128 v[184:187], v149 offset:50176
	ds_read_b128 v[188:191], v149 offset:51200
	ds_read_b128 v[198:201], v149 offset:52224
	ds_read_b128 v[202:205], v149 offset:53248
	ds_read_b128 v[206:209], v149 offset:54272
	ds_read_b128 v[210:213], v149 offset:55296
	ds_read_b128 v[214:217], v149 offset:56320
	global_load_lds_dwordx4 v[192:193], off
	v_lshl_add_u64 v[192:193], v[218:219], 0, s[10:11]
	s_add_i32 m0, s22, 0x2000
	s_add_i32 s22, s52, s26
	global_load_lds_dwordx4 v[192:193], off
	v_lshl_add_u64 v[192:193], v[220:221], 0, s[10:11]
	s_mov_b32 m0, s22
	s_nop 0
	global_load_lds_dwordx4 v[192:193], off
	v_lshl_add_u64 v[192:193], v[222:223], 0, s[10:11]
	s_add_i32 m0, s22, 0x2000
	s_nop 0
	global_load_lds_dwordx4 v[192:193], off
	v_lshl_add_u64 v[192:193], v[224:225], 0, s[10:11]
	s_mov_b32 m0, s31
	s_nop 0
	global_load_lds_dwordx4 v[192:193], off
	v_lshl_add_u64 v[192:193], v[232:233], 0, s[10:11]
	s_mov_b32 m0, s33
	s_nop 0
	global_load_lds_dwordx4 v[192:193], off
	s_waitcnt vmcnt(8)
	s_waitcnt lgkmcnt(0)
	s_barrier
	s_setprio 1
	v_mfma_f32_16x16x32_bf16 v[56:59], v[142:145], v[180:183], v[56:59]
	v_mfma_f32_16x16x32_bf16 v[64:67], v[156:159], v[180:183], v[64:67]
	v_mfma_f32_16x16x32_bf16 v[40:43], v[142:145], v[188:191], v[40:43]
	v_mfma_f32_16x16x32_bf16 v[48:51], v[156:159], v[188:191], v[48:51]
	v_mfma_f32_16x16x32_bf16 v[24:27], v[142:145], v[202:205], v[24:27]
	v_mfma_f32_16x16x32_bf16 v[32:35], v[156:159], v[202:205], v[32:35]
	v_mfma_f32_16x16x32_bf16 v[8:11], v[142:145], v[210:213], v[8:11]
	v_mfma_f32_16x16x32_bf16 v[16:19], v[156:159], v[210:213], v[16:19]
	v_mfma_f32_16x16x32_bf16 v[56:59], v[152:155], v[184:187], v[56:59]
	v_mfma_f32_16x16x32_bf16 v[64:67], v[160:163], v[184:187], v[64:67]
	v_mfma_f32_16x16x32_bf16 v[40:43], v[152:155], v[198:201], v[40:43]
	v_mfma_f32_16x16x32_bf16 v[48:51], v[160:163], v[198:201], v[48:51]
	v_mfma_f32_16x16x32_bf16 v[24:27], v[152:155], v[206:209], v[24:27]
	v_mfma_f32_16x16x32_bf16 v[32:35], v[160:163], v[206:209], v[32:35]
	v_mfma_f32_16x16x32_bf16 v[8:11], v[152:155], v[214:217], v[8:11]
	v_mfma_f32_16x16x32_bf16 v[16:19], v[160:163], v[214:217], v[16:19]
	s_setprio 0
	s_setprio 1
	v_mfma_f32_16x16x32_bf16 v[52:55], v[164:167], v[180:183], v[52:55]
	v_mfma_f32_16x16x32_bf16 v[60:63], v[172:175], v[180:183], v[60:63]
	v_mfma_f32_16x16x32_bf16 v[36:39], v[164:167], v[188:191], v[36:39]
	v_mfma_f32_16x16x32_bf16 v[44:47], v[172:175], v[188:191], v[44:47]
	v_mfma_f32_16x16x32_bf16 v[20:23], v[164:167], v[202:205], v[20:23]
	v_mfma_f32_16x16x32_bf16 v[28:31], v[172:175], v[202:205], v[28:31]
	v_mfma_f32_16x16x32_bf16 v[4:7], v[164:167], v[210:213], v[4:7]
	v_mfma_f32_16x16x32_bf16 v[12:15], v[172:175], v[210:213], v[12:15]
	v_mfma_f32_16x16x32_bf16 v[52:55], v[168:171], v[184:187], v[52:55]
	v_mfma_f32_16x16x32_bf16 v[60:63], v[176:179], v[184:187], v[60:63]
	v_mfma_f32_16x16x32_bf16 v[36:39], v[168:171], v[198:201], v[36:39]
	v_mfma_f32_16x16x32_bf16 v[44:47], v[176:179], v[198:201], v[44:47]
	v_mfma_f32_16x16x32_bf16 v[20:23], v[168:171], v[206:209], v[20:23]
	v_mfma_f32_16x16x32_bf16 v[28:31], v[176:179], v[206:209], v[28:31]
	v_mfma_f32_16x16x32_bf16 v[4:7], v[168:171], v[214:217], v[4:7]
	v_mfma_f32_16x16x32_bf16 v[12:15], v[176:179], v[214:217], v[12:15]
	s_setprio 0
	s_barrier
	s_add_u32 s48, s48, 0x100
	s_addc_u32 s49, s49, 0
	s_add_u32 s20, s20, 0x100
	s_addc_u32 s21, s21, 0
	s_cmp_ge_i32 s50, s34
	s_mov_b32 s22, s50
	s_cbranch_scc0 .LBB0_216
	v_readlane_b32 s54, v254, 25
	v_readlane_b32 s52, v254, 27
	v_readlane_b32 s55, v254, 26
	v_readlane_b32 s53, v254, 28
	s_mov_b32 s50, s94
	s_and_b64 vcc, exec, s[16:17]
	s_cbranch_vccnz .LBB0_221
	s_branch .LBB0_222

; #define PG8_STAGE(bufoff, gbase, voff) do { _Pragma("unroll") for (int _i = 0; _i < 2; ++_i) \
;         __builtin_amdgcn_global_load_lds((const unsigned*)((const char*)(gbase) + (voff)[_i]), (PG8_LAS unsigned*)(lds + (bufoff) + ldsw + _i * 8192), 16, 0, 0); } while (0)
; #define PG8_LDA(dst, b, h) do { _Pragma("unroll") for (int m = 0; m < 4; ++m) _Pragma("unroll") for (int k = 0; k < 2; ++k) dst[m][k] = *(const PG8_LAS bf16x8*)(lds + PG8_SA(b, h) + aoff + m * 2048 + k * 1024); } while (0)
; #define PG8_LDB(dst, b, h) do { _Pragma("unroll") for (int n = 0; n < 2; ++n) _Pragma("unroll") for (int k = 0; k < 2; ++k) dst[n][k] = *(const PG8_LAS bf16x8*)(lds + PG8_SB(b, h) + boff + n * 2048 + k * 1024); } while (0)
; #define PG8_MMA(ai, bj, At, Bt) do { __builtin_amdgcn_s_setprio(1); _Pragma("unroll") for (int m = 0; m < 4; ++m) _Pragma("unroll") for (int n = 0; n < 2; ++n) _Pragma("unroll") for (int k = 0; k < 2; ++k) \
;         acc[ai][bj][m][n] = __builtin_amdgcn_mfma_f32_16x16x32_bf16(Bt[n][k], At[m][k], acc[ai][bj][m][n], 0, 0, 0); __builtin_amdgcn_s_setprio(0); } while (0)
; #define PG8_WAIT_V(n) asm volatile("s_waitcnt vmcnt(" #n ")" ::: "memory")
; #define PG8_WAIT_L(n) asm volatile("s_waitcnt lgkmcnt(" #n ")" ::: "memory")
; #define PG8_BAR __builtin_amdgcn_s_barrier()
; #define PG8_SCHED __builtin_amdgcn_sched_barrier(0)
; template <class Epi, class Sched, bool ALIGN_EPI = false, bool SP2 = false, bool ACHUNK = false>
; __device__ __forceinline__ void gemm_phase(PG8_LAS unsigned char* lds, const Gemm g, const Sched& S, const Epi& E) {
;     ...
;             PG8_LDB(B0, 0, 0); PG8_LDB(B1, 0, 1); PG8_SCHED; PG8_LDA(At, 0, 0); PG8_STAGE(PG8_SA(1, 1), a1 + hstepA, voffA);
;             PG8_WAIT_V(8); PG8_WAIT_L(0); PG8_BAR; PG8_MMA(0, 0, At, B0); PG8_MMA(0, 1, At, B1); PG8_BAR; PG8_SCHED;
;             PG8_LDA(At, 0, 1); PG8_STAGE(PG8_SB(0, 0), b2, voffB); PG8_STAGE(PG8_SB(0, 1), b2 + hstepB, voffB); PG8_STAGE(PG8_SA(0, 0), a2, voffA);
;             PG8_WAIT_V(8); PG8_WAIT_L(0); PG8_BAR; PG8_MMA(1, 0, At, B0); PG8_MMA(1, 1, At, B1); PG8_BAR; PG8_SCHED;
.Lnl_mg:
	s_add_i32 s54, 0, 0x14000
	ds_read_b128 v[134:137], v2
	ds_read_b128 v[138:141], v2 offset:1024
	ds_read_b128 v[142:145], v2 offset:2048
	ds_read_b128 v[146:149], v2 offset:3072
	v_add_u32_e32 v2, s54, v235
	ds_read_b128 v[150:153], v2
	ds_read_b128 v[154:157], v2 offset:1024
	ds_read_b128 v[158:161], v2 offset:2048
	ds_read_b128 v[162:165], v2 offset:3072
	v_lshl_add_u64 v[4:5], v[210:211], 0, s[6:7]
	s_add_i32 m0, s17, 0xc000
	ds_read_b128 v[166:169], v237
	ds_read_b128 v[170:173], v237 offset:1024
	ds_read_b128 v[174:177], v237 offset:2048
	ds_read_b128 v[178:181], v237 offset:3072
	ds_read_b128 v[182:185], v237 offset:4096
	ds_read_b128 v[186:189], v237 offset:5120
	ds_read_b128 v[190:193], v237 offset:6144
	ds_read_b128 v[214:217], v237 offset:7168
	global_load_lds_dwordx4 v[4:5], off
	v_lshl_add_u64 v[4:5], v[212:213], 0, s[6:7]
	s_add_i32 m0, s17, 0xe000
	s_nop 0
	global_load_lds_dwordx4 v[4:5], off
	s_waitcnt vmcnt(8)
	s_waitcnt lgkmcnt(0)
	s_barrier
	s_setprio 1
	v_mfma_f32_16x16x32_bf16 v[126:129], v[134:137], v[166:169], v[126:129]
	v_mfma_f32_16x16x32_bf16 v[130:133], v[142:145], v[166:169], v[130:133]
	v_mfma_f32_16x16x32_bf16 v[114:117], v[134:137], v[174:177], v[114:117]
	v_mfma_f32_16x16x32_bf16 v[110:113], v[142:145], v[174:177], v[110:113]
	v_mfma_f32_16x16x32_bf16 v[98:101], v[134:137], v[182:185], v[98:101]
	v_mfma_f32_16x16x32_bf16 v[94:97], v[142:145], v[182:185], v[94:97]
	v_mfma_f32_16x16x32_bf16 v[82:85], v[134:137], v[190:193], v[82:85]
	v_mfma_f32_16x16x32_bf16 v[78:81], v[142:145], v[190:193], v[78:81]
	v_mfma_f32_16x16x32_bf16 v[126:129], v[138:141], v[170:173], v[126:129]
	v_mfma_f32_16x16x32_bf16 v[130:133], v[146:149], v[170:173], v[130:133]
	v_mfma_f32_16x16x32_bf16 v[114:117], v[138:141], v[178:181], v[114:117]
	v_mfma_f32_16x16x32_bf16 v[110:113], v[146:149], v[178:181], v[110:113]
	v_mfma_f32_16x16x32_bf16 v[98:101], v[138:141], v[186:189], v[98:101]
	v_mfma_f32_16x16x32_bf16 v[94:97], v[146:149], v[186:189], v[94:97]
	v_mfma_f32_16x16x32_bf16 v[82:85], v[138:141], v[214:217], v[82:85]
	v_mfma_f32_16x16x32_bf16 v[78:81], v[146:149], v[214:217], v[78:81]
	s_setprio 0
	s_setprio 1
	v_mfma_f32_16x16x32_bf16 v[122:125], v[150:153], v[166:169], v[122:125]
	v_mfma_f32_16x16x32_bf16 v[118:121], v[158:161], v[166:169], v[118:121]
	v_mfma_f32_16x16x32_bf16 v[106:109], v[150:153], v[174:177], v[106:109]
	v_mfma_f32_16x16x32_bf16 v[102:105], v[158:161], v[174:177], v[102:105]
	v_mfma_f32_16x16x32_bf16 v[90:93], v[150:153], v[182:185], v[90:93]
	v_mfma_f32_16x16x32_bf16 v[86:89], v[158:161], v[182:185], v[86:89]
	v_mfma_f32_16x16x32_bf16 v[74:77], v[150:153], v[190:193], v[74:77]
	v_mfma_f32_16x16x32_bf16 v[70:73], v[158:161], v[190:193], v[70:73]
	v_mfma_f32_16x16x32_bf16 v[122:125], v[154:157], v[170:173], v[122:125]
	v_mfma_f32_16x16x32_bf16 v[118:121], v[162:165], v[170:173], v[118:121]
	v_mfma_f32_16x16x32_bf16 v[106:109], v[154:157], v[178:181], v[106:109]
	v_mfma_f32_16x16x32_bf16 v[102:105], v[162:165], v[178:181], v[102:105]
	v_mfma_f32_16x16x32_bf16 v[90:93], v[154:157], v[186:189], v[90:93]
	v_mfma_f32_16x16x32_bf16 v[86:89], v[162:165], v[186:189], v[86:89]
	v_mfma_f32_16x16x32_bf16 v[74:77], v[154:157], v[214:217], v[74:77]
	v_mfma_f32_16x16x32_bf16 v[70:73], v[162:165], v[214:217], v[70:73]
	s_setprio 0
	s_barrier
	s_add_i32 s55, s55, s16
	v_lshl_add_u64 v[218:219], s[52:53], 0, v[200:201]
	s_mov_b32 m0, s55
	ds_read_b128 v[166:169], v237 offset:16384
	ds_read_b128 v[170:173], v237 offset:17408
	ds_read_b128 v[174:177], v237 offset:18432
	ds_read_b128 v[178:181], v237 offset:19456
	ds_read_b128 v[182:185], v237 offset:20480
	ds_read_b128 v[186:189], v237 offset:21504
	ds_read_b128 v[190:193], v237 offset:22528
	ds_read_b128 v[214:217], v237 offset:23552
	global_load_lds_dwordx4 v[218:219], off
	s_add_i32 m0, s55, 0x2000
	v_lshl_add_u64 v[220:221], s[52:53], 0, v[204:205]
	s_add_u32 s52, s52, s2
	s_addc_u32 s53, s53, s3
	s_add_i32 s54, s54, s16
	global_load_lds_dwordx4 v[220:221], off
	v_lshl_add_u64 v[222:223], s[52:53], 0, v[200:201]
	s_mov_b32 m0, s54
	v_lshl_add_u64 v[224:225], s[52:53], 0, v[204:205]
	global_load_lds_dwordx4 v[222:223], off
	s_add_i32 m0, s54, 0x2000
	v_lshl_add_u64 v[238:239], s[8:9], 0, v[198:199]
	global_load_lds_dwordx4 v[224:225], off
	s_mov_b32 m0, s17
	v_lshl_add_u64 v[240:241], s[8:9], 0, v[202:203]
	global_load_lds_dwordx4 v[238:239], off
	s_mov_b32 m0, s20
	s_nop 0
	global_load_lds_dwordx4 v[240:241], off
	s_waitcnt vmcnt(8)
	s_waitcnt lgkmcnt(0)
	s_barrier
; #define PG8_STAGE(bufoff, gbase, voff) do { _Pragma("unroll") for (int _i = 0; _i < 2; ++_i) \
;         __builtin_amdgcn_global_load_lds((const unsigned*)((const char*)(gbase) + (voff)[_i]), (PG8_LAS unsigned*)(lds + (bufoff) + ldsw + _i * 8192), 16, 0, 0); } while (0)
; #define PG8_LDA(dst, b, h) do { _Pragma("unroll") for (int m = 0; m < 4; ++m) _Pragma("unroll") for (int k = 0; k < 2; ++k) dst[m][k] = *(const PG8_LAS bf16x8*)(lds + PG8_SA(b, h) + aoff + m * 2048 + k * 1024); } while (0)
; #define PG8_LDB(dst, b, h) do { _Pragma("unroll") for (int n = 0; n < 2; ++n) _Pragma("unroll") for (int k = 0; k < 2; ++k) dst[n][k] = *(const PG8_LAS bf16x8*)(lds + PG8_SB(b, h) + boff + n * 2048 + k * 1024); } while (0)
; #define PG8_MMA(ai, bj, At, Bt) do { __builtin_amdgcn_s_setprio(1); _Pragma("unroll") for (int m = 0; m < 4; ++m) _Pragma("unroll") for (int n = 0; n < 2; ++n) _Pragma("unroll") for (int k = 0; k < 2; ++k) \
;         acc[ai][bj][m][n] = __builtin_amdgcn_mfma_f32_16x16x32_bf16(Bt[n][k], At[m][k], acc[ai][bj][m][n], 0, 0, 0); __builtin_amdgcn_s_setprio(0); } while (0)
; #define PG8_WAIT_V(n) asm volatile("s_waitcnt vmcnt(" #n ")" ::: "memory")
; #define PG8_WAIT_L(n) asm volatile("s_waitcnt lgkmcnt(" #n ")" ::: "memory")
; #define PG8_BAR __builtin_amdgcn_s_barrier()
; #define PG8_SCHED __builtin_amdgcn_sched_barrier(0)
; template <class Epi, class Sched, bool ALIGN_EPI = false, bool SP2 = false, bool ACHUNK = false>
; __device__ __forceinline__ void gemm_phase(PG8_LAS unsigned char* lds, const Gemm g, const Sched& S, const Epi& E) {
;     ...
;             PG8_WAIT_V(8); PG8_WAIT_L(0); PG8_BAR; PG8_MMA(1, 0, At, B0); PG8_MMA(1, 1, At, B1); PG8_BAR; PG8_SCHED;
;             PG8_LDB(B0, 1, 0); PG8_LDB(B1, 1, 1); PG8_SCHED; PG8_LDA(At, 1, 0); PG8_STAGE(PG8_SA(0, 1), a2 + hstepA, voffA);
;             PG8_WAIT_V(8); PG8_WAIT_L(0); PG8_BAR; PG8_MMA(0, 0, At, B0); PG8_MMA(0, 1, At, B1); PG8_BAR; PG8_SCHED;
	s_setprio 1
	v_mfma_f32_16x16x32_bf16 v[66:69], v[134:137], v[166:169], v[66:69]
	v_mfma_f32_16x16x32_bf16 v[62:65], v[142:145], v[166:169], v[62:65]
	v_mfma_f32_16x16x32_bf16 v[50:53], v[134:137], v[174:177], v[50:53]
	v_mfma_f32_16x16x32_bf16 v[46:49], v[142:145], v[174:177], v[46:49]
	v_mfma_f32_16x16x32_bf16 v[34:37], v[134:137], v[182:185], v[34:37]
	v_mfma_f32_16x16x32_bf16 v[30:33], v[142:145], v[182:185], v[30:33]
	v_mfma_f32_16x16x32_bf16 v[18:21], v[134:137], v[190:193], v[18:21]
	v_mfma_f32_16x16x32_bf16 v[14:17], v[142:145], v[190:193], v[14:17]
	v_mfma_f32_16x16x32_bf16 v[66:69], v[138:141], v[170:173], v[66:69]
	v_mfma_f32_16x16x32_bf16 v[62:65], v[146:149], v[170:173], v[62:65]
	v_mfma_f32_16x16x32_bf16 v[50:53], v[138:141], v[178:181], v[50:53]
	v_mfma_f32_16x16x32_bf16 v[46:49], v[146:149], v[178:181], v[46:49]
	v_mfma_f32_16x16x32_bf16 v[34:37], v[138:141], v[186:189], v[34:37]
	v_mfma_f32_16x16x32_bf16 v[30:33], v[146:149], v[186:189], v[30:33]
	v_mfma_f32_16x16x32_bf16 v[18:21], v[138:141], v[214:217], v[18:21]
	v_mfma_f32_16x16x32_bf16 v[14:17], v[146:149], v[214:217], v[14:17]
	s_setprio 0
	s_setprio 1
	v_mfma_f32_16x16x32_bf16 v[58:61], v[150:153], v[166:169], v[58:61]
	v_mfma_f32_16x16x32_bf16 v[54:57], v[158:161], v[166:169], v[54:57]
	v_mfma_f32_16x16x32_bf16 v[42:45], v[150:153], v[174:177], v[42:45]
	v_mfma_f32_16x16x32_bf16 v[38:41], v[158:161], v[174:177], v[38:41]
	v_mfma_f32_16x16x32_bf16 v[26:29], v[150:153], v[182:185], v[26:29]
	v_mfma_f32_16x16x32_bf16 v[22:25], v[158:161], v[182:185], v[22:25]
	v_mfma_f32_16x16x32_bf16 v[10:13], v[150:153], v[190:193], v[10:13]
	v_mfma_f32_16x16x32_bf16 v[4:7], v[158:161], v[190:193], v[6:9]
	v_mfma_f32_16x16x32_bf16 v[58:61], v[154:157], v[170:173], v[58:61]
	v_mfma_f32_16x16x32_bf16 v[54:57], v[162:165], v[170:173], v[54:57]
	v_mfma_f32_16x16x32_bf16 v[42:45], v[154:157], v[178:181], v[42:45]
	v_mfma_f32_16x16x32_bf16 v[38:41], v[162:165], v[178:181], v[38:41]
	v_mfma_f32_16x16x32_bf16 v[26:29], v[154:157], v[186:189], v[26:29]
	v_mfma_f32_16x16x32_bf16 v[22:25], v[162:165], v[186:189], v[22:25]
	v_mfma_f32_16x16x32_bf16 v[10:13], v[154:157], v[214:217], v[10:13]
	v_mfma_f32_16x16x32_bf16 v[4:7], v[162:165], v[214:217], v[4:7]
	s_setprio 0
	s_barrier
	s_add_i32 s52, 0, 0x18000
	v_add_u32_e32 v2, s52, v235
	s_add_i32 s53, 0, 0x1c000
	ds_read_b128 v[134:137], v2
	ds_read_b128 v[138:141], v2 offset:1024
	ds_read_b128 v[142:145], v2 offset:2048
	ds_read_b128 v[146:149], v2 offset:3072
	v_add_u32_e32 v2, s53, v235
	ds_read_b128 v[150:153], v2
	ds_read_b128 v[154:157], v2 offset:1024
	ds_read_b128 v[158:161], v2 offset:2048
	ds_read_b128 v[162:165], v2 offset:3072
	s_add_u32 s8, s8, s2
	s_addc_u32 s9, s9, s3
	s_mov_b32 m0, s21
	v_lshl_add_u64 v[8:9], s[8:9], 0, v[198:199]
	ds_read_b128 v[166:169], v237 offset:32768
	ds_read_b128 v[170:173], v237 offset:33792
	ds_read_b128 v[174:177], v237 offset:34816
	ds_read_b128 v[178:181], v237 offset:35840
	ds_read_b128 v[182:185], v237 offset:36864
	ds_read_b128 v[186:189], v237 offset:37888
	ds_read_b128 v[190:193], v237 offset:38912
	ds_read_b128 v[214:217], v237 offset:39936
	global_load_lds_dwordx4 v[8:9], off
	v_lshl_add_u64 v[8:9], s[8:9], 0, v[202:203]
	s_mov_b32 m0, s22
	s_nop 0
	global_load_lds_dwordx4 v[8:9], off
	s_waitcnt vmcnt(8)
	s_waitcnt lgkmcnt(0)
	s_barrier
	s_setprio 1
	v_mfma_f32_16x16x32_bf16 v[126:129], v[134:137], v[166:169], v[126:129]
	v_mfma_f32_16x16x32_bf16 v[130:133], v[142:145], v[166:169], v[130:133]
	v_mfma_f32_16x16x32_bf16 v[114:117], v[134:137], v[174:177], v[114:117]
	v_mfma_f32_16x16x32_bf16 v[110:113], v[142:145], v[174:177], v[110:113]
	v_mfma_f32_16x16x32_bf16 v[98:101], v[134:137], v[182:185], v[98:101]
	v_mfma_f32_16x16x32_bf16 v[94:97], v[142:145], v[182:185], v[94:97]
	v_mfma_f32_16x16x32_bf16 v[82:85], v[134:137], v[190:193], v[82:85]
	v_mfma_f32_16x16x32_bf16 v[78:81], v[142:145], v[190:193], v[78:81]
	v_mfma_f32_16x16x32_bf16 v[126:129], v[138:141], v[170:173], v[126:129]
	v_mfma_f32_16x16x32_bf16 v[130:133], v[146:149], v[170:173], v[130:133]
	v_mfma_f32_16x16x32_bf16 v[114:117], v[138:141], v[178:181], v[114:117]
	v_mfma_f32_16x16x32_bf16 v[110:113], v[146:149], v[178:181], v[110:113]
	v_mfma_f32_16x16x32_bf16 v[98:101], v[138:141], v[186:189], v[98:101]
	v_mfma_f32_16x16x32_bf16 v[94:97], v[146:149], v[186:189], v[94:97]
	v_mfma_f32_16x16x32_bf16 v[82:85], v[138:141], v[214:217], v[82:85]
	v_mfma_f32_16x16x32_bf16 v[78:81], v[146:149], v[214:217], v[78:81]
	s_setprio 0
	s_setprio 1
	v_mfma_f32_16x16x32_bf16 v[122:125], v[150:153], v[166:169], v[122:125]
	v_mfma_f32_16x16x32_bf16 v[118:121], v[158:161], v[166:169], v[118:121]
	v_mfma_f32_16x16x32_bf16 v[106:109], v[150:153], v[174:177], v[106:109]
	v_mfma_f32_16x16x32_bf16 v[102:105], v[158:161], v[174:177], v[102:105]
	v_mfma_f32_16x16x32_bf16 v[90:93], v[150:153], v[182:185], v[90:93]
	v_mfma_f32_16x16x32_bf16 v[86:89], v[158:161], v[182:185], v[86:89]
	v_mfma_f32_16x16x32_bf16 v[74:77], v[150:153], v[190:193], v[74:77]
	v_mfma_f32_16x16x32_bf16 v[70:73], v[158:161], v[190:193], v[70:73]
	v_mfma_f32_16x16x32_bf16 v[122:125], v[154:157], v[170:173], v[122:125]
	v_mfma_f32_16x16x32_bf16 v[118:121], v[162:165], v[170:173], v[118:121]
	v_mfma_f32_16x16x32_bf16 v[106:109], v[154:157], v[178:181], v[106:109]
	v_mfma_f32_16x16x32_bf16 v[102:105], v[162:165], v[178:181], v[102:105]
	v_mfma_f32_16x16x32_bf16 v[90:93], v[154:157], v[186:189], v[90:93]
	v_mfma_f32_16x16x32_bf16 v[86:89], v[162:165], v[186:189], v[86:89]
	v_mfma_f32_16x16x32_bf16 v[74:77], v[154:157], v[214:217], v[74:77]
	v_mfma_f32_16x16x32_bf16 v[70:73], v[162:165], v[214:217], v[70:73]
	s_setprio 0
	s_barrier
; #define PG8_STAGE(bufoff, gbase, voff) do { _Pragma("unroll") for (int _i = 0; _i < 2; ++_i) \
;         __builtin_amdgcn_global_load_lds((const unsigned*)((const char*)(gbase) + (voff)[_i]), (PG8_LAS unsigned*)(lds + (bufoff) + ldsw + _i * 8192), 16, 0, 0); } while (0)
; #define PG8_LDA(dst, b, h) do { _Pragma("unroll") for (int m = 0; m < 4; ++m) _Pragma("unroll") for (int k = 0; k < 2; ++k) dst[m][k] = *(const PG8_LAS bf16x8*)(lds + PG8_SA(b, h) + aoff + m * 2048 + k * 1024); } while (0)
; #define PG8_MMA(ai, bj, At, Bt) do { __builtin_amdgcn_s_setprio(1); _Pragma("unroll") for (int m = 0; m < 4; ++m) _Pragma("unroll") for (int n = 0; n < 2; ++n) _Pragma("unroll") for (int k = 0; k < 2; ++k) \
;         acc[ai][bj][m][n] = __builtin_amdgcn_mfma_f32_16x16x32_bf16(Bt[n][k], At[m][k], acc[ai][bj][m][n], 0, 0, 0); __builtin_amdgcn_s_setprio(0); } while (0)
; #define PG8_WAIT_V(n) asm volatile("s_waitcnt vmcnt(" #n ")" ::: "memory")
; #define PG8_WAIT_L(n) asm volatile("s_waitcnt lgkmcnt(" #n ")" ::: "memory")
; #define PG8_BAR __builtin_amdgcn_s_barrier()
; #define PG8_SCHED __builtin_amdgcn_sched_barrier(0)
; template <class Epi, class Sched, bool ALIGN_EPI = false, bool SP2 = false, bool ACHUNK = false>
; __device__ __forceinline__ void gemm_phase(PG8_LAS unsigned char* lds, const Gemm g, const Sched& S, const Epi& E) {
;     ...
;         for (int t = 0; t < nt; t += 2) {
;     ...
;             PG8_LDA(At, 1, 1); PG8_STAGE(PG8_SB(1, 0), b3, voffB); PG8_STAGE(PG8_SB(1, 1), b3 + hstepB, voffB); PG8_STAGE(PG8_SA(1, 0), a3, voffA);
;             PG8_WAIT_V(8); PG8_WAIT_L(0); PG8_BAR; PG8_MMA(1, 0, At, B0); PG8_MMA(1, 1, At, B1); PG8_BAR; PG8_SCHED;
	s_add_i32 s8, s52, s16
	v_lshl_add_u64 v[8:9], v[218:219], 0, s[10:11]
	s_mov_b32 m0, s8
	ds_read_b128 v[166:169], v237 offset:49152
	ds_read_b128 v[170:173], v237 offset:50176
	ds_read_b128 v[174:177], v237 offset:51200
	ds_read_b128 v[178:181], v237 offset:52224
	ds_read_b128 v[182:185], v237 offset:53248
	ds_read_b128 v[186:189], v237 offset:54272
	ds_read_b128 v[190:193], v237 offset:55296
	ds_read_b128 v[214:217], v237 offset:56320
	global_load_lds_dwordx4 v[8:9], off
	v_lshl_add_u64 v[8:9], v[220:221], 0, s[10:11]
	s_add_i32 m0, s8, 0x2000
	s_add_i32 s8, s53, s16
	global_load_lds_dwordx4 v[8:9], off
	v_lshl_add_u64 v[8:9], v[222:223], 0, s[10:11]
	s_mov_b32 m0, s8
	s_nop 0
	global_load_lds_dwordx4 v[8:9], off
	v_lshl_add_u64 v[8:9], v[224:225], 0, s[10:11]
	s_add_i32 m0, s8, 0x2000
	s_nop 0
	global_load_lds_dwordx4 v[8:9], off
	v_lshl_add_u64 v[8:9], v[238:239], 0, s[10:11]
	s_mov_b32 m0, s26
	s_nop 0
	global_load_lds_dwordx4 v[8:9], off
	v_lshl_add_u64 v[8:9], v[240:241], 0, s[10:11]
	s_mov_b32 m0, s27
	s_nop 0
	global_load_lds_dwordx4 v[8:9], off
	s_waitcnt vmcnt(8)
	s_waitcnt lgkmcnt(0)
	s_barrier
	s_setprio 1
	v_mfma_f32_16x16x32_bf16 v[66:69], v[134:137], v[166:169], v[66:69]
	v_mfma_f32_16x16x32_bf16 v[62:65], v[142:145], v[166:169], v[62:65]
	v_mfma_f32_16x16x32_bf16 v[50:53], v[134:137], v[174:177], v[50:53]
	v_mfma_f32_16x16x32_bf16 v[46:49], v[142:145], v[174:177], v[46:49]
	v_mfma_f32_16x16x32_bf16 v[34:37], v[134:137], v[182:185], v[34:37]
	v_mfma_f32_16x16x32_bf16 v[30:33], v[142:145], v[182:185], v[30:33]
	v_mfma_f32_16x16x32_bf16 v[18:21], v[134:137], v[190:193], v[18:21]
	v_mfma_f32_16x16x32_bf16 v[14:17], v[142:145], v[190:193], v[14:17]
	v_mfma_f32_16x16x32_bf16 v[66:69], v[138:141], v[170:173], v[66:69]
	v_mfma_f32_16x16x32_bf16 v[62:65], v[146:149], v[170:173], v[62:65]
	v_mfma_f32_16x16x32_bf16 v[50:53], v[138:141], v[178:181], v[50:53]
	v_mfma_f32_16x16x32_bf16 v[46:49], v[146:149], v[178:181], v[46:49]
	v_mfma_f32_16x16x32_bf16 v[34:37], v[138:141], v[186:189], v[34:37]
	v_mfma_f32_16x16x32_bf16 v[30:33], v[146:149], v[186:189], v[30:33]
	v_mfma_f32_16x16x32_bf16 v[18:21], v[138:141], v[214:217], v[18:21]
	v_mfma_f32_16x16x32_bf16 v[14:17], v[146:149], v[214:217], v[14:17]
	s_setprio 0
	s_setprio 1
	v_mfma_f32_16x16x32_bf16 v[58:61], v[150:153], v[166:169], v[58:61]
	v_mfma_f32_16x16x32_bf16 v[54:57], v[158:161], v[166:169], v[54:57]
	v_mfma_f32_16x16x32_bf16 v[42:45], v[150:153], v[174:177], v[42:45]
	v_mfma_f32_16x16x32_bf16 v[38:41], v[158:161], v[174:177], v[38:41]
	v_mfma_f32_16x16x32_bf16 v[26:29], v[150:153], v[182:185], v[26:29]
	v_mfma_f32_16x16x32_bf16 v[22:25], v[158:161], v[182:185], v[22:25]
	v_mfma_f32_16x16x32_bf16 v[8:11], v[150:153], v[190:193], v[10:13]
	v_mfma_f32_16x16x32_bf16 v[4:7], v[158:161], v[190:193], v[4:7]
	v_mfma_f32_16x16x32_bf16 v[58:61], v[154:157], v[170:173], v[58:61]
	v_mfma_f32_16x16x32_bf16 v[54:57], v[162:165], v[170:173], v[54:57]
	v_mfma_f32_16x16x32_bf16 v[42:45], v[154:157], v[178:181], v[42:45]
	v_mfma_f32_16x16x32_bf16 v[38:41], v[162:165], v[178:181], v[38:41]
	v_mfma_f32_16x16x32_bf16 v[26:29], v[154:157], v[186:189], v[26:29]
	v_mfma_f32_16x16x32_bf16 v[22:25], v[162:165], v[186:189], v[22:25]
	v_mfma_f32_16x16x32_bf16 v[10:13], v[154:157], v[214:217], v[8:11]
	v_mfma_f32_16x16x32_bf16 v[6:9], v[162:165], v[214:217], v[4:7]
	s_setprio 0
	s_barrier
	s_add_u32 s6, s6, 0x100
	s_addc_u32 s7, s7, 0
	s_cmp_ge_i32 s51, s23
	s_cbranch_scc0 .LBB0_266
	v_readlane_b32 s54, v254, 25
	v_readlane_b32 s52, v254, 27
	v_readlane_b32 s55, v254, 26
	v_readlane_b32 s53, v254, 28
	v_readlane_b32 s47, v255, 0
	s_mov_b32 s50, s94

; #define PG8_STAGE(bufoff, gbase, voff) do { _Pragma("unroll") for (int _i = 0; _i < 2; ++_i) \
;         __builtin_amdgcn_global_load_lds((const unsigned*)((const char*)(gbase) + (voff)[_i]), (PG8_LAS unsigned*)(lds + (bufoff) + ldsw + _i * 8192), 16, 0, 0); } while (0)
; #define PG8_LDA(dst, b, h) do { _Pragma("unroll") for (int m = 0; m < 4; ++m) _Pragma("unroll") for (int k = 0; k < 2; ++k) dst[m][k] = *(const PG8_LAS bf16x8*)(lds + PG8_SA(b, h) + aoff + m * 2048 + k * 1024); } while (0)
; #define PG8_LDB(dst, b, h) do { _Pragma("unroll") for (int n = 0; n < 2; ++n) _Pragma("unroll") for (int k = 0; k < 2; ++k) dst[n][k] = *(const PG8_LAS bf16x8*)(lds + PG8_SB(b, h) + boff + n * 2048 + k * 1024); } while (0)
; #define PG8_WAIT_V(n) asm volatile("s_waitcnt vmcnt(" #n ")" ::: "memory")
; #define PG8_WAIT_L(n) asm volatile("s_waitcnt lgkmcnt(" #n ")" ::: "memory")
; template <class Epi, class Sched, bool ALIGN_EPI = false, bool SP2 = false, bool ACHUNK = false>
; __device__ __forceinline__ void gemm_phase(PG8_LAS unsigned char* lds, const Gemm g, const Sched& S, const Epi& E) {
;     ...
;         const bool has_next = S.next(ui + 1, nxt);
;         const char* nA = has_next ? (const char*)g.A + (size_t)nxt.pm * tstepA : cA; const char* nB = has_next ? (const char*)g.Bt + (size_t)nxt.pn * tstepB : cB;
;         for (int t = 0; t < nt; t += 2) {
;             const bool last = (t == nt - 2);
;             if constexpr (Epi::HAS_MID) { if (t == Epi::MID_T) E.mid(acc, cur, wr, wc, fr, fq, ShflDev{}); }
;             const char* a1 = cA + (size_t)(t + 1) * kstep;
;             const char* a2 = last ? nA : cA + (size_t)(t + 2) * kstep; const char* b2 = last ? nB : cB + (size_t)(t + 2) * kstep;
;             const char* a3 = a2 + kstep; const char* b3 = b2 + kstep;
;             if (last && has_next) S.a_ready(nxt);
;             if constexpr (SP2) {
;             PG8_LDB(B0, 0, 0); PG8_LDB(B1, 0, 1); PG8_SCHED; PG8_LDA(At, 0, 0); PG8_STAGE(PG8_SA(1, 1), a1 + hstepA, voffA);
;             PG8_WAIT_V(8); PG8_WAIT_L(0); PG8_BAR; PG8_MMA(0, 0, At, B0); PG8_MMA(0, 1, At, B1); PG8_BAR; PG8_SCHED;
;             PG8_LDA(At, 0, 1); PG8_STAGE(PG8_SB(0, 0), b2, voffB); PG8_STAGE(PG8_SB(0, 1), b2 + hstepB, voffB); PG8_STAGE(PG8_SA(0, 0), a2, voffA);
;             PG8_WAIT_V(8); PG8_WAIT_L(0); PG8_BAR; PG8_MMA(1, 0, At, B0); PG8_MMA(1, 1, At, B1); PG8_BAR; PG8_SCHED;
.LBB0_353:
	s_add_i32 s42, s20, 2
	s_add_u32 s43, s18, 0x80
	s_addc_u32 s21, s19, 0
	s_add_i32 s46, 0, 0x10000
	s_cmp_eq_u32 s33, s20
	s_cselect_b32 s21, s13, s21
	s_cselect_b32 s20, s12, s43
	v_add_u32_e32 v153, s46, v143
	s_cselect_b32 s45, s17, s41
	s_cselect_b32 s44, s16, s40
	s_add_i32 s43, 0, 0x14000
	ds_read_b128 v[154:157], v153
	ds_read_b128 v[158:161], v153 offset:1024
	ds_read_b128 v[162:165], v153 offset:2048
	ds_read_b128 v[166:169], v153 offset:3072
	v_add_u32_e32 v153, s43, v143
	ds_read_b128 v[170:173], v153
	ds_read_b128 v[174:177], v153 offset:1024
	ds_read_b128 v[178:181], v153 offset:2048
	ds_read_b128 v[182:185], v153 offset:3072
	v_lshl_add_u64 v[222:223], s[18:19], 0, v[138:139]
	s_add_i32 m0, s25, 0xc000
	ds_read_b128 v[186:189], v152
	ds_read_b128 v[190:193], v152 offset:1024
	ds_read_b128 v[198:201], v152 offset:2048
	ds_read_b128 v[202:205], v152 offset:3072
	ds_read_b128 v[206:209], v152 offset:4096
	ds_read_b128 v[210:213], v152 offset:5120
	ds_read_b128 v[214:217], v152 offset:6144
	ds_read_b128 v[218:221], v152 offset:7168
	global_load_lds_dwordx4 v[222:223], off
	v_lshl_add_u64 v[222:223], s[18:19], 0, v[140:141]
	s_add_i32 m0, s25, 0xe000
	s_nop 0
	global_load_lds_dwordx4 v[222:223], off
	s_waitcnt vmcnt(8)
	s_waitcnt lgkmcnt(0)
	s_barrier
	s_setprio 1
	v_mfma_f32_16x16x32_bf16 v[124:127], v[154:157], v[186:189], v[124:127]
	v_mfma_f32_16x16x32_bf16 v[128:131], v[162:165], v[186:189], v[128:131]
	v_mfma_f32_16x16x32_bf16 v[112:115], v[154:157], v[198:201], v[112:115]
	v_mfma_f32_16x16x32_bf16 v[108:111], v[162:165], v[198:201], v[108:111]
	v_mfma_f32_16x16x32_bf16 v[96:99], v[154:157], v[206:209], v[96:99]
	v_mfma_f32_16x16x32_bf16 v[92:95], v[162:165], v[206:209], v[92:95]
	v_mfma_f32_16x16x32_bf16 v[80:83], v[154:157], v[214:217], v[80:83]
	v_mfma_f32_16x16x32_bf16 v[76:79], v[162:165], v[214:217], v[76:79]
	v_mfma_f32_16x16x32_bf16 v[124:127], v[158:161], v[190:193], v[124:127]
	v_mfma_f32_16x16x32_bf16 v[128:131], v[166:169], v[190:193], v[128:131]
	v_mfma_f32_16x16x32_bf16 v[112:115], v[158:161], v[202:205], v[112:115]
	v_mfma_f32_16x16x32_bf16 v[108:111], v[166:169], v[202:205], v[108:111]
	v_mfma_f32_16x16x32_bf16 v[96:99], v[158:161], v[210:213], v[96:99]
	v_mfma_f32_16x16x32_bf16 v[92:95], v[166:169], v[210:213], v[92:95]
	v_mfma_f32_16x16x32_bf16 v[80:83], v[158:161], v[218:221], v[80:83]
	v_mfma_f32_16x16x32_bf16 v[76:79], v[166:169], v[218:221], v[76:79]
	s_setprio 0
	s_setprio 1
	v_mfma_f32_16x16x32_bf16 v[120:123], v[170:173], v[186:189], v[120:123]
	v_mfma_f32_16x16x32_bf16 v[116:119], v[178:181], v[186:189], v[116:119]
	v_mfma_f32_16x16x32_bf16 v[104:107], v[170:173], v[198:201], v[104:107]
	v_mfma_f32_16x16x32_bf16 v[100:103], v[178:181], v[198:201], v[100:103]
	v_mfma_f32_16x16x32_bf16 v[88:91], v[170:173], v[206:209], v[88:91]
	v_mfma_f32_16x16x32_bf16 v[84:87], v[178:181], v[206:209], v[84:87]
	v_mfma_f32_16x16x32_bf16 v[72:75], v[170:173], v[214:217], v[72:75]
	v_mfma_f32_16x16x32_bf16 v[68:71], v[178:181], v[214:217], v[68:71]
	v_mfma_f32_16x16x32_bf16 v[120:123], v[174:177], v[190:193], v[120:123]
	v_mfma_f32_16x16x32_bf16 v[116:119], v[182:185], v[190:193], v[116:119]
	v_mfma_f32_16x16x32_bf16 v[104:107], v[174:177], v[202:205], v[104:107]
	v_mfma_f32_16x16x32_bf16 v[100:103], v[182:185], v[202:205], v[100:103]
	v_mfma_f32_16x16x32_bf16 v[88:91], v[174:177], v[210:213], v[88:91]
	v_mfma_f32_16x16x32_bf16 v[84:87], v[182:185], v[210:213], v[84:87]
	v_mfma_f32_16x16x32_bf16 v[72:75], v[174:177], v[218:221], v[72:75]
	v_mfma_f32_16x16x32_bf16 v[68:71], v[182:185], v[218:221], v[68:71]
	s_setprio 0
	s_barrier
	s_add_i32 s46, s46, s24
	v_lshl_add_u64 v[222:223], s[44:45], 0, v[2:3]
	s_mov_b32 m0, s46
	ds_read_b128 v[186:189], v152 offset:16384
	ds_read_b128 v[190:193], v152 offset:17408
	ds_read_b128 v[198:201], v152 offset:18432
	ds_read_b128 v[202:205], v152 offset:19456
	ds_read_b128 v[206:209], v152 offset:20480
	ds_read_b128 v[210:213], v152 offset:21504
	ds_read_b128 v[214:217], v152 offset:22528
	ds_read_b128 v[218:221], v152 offset:23552
	global_load_lds_dwordx4 v[222:223], off
	s_add_i32 m0, s46, 0x2000
	v_lshl_add_u64 v[224:225], s[44:45], 0, v[136:137]
	s_add_u32 s44, s44, s0
	s_addc_u32 s45, s45, s1
	s_add_i32 s43, s43, s24
	global_load_lds_dwordx4 v[224:225], off
	v_lshl_add_u64 v[232:233], s[44:45], 0, v[2:3]
	s_mov_b32 m0, s43
	v_lshl_add_u64 v[234:235], s[44:45], 0, v[136:137]
	global_load_lds_dwordx4 v[232:233], off
	s_add_i32 m0, s43, 0x2000
	v_lshl_add_u64 v[236:237], s[20:21], 0, v[132:133]
	global_load_lds_dwordx4 v[234:235], off
	s_mov_b32 m0, s25
	v_lshl_add_u64 v[238:239], s[20:21], 0, v[134:135]
	global_load_lds_dwordx4 v[236:237], off
	s_mov_b32 m0, s26
	s_nop 0
	global_load_lds_dwordx4 v[238:239], off
	s_waitcnt vmcnt(8)
	s_waitcnt lgkmcnt(0)
	s_barrier
; #define PG8_STAGE(bufoff, gbase, voff) do { _Pragma("unroll") for (int _i = 0; _i < 2; ++_i) \
;         __builtin_amdgcn_global_load_lds((const unsigned*)((const char*)(gbase) + (voff)[_i]), (PG8_LAS unsigned*)(lds + (bufoff) + ldsw + _i * 8192), 16, 0, 0); } while (0)
; #define PG8_LDA(dst, b, h) do { _Pragma("unroll") for (int m = 0; m < 4; ++m) _Pragma("unroll") for (int k = 0; k < 2; ++k) dst[m][k] = *(const PG8_LAS bf16x8*)(lds + PG8_SA(b, h) + aoff + m * 2048 + k * 1024); } while (0)
; #define PG8_LDB(dst, b, h) do { _Pragma("unroll") for (int n = 0; n < 2; ++n) _Pragma("unroll") for (int k = 0; k < 2; ++k) dst[n][k] = *(const PG8_LAS bf16x8*)(lds + PG8_SB(b, h) + boff + n * 2048 + k * 1024); } while (0)
; #define PG8_MMA(ai, bj, At, Bt) do { __builtin_amdgcn_s_setprio(1); _Pragma("unroll") for (int m = 0; m < 4; ++m) _Pragma("unroll") for (int n = 0; n < 2; ++n) _Pragma("unroll") for (int k = 0; k < 2; ++k) \
;         acc[ai][bj][m][n] = __builtin_amdgcn_mfma_f32_16x16x32_bf16(Bt[n][k], At[m][k], acc[ai][bj][m][n], 0, 0, 0); __builtin_amdgcn_s_setprio(0); } while (0)
; #define PG8_WAIT_V(n) asm volatile("s_waitcnt vmcnt(" #n ")" ::: "memory")
; #define PG8_WAIT_L(n) asm volatile("s_waitcnt lgkmcnt(" #n ")" ::: "memory")
; #define PG8_BAR __builtin_amdgcn_s_barrier()
; #define PG8_SCHED __builtin_amdgcn_sched_barrier(0)
; template <class Epi, class Sched, bool ALIGN_EPI = false, bool SP2 = false, bool ACHUNK = false>
; __device__ __forceinline__ void gemm_phase(PG8_LAS unsigned char* lds, const Gemm g, const Sched& S, const Epi& E) {
;     ...
;             PG8_WAIT_V(8); PG8_WAIT_L(0); PG8_BAR; PG8_MMA(1, 0, At, B0); PG8_MMA(1, 1, At, B1); PG8_BAR; PG8_SCHED;
;             PG8_LDB(B0, 1, 0); PG8_LDB(B1, 1, 1); PG8_SCHED; PG8_LDA(At, 1, 0); PG8_STAGE(PG8_SA(0, 1), a2 + hstepA, voffA);
;             PG8_WAIT_V(8); PG8_WAIT_L(0); PG8_BAR; PG8_MMA(0, 0, At, B0); PG8_MMA(0, 1, At, B1); PG8_BAR; PG8_SCHED;
	s_setprio 1
	v_mfma_f32_16x16x32_bf16 v[64:67], v[154:157], v[186:189], v[64:67]
	v_mfma_f32_16x16x32_bf16 v[60:63], v[162:165], v[186:189], v[60:63]
	v_mfma_f32_16x16x32_bf16 v[48:51], v[154:157], v[198:201], v[48:51]
	v_mfma_f32_16x16x32_bf16 v[44:47], v[162:165], v[198:201], v[44:47]
	v_mfma_f32_16x16x32_bf16 v[32:35], v[154:157], v[206:209], v[32:35]
	v_mfma_f32_16x16x32_bf16 v[28:31], v[162:165], v[206:209], v[28:31]
	v_mfma_f32_16x16x32_bf16 v[16:19], v[154:157], v[214:217], v[16:19]
	v_mfma_f32_16x16x32_bf16 v[12:15], v[162:165], v[214:217], v[12:15]
	v_mfma_f32_16x16x32_bf16 v[64:67], v[158:161], v[190:193], v[64:67]
	v_mfma_f32_16x16x32_bf16 v[60:63], v[166:169], v[190:193], v[60:63]
	v_mfma_f32_16x16x32_bf16 v[48:51], v[158:161], v[202:205], v[48:51]
	v_mfma_f32_16x16x32_bf16 v[44:47], v[166:169], v[202:205], v[44:47]
	v_mfma_f32_16x16x32_bf16 v[32:35], v[158:161], v[210:213], v[32:35]
	v_mfma_f32_16x16x32_bf16 v[28:31], v[166:169], v[210:213], v[28:31]
	v_mfma_f32_16x16x32_bf16 v[16:19], v[158:161], v[218:221], v[16:19]
	v_mfma_f32_16x16x32_bf16 v[12:15], v[166:169], v[218:221], v[12:15]
	s_setprio 0
	s_setprio 1
	v_mfma_f32_16x16x32_bf16 v[56:59], v[170:173], v[186:189], v[56:59]
	v_mfma_f32_16x16x32_bf16 v[52:55], v[178:181], v[186:189], v[52:55]
	v_mfma_f32_16x16x32_bf16 v[40:43], v[170:173], v[198:201], v[40:43]
	v_mfma_f32_16x16x32_bf16 v[36:39], v[178:181], v[198:201], v[36:39]
	v_mfma_f32_16x16x32_bf16 v[24:27], v[170:173], v[206:209], v[24:27]
	v_mfma_f32_16x16x32_bf16 v[20:23], v[178:181], v[206:209], v[20:23]
	v_mfma_f32_16x16x32_bf16 v[8:11], v[170:173], v[214:217], v[8:11]
	v_mfma_f32_16x16x32_bf16 v[4:7], v[178:181], v[214:217], v[4:7]
	v_mfma_f32_16x16x32_bf16 v[56:59], v[174:177], v[190:193], v[56:59]
	v_mfma_f32_16x16x32_bf16 v[52:55], v[182:185], v[190:193], v[52:55]
	v_mfma_f32_16x16x32_bf16 v[40:43], v[174:177], v[202:205], v[40:43]
	v_mfma_f32_16x16x32_bf16 v[36:39], v[182:185], v[202:205], v[36:39]
	v_mfma_f32_16x16x32_bf16 v[24:27], v[174:177], v[210:213], v[24:27]
	v_mfma_f32_16x16x32_bf16 v[20:23], v[182:185], v[210:213], v[20:23]
	v_mfma_f32_16x16x32_bf16 v[8:11], v[174:177], v[218:221], v[8:11]
	v_mfma_f32_16x16x32_bf16 v[4:7], v[182:185], v[218:221], v[4:7]
	s_setprio 0
	s_barrier
	s_add_i32 s43, 0, 0x18000
	v_add_u32_e32 v153, s43, v143
	s_add_i32 s44, 0, 0x1c000
	ds_read_b128 v[154:157], v153
	ds_read_b128 v[158:161], v153 offset:1024
	ds_read_b128 v[162:165], v153 offset:2048
	ds_read_b128 v[166:169], v153 offset:3072
	v_add_u32_e32 v153, s44, v143
	ds_read_b128 v[170:173], v153
	ds_read_b128 v[174:177], v153 offset:1024
	ds_read_b128 v[178:181], v153 offset:2048
	ds_read_b128 v[182:185], v153 offset:3072
	s_add_u32 s20, s20, s0
	s_addc_u32 s21, s21, s1
	s_mov_b32 m0, s27
	v_lshl_add_u64 v[240:241], s[20:21], 0, v[132:133]
	ds_read_b128 v[186:189], v152 offset:32768
	ds_read_b128 v[190:193], v152 offset:33792
	ds_read_b128 v[198:201], v152 offset:34816
	ds_read_b128 v[202:205], v152 offset:35840
	ds_read_b128 v[206:209], v152 offset:36864
	ds_read_b128 v[210:213], v152 offset:37888
	ds_read_b128 v[214:217], v152 offset:38912
	ds_read_b128 v[218:221], v152 offset:39936
	global_load_lds_dwordx4 v[240:241], off
	v_lshl_add_u64 v[240:241], s[20:21], 0, v[134:135]
	s_mov_b32 m0, s28
	s_nop 0
	global_load_lds_dwordx4 v[240:241], off
	s_waitcnt vmcnt(8)
	s_waitcnt lgkmcnt(0)
	s_barrier
	s_setprio 1
	v_mfma_f32_16x16x32_bf16 v[124:127], v[154:157], v[186:189], v[124:127]
	v_mfma_f32_16x16x32_bf16 v[128:131], v[162:165], v[186:189], v[128:131]
	v_mfma_f32_16x16x32_bf16 v[112:115], v[154:157], v[198:201], v[112:115]
	v_mfma_f32_16x16x32_bf16 v[108:111], v[162:165], v[198:201], v[108:111]
	v_mfma_f32_16x16x32_bf16 v[96:99], v[154:157], v[206:209], v[96:99]
	v_mfma_f32_16x16x32_bf16 v[92:95], v[162:165], v[206:209], v[92:95]
	v_mfma_f32_16x16x32_bf16 v[80:83], v[154:157], v[214:217], v[80:83]
	v_mfma_f32_16x16x32_bf16 v[76:79], v[162:165], v[214:217], v[76:79]
	v_mfma_f32_16x16x32_bf16 v[124:127], v[158:161], v[190:193], v[124:127]
	v_mfma_f32_16x16x32_bf16 v[128:131], v[166:169], v[190:193], v[128:131]
	v_mfma_f32_16x16x32_bf16 v[112:115], v[158:161], v[202:205], v[112:115]
	v_mfma_f32_16x16x32_bf16 v[108:111], v[166:169], v[202:205], v[108:111]
	v_mfma_f32_16x16x32_bf16 v[96:99], v[158:161], v[210:213], v[96:99]
	v_mfma_f32_16x16x32_bf16 v[92:95], v[166:169], v[210:213], v[92:95]
	v_mfma_f32_16x16x32_bf16 v[80:83], v[158:161], v[218:221], v[80:83]
	v_mfma_f32_16x16x32_bf16 v[76:79], v[166:169], v[218:221], v[76:79]
	s_setprio 0
	s_setprio 1
	v_mfma_f32_16x16x32_bf16 v[120:123], v[170:173], v[186:189], v[120:123]
	v_mfma_f32_16x16x32_bf16 v[116:119], v[178:181], v[186:189], v[116:119]
	v_mfma_f32_16x16x32_bf16 v[104:107], v[170:173], v[198:201], v[104:107]
	v_mfma_f32_16x16x32_bf16 v[100:103], v[178:181], v[198:201], v[100:103]
	v_mfma_f32_16x16x32_bf16 v[88:91], v[170:173], v[206:209], v[88:91]
	v_mfma_f32_16x16x32_bf16 v[84:87], v[178:181], v[206:209], v[84:87]
	v_mfma_f32_16x16x32_bf16 v[72:75], v[170:173], v[214:217], v[72:75]
	v_mfma_f32_16x16x32_bf16 v[68:71], v[178:181], v[214:217], v[68:71]
	v_mfma_f32_16x16x32_bf16 v[120:123], v[174:177], v[190:193], v[120:123]
	v_mfma_f32_16x16x32_bf16 v[116:119], v[182:185], v[190:193], v[116:119]
	v_mfma_f32_16x16x32_bf16 v[104:107], v[174:177], v[202:205], v[104:107]
	v_mfma_f32_16x16x32_bf16 v[100:103], v[182:185], v[202:205], v[100:103]
	v_mfma_f32_16x16x32_bf16 v[88:91], v[174:177], v[210:213], v[88:91]
	v_mfma_f32_16x16x32_bf16 v[84:87], v[182:185], v[210:213], v[84:87]
	v_mfma_f32_16x16x32_bf16 v[72:75], v[174:177], v[218:221], v[72:75]
	v_mfma_f32_16x16x32_bf16 v[68:71], v[182:185], v[218:221], v[68:71]
	s_setprio 0
	s_barrier
; #define PG8_STAGE(bufoff, gbase, voff) do { _Pragma("unroll") for (int _i = 0; _i < 2; ++_i) \
;         __builtin_amdgcn_global_load_lds((const unsigned*)((const char*)(gbase) + (voff)[_i]), (PG8_LAS unsigned*)(lds + (bufoff) + ldsw + _i * 8192), 16, 0, 0); } while (0)
; #define PG8_LDA(dst, b, h) do { _Pragma("unroll") for (int m = 0; m < 4; ++m) _Pragma("unroll") for (int k = 0; k < 2; ++k) dst[m][k] = *(const PG8_LAS bf16x8*)(lds + PG8_SA(b, h) + aoff + m * 2048 + k * 1024); } while (0)
; #define PG8_MMA(ai, bj, At, Bt) do { __builtin_amdgcn_s_setprio(1); _Pragma("unroll") for (int m = 0; m < 4; ++m) _Pragma("unroll") for (int n = 0; n < 2; ++n) _Pragma("unroll") for (int k = 0; k < 2; ++k) \
;         acc[ai][bj][m][n] = __builtin_amdgcn_mfma_f32_16x16x32_bf16(Bt[n][k], At[m][k], acc[ai][bj][m][n], 0, 0, 0); __builtin_amdgcn_s_setprio(0); } while (0)
; #define PG8_WAIT_V(n) asm volatile("s_waitcnt vmcnt(" #n ")" ::: "memory")
; #define PG8_WAIT_L(n) asm volatile("s_waitcnt lgkmcnt(" #n ")" ::: "memory")
; #define PG8_BAR __builtin_amdgcn_s_barrier()
; #define PG8_SCHED __builtin_amdgcn_sched_barrier(0)
; template <class Epi, class Sched, bool ALIGN_EPI = false, bool SP2 = false, bool ACHUNK = false>
; __device__ __forceinline__ void gemm_phase(PG8_LAS unsigned char* lds, const Gemm g, const Sched& S, const Epi& E) {
;     ...
;         for (int t = 0; t < nt; t += 2) {
;     ...
;             PG8_LDA(At, 1, 1); PG8_STAGE(PG8_SB(1, 0), b3, voffB); PG8_STAGE(PG8_SB(1, 1), b3 + hstepB, voffB); PG8_STAGE(PG8_SA(1, 0), a3, voffA);
;             PG8_WAIT_V(8); PG8_WAIT_L(0); PG8_BAR; PG8_MMA(1, 0, At, B0); PG8_MMA(1, 1, At, B1); PG8_BAR; PG8_SCHED;
	s_add_i32 s20, s43, s24
	v_lshl_add_u64 v[222:223], v[222:223], 0, s[10:11]
	s_mov_b32 m0, s20
	ds_read_b128 v[186:189], v152 offset:49152
	ds_read_b128 v[190:193], v152 offset:50176
	ds_read_b128 v[198:201], v152 offset:51200
	ds_read_b128 v[202:205], v152 offset:52224
	ds_read_b128 v[206:209], v152 offset:53248
	ds_read_b128 v[210:213], v152 offset:54272
	ds_read_b128 v[214:217], v152 offset:55296
	ds_read_b128 v[218:221], v152 offset:56320
	global_load_lds_dwordx4 v[222:223], off
	v_lshl_add_u64 v[222:223], v[224:225], 0, s[10:11]
	s_add_i32 m0, s20, 0x2000
	s_add_i32 s20, s44, s24
	global_load_lds_dwordx4 v[222:223], off
	v_lshl_add_u64 v[222:223], v[232:233], 0, s[10:11]
	s_mov_b32 m0, s20
	s_nop 0
	global_load_lds_dwordx4 v[222:223], off
	v_lshl_add_u64 v[222:223], v[234:235], 0, s[10:11]
	s_add_i32 m0, s20, 0x2000
	s_nop 0
	global_load_lds_dwordx4 v[222:223], off
	v_lshl_add_u64 v[222:223], v[236:237], 0, s[10:11]
	s_mov_b32 m0, s29
	s_nop 0
	global_load_lds_dwordx4 v[222:223], off
	v_lshl_add_u64 v[222:223], v[238:239], 0, s[10:11]
	s_mov_b32 m0, s30
	s_nop 0
	global_load_lds_dwordx4 v[222:223], off
	s_waitcnt vmcnt(8)
	s_waitcnt lgkmcnt(0)
	s_barrier
	s_setprio 1
	v_mfma_f32_16x16x32_bf16 v[64:67], v[154:157], v[186:189], v[64:67]
	v_mfma_f32_16x16x32_bf16 v[60:63], v[162:165], v[186:189], v[60:63]
	v_mfma_f32_16x16x32_bf16 v[48:51], v[154:157], v[198:201], v[48:51]
	v_mfma_f32_16x16x32_bf16 v[44:47], v[162:165], v[198:201], v[44:47]
	v_mfma_f32_16x16x32_bf16 v[32:35], v[154:157], v[206:209], v[32:35]
	v_mfma_f32_16x16x32_bf16 v[28:31], v[162:165], v[206:209], v[28:31]
	v_mfma_f32_16x16x32_bf16 v[16:19], v[154:157], v[214:217], v[16:19]
	v_mfma_f32_16x16x32_bf16 v[12:15], v[162:165], v[214:217], v[12:15]
	v_mfma_f32_16x16x32_bf16 v[64:67], v[158:161], v[190:193], v[64:67]
	v_mfma_f32_16x16x32_bf16 v[60:63], v[166:169], v[190:193], v[60:63]
	v_mfma_f32_16x16x32_bf16 v[48:51], v[158:161], v[202:205], v[48:51]
	v_mfma_f32_16x16x32_bf16 v[44:47], v[166:169], v[202:205], v[44:47]
	v_mfma_f32_16x16x32_bf16 v[32:35], v[158:161], v[210:213], v[32:35]
	v_mfma_f32_16x16x32_bf16 v[28:31], v[166:169], v[210:213], v[28:31]
	v_mfma_f32_16x16x32_bf16 v[16:19], v[158:161], v[218:221], v[16:19]
	v_mfma_f32_16x16x32_bf16 v[12:15], v[166:169], v[218:221], v[12:15]
	s_setprio 0
	s_setprio 1
	v_mfma_f32_16x16x32_bf16 v[56:59], v[170:173], v[186:189], v[56:59]
	v_mfma_f32_16x16x32_bf16 v[52:55], v[178:181], v[186:189], v[52:55]
	v_mfma_f32_16x16x32_bf16 v[40:43], v[170:173], v[198:201], v[40:43]
	v_mfma_f32_16x16x32_bf16 v[36:39], v[178:181], v[198:201], v[36:39]
	v_mfma_f32_16x16x32_bf16 v[24:27], v[170:173], v[206:209], v[24:27]
	v_mfma_f32_16x16x32_bf16 v[20:23], v[178:181], v[206:209], v[20:23]
	v_mfma_f32_16x16x32_bf16 v[8:11], v[170:173], v[214:217], v[8:11]
	v_mfma_f32_16x16x32_bf16 v[4:7], v[178:181], v[214:217], v[4:7]
	v_mfma_f32_16x16x32_bf16 v[56:59], v[174:177], v[190:193], v[56:59]
	v_mfma_f32_16x16x32_bf16 v[52:55], v[182:185], v[190:193], v[52:55]
	v_mfma_f32_16x16x32_bf16 v[40:43], v[174:177], v[202:205], v[40:43]
	v_mfma_f32_16x16x32_bf16 v[36:39], v[182:185], v[202:205], v[36:39]
	v_mfma_f32_16x16x32_bf16 v[24:27], v[174:177], v[210:213], v[24:27]
	v_mfma_f32_16x16x32_bf16 v[20:23], v[182:185], v[210:213], v[20:23]
	v_mfma_f32_16x16x32_bf16 v[8:11], v[174:177], v[218:221], v[8:11]
	v_mfma_f32_16x16x32_bf16 v[4:7], v[182:185], v[218:221], v[4:7]
	s_setprio 0
	s_barrier
	s_add_u32 s40, s40, 0x100
	s_addc_u32 s41, s41, 0
	s_add_u32 s18, s18, 0x100
	s_addc_u32 s19, s19, 0
	s_cmp_ge_i32 s42, s31
	s_mov_b32 s20, s42
	s_cbranch_scc0 .LBB0_353
	s_branch .LBB0_342

; #define PG8_STAGE(bufoff, gbase, voff) do { _Pragma("unroll") for (int _i = 0; _i < 2; ++_i) \
;         __builtin_amdgcn_global_load_lds((const unsigned*)((const char*)(gbase) + (voff)[_i]), (PG8_LAS unsigned*)(lds + (bufoff) + ldsw + _i * 8192), 16, 0, 0); } while (0)
; #define PG8_LDA(dst, b, h) do { _Pragma("unroll") for (int m = 0; m < 4; ++m) _Pragma("unroll") for (int k = 0; k < 2; ++k) dst[m][k] = *(const PG8_LAS bf16x8*)(lds + PG8_SA(b, h) + aoff + m * 2048 + k * 1024); } while (0)
; #define PG8_LDB(dst, b, h) do { _Pragma("unroll") for (int n = 0; n < 2; ++n) _Pragma("unroll") for (int k = 0; k < 2; ++k) dst[n][k] = *(const PG8_LAS bf16x8*)(lds + PG8_SB(b, h) + boff + n * 2048 + k * 1024); } while (0)
; #define PG8_WAIT_V(n) asm volatile("s_waitcnt vmcnt(" #n ")" ::: "memory")
; #define PG8_WAIT_L(n) asm volatile("s_waitcnt lgkmcnt(" #n ")" ::: "memory")
; template <class Epi, class Sched, bool ALIGN_EPI = false, bool SP2 = false, bool ACHUNK = false>
; __device__ __forceinline__ void gemm_phase(PG8_LAS unsigned char* lds, const Gemm g, const Sched& S, const Epi& E) {
;     ...
;         const bool has_next = S.next(ui + 1, nxt);
;         const char* nA = has_next ? (const char*)g.A + (size_t)nxt.pm * tstepA : cA; const char* nB = has_next ? (const char*)g.Bt + (size_t)nxt.pn * tstepB : cB;
;         for (int t = 0; t < nt; t += 2) {
;             const bool last = (t == nt - 2);
;             if constexpr (Epi::HAS_MID) { if (t == Epi::MID_T) E.mid(acc, cur, wr, wc, fr, fq, ShflDev{}); }
;             const char* a1 = cA + (size_t)(t + 1) * kstep;
;             const char* a2 = last ? nA : cA + (size_t)(t + 2) * kstep; const char* b2 = last ? nB : cB + (size_t)(t + 2) * kstep;
;             const char* a3 = a2 + kstep; const char* b3 = b2 + kstep;
;             if (last && has_next) S.a_ready(nxt);
;             if constexpr (SP2) {
;             PG8_LDB(B0, 0, 0); PG8_LDB(B1, 0, 1); PG8_SCHED; PG8_LDA(At, 0, 0); PG8_STAGE(PG8_SA(1, 1), a1 + hstepA, voffA);
;             PG8_WAIT_V(8); PG8_WAIT_L(0); PG8_BAR; PG8_MMA(0, 0, At, B0); PG8_MMA(0, 1, At, B1); PG8_BAR; PG8_SCHED;
;             PG8_LDA(At, 0, 1); PG8_STAGE(PG8_SB(0, 0), b2, voffB); PG8_STAGE(PG8_SB(0, 1), b2 + hstepB, voffB); PG8_STAGE(PG8_SA(0, 0), a2, voffA);
;             PG8_WAIT_V(8); PG8_WAIT_L(0); PG8_BAR; PG8_MMA(1, 0, At, B0); PG8_MMA(1, 1, At, B1); PG8_BAR; PG8_SCHED;
.LBB0_377:
	s_add_i32 s48, s6, 2
	s_add_u32 s49, s4, 0x80
	s_addc_u32 s7, s5, 0
	s_add_i32 s52, 0, 0x10000
	s_cmp_eq_u32 s27, s6
	s_cselect_b32 s7, s1, s7
	s_cselect_b32 s6, s0, s49
	v_add_u32_e32 v2, s52, v175
	s_cselect_b32 s51, s43, s9
	s_cselect_b32 s50, s42, s8
	s_add_i32 s49, 0, 0x14000
	s_waitcnt lgkmcnt(0)
	ds_read_b128 v[146:149], v2
	ds_read_b128 v[150:153], v2 offset:1024
	ds_read_b128 v[154:157], v2 offset:2048
	ds_read_b128 v[158:161], v2 offset:3072
	v_add_u32_e32 v2, s49, v175
	ds_read_b128 v[162:165], v2
	ds_read_b128 v[166:169], v2 offset:1024
	ds_read_b128 v[170:173], v2 offset:2048
	ds_read_b128 v[180:183], v2 offset:3072
	v_lshl_add_u64 v[192:193], s[4:5], 0, v[142:143]
	s_add_i32 m0, s20, 0xc000
	ds_read_b128 v[184:187], v179
	ds_read_b128 v[188:191], v179 offset:1024
	ds_read_b128 v[198:201], v179 offset:2048
	ds_read_b128 v[202:205], v179 offset:3072
	ds_read_b128 v[206:209], v179 offset:4096
	ds_read_b128 v[210:213], v179 offset:5120
	ds_read_b128 v[214:217], v179 offset:6144
	ds_read_b128 v[218:221], v179 offset:7168
	global_load_lds_dwordx4 v[192:193], off
	v_lshl_add_u64 v[192:193], s[4:5], 0, v[144:145]
	s_add_i32 m0, s20, 0xe000
	s_nop 0
	global_load_lds_dwordx4 v[192:193], off
	s_waitcnt vmcnt(8)
	s_waitcnt lgkmcnt(0)
	s_barrier
	s_setprio 1
	v_mfma_f32_16x16x32_bf16 v[124:127], v[146:149], v[184:187], v[124:127]
	v_mfma_f32_16x16x32_bf16 v[116:119], v[154:157], v[184:187], v[116:119]
	v_mfma_f32_16x16x32_bf16 v[108:111], v[146:149], v[198:201], v[108:111]
	v_mfma_f32_16x16x32_bf16 v[100:103], v[154:157], v[198:201], v[100:103]
	v_mfma_f32_16x16x32_bf16 v[92:95], v[146:149], v[206:209], v[92:95]
	v_mfma_f32_16x16x32_bf16 v[84:87], v[154:157], v[206:209], v[84:87]
	v_mfma_f32_16x16x32_bf16 v[76:79], v[146:149], v[214:217], v[76:79]
	v_mfma_f32_16x16x32_bf16 v[68:71], v[154:157], v[214:217], v[68:71]
	v_mfma_f32_16x16x32_bf16 v[124:127], v[150:153], v[188:191], v[124:127]
	v_mfma_f32_16x16x32_bf16 v[116:119], v[158:161], v[188:191], v[116:119]
	v_mfma_f32_16x16x32_bf16 v[108:111], v[150:153], v[202:205], v[108:111]
	v_mfma_f32_16x16x32_bf16 v[100:103], v[158:161], v[202:205], v[100:103]
	v_mfma_f32_16x16x32_bf16 v[92:95], v[150:153], v[210:213], v[92:95]
	v_mfma_f32_16x16x32_bf16 v[84:87], v[158:161], v[210:213], v[84:87]
	v_mfma_f32_16x16x32_bf16 v[76:79], v[150:153], v[218:221], v[76:79]
	v_mfma_f32_16x16x32_bf16 v[68:71], v[158:161], v[218:221], v[68:71]
	s_setprio 0
	s_setprio 1
	v_mfma_f32_16x16x32_bf16 v[128:131], v[162:165], v[184:187], v[128:131]
	v_mfma_f32_16x16x32_bf16 v[120:123], v[170:173], v[184:187], v[120:123]
	v_mfma_f32_16x16x32_bf16 v[112:115], v[162:165], v[198:201], v[112:115]
	v_mfma_f32_16x16x32_bf16 v[104:107], v[170:173], v[198:201], v[104:107]
	v_mfma_f32_16x16x32_bf16 v[96:99], v[162:165], v[206:209], v[96:99]
	v_mfma_f32_16x16x32_bf16 v[88:91], v[170:173], v[206:209], v[88:91]
	v_mfma_f32_16x16x32_bf16 v[80:83], v[162:165], v[214:217], v[80:83]
	v_mfma_f32_16x16x32_bf16 v[72:75], v[170:173], v[214:217], v[72:75]
	v_mfma_f32_16x16x32_bf16 v[128:131], v[166:169], v[188:191], v[128:131]
	v_mfma_f32_16x16x32_bf16 v[120:123], v[180:183], v[188:191], v[120:123]
	v_mfma_f32_16x16x32_bf16 v[112:115], v[166:169], v[202:205], v[112:115]
	v_mfma_f32_16x16x32_bf16 v[104:107], v[180:183], v[202:205], v[104:107]
	v_mfma_f32_16x16x32_bf16 v[96:99], v[166:169], v[210:213], v[96:99]
	v_mfma_f32_16x16x32_bf16 v[88:91], v[180:183], v[210:213], v[88:91]
	v_mfma_f32_16x16x32_bf16 v[80:83], v[166:169], v[218:221], v[80:83]
	v_mfma_f32_16x16x32_bf16 v[72:75], v[180:183], v[218:221], v[72:75]
	s_setprio 0
	s_barrier
	s_add_i32 s52, s52, s13
	v_lshl_add_u64 v[192:193], s[50:51], 0, v[134:135]
	s_mov_b32 m0, s52
	ds_read_b128 v[184:187], v179 offset:16384
	ds_read_b128 v[188:191], v179 offset:17408
	ds_read_b128 v[198:201], v179 offset:18432
	ds_read_b128 v[202:205], v179 offset:19456
	ds_read_b128 v[206:209], v179 offset:20480
	ds_read_b128 v[210:213], v179 offset:21504
	ds_read_b128 v[214:217], v179 offset:22528
	ds_read_b128 v[218:221], v179 offset:23552
	global_load_lds_dwordx4 v[192:193], off
	s_add_i32 m0, s52, 0x2000
	v_lshl_add_u64 v[222:223], s[50:51], 0, v[138:139]
	s_add_u32 s50, s50, s18
	s_addc_u32 s51, s51, s19
	s_add_i32 s49, s49, s13
	global_load_lds_dwordx4 v[222:223], off
	v_lshl_add_u64 v[224:225], s[50:51], 0, v[134:135]
	s_mov_b32 m0, s49
	v_lshl_add_u64 v[232:233], s[50:51], 0, v[138:139]
	global_load_lds_dwordx4 v[224:225], off
	s_add_i32 m0, s49, 0x2000
	v_lshl_add_u64 v[234:235], s[6:7], 0, v[132:133]
	global_load_lds_dwordx4 v[232:233], off
	s_mov_b32 m0, s20
	v_lshl_add_u64 v[236:237], s[6:7], 0, v[136:137]
	global_load_lds_dwordx4 v[234:235], off
	s_mov_b32 m0, s21
	s_nop 0
	global_load_lds_dwordx4 v[236:237], off
	s_waitcnt vmcnt(8)
	s_waitcnt lgkmcnt(0)
	s_barrier
; #define PG8_STAGE(bufoff, gbase, voff) do { _Pragma("unroll") for (int _i = 0; _i < 2; ++_i) \
;         __builtin_amdgcn_global_load_lds((const unsigned*)((const char*)(gbase) + (voff)[_i]), (PG8_LAS unsigned*)(lds + (bufoff) + ldsw + _i * 8192), 16, 0, 0); } while (0)
; #define PG8_LDA(dst, b, h) do { _Pragma("unroll") for (int m = 0; m < 4; ++m) _Pragma("unroll") for (int k = 0; k < 2; ++k) dst[m][k] = *(const PG8_LAS bf16x8*)(lds + PG8_SA(b, h) + aoff + m * 2048 + k * 1024); } while (0)
; #define PG8_LDB(dst, b, h) do { _Pragma("unroll") for (int n = 0; n < 2; ++n) _Pragma("unroll") for (int k = 0; k < 2; ++k) dst[n][k] = *(const PG8_LAS bf16x8*)(lds + PG8_SB(b, h) + boff + n * 2048 + k * 1024); } while (0)
; #define PG8_MMA(ai, bj, At, Bt) do { __builtin_amdgcn_s_setprio(1); _Pragma("unroll") for (int m = 0; m < 4; ++m) _Pragma("unroll") for (int n = 0; n < 2; ++n) _Pragma("unroll") for (int k = 0; k < 2; ++k) \
;         acc[ai][bj][m][n] = __builtin_amdgcn_mfma_f32_16x16x32_bf16(Bt[n][k], At[m][k], acc[ai][bj][m][n], 0, 0, 0); __builtin_amdgcn_s_setprio(0); } while (0)
; #define PG8_WAIT_V(n) asm volatile("s_waitcnt vmcnt(" #n ")" ::: "memory")
; #define PG8_WAIT_L(n) asm volatile("s_waitcnt lgkmcnt(" #n ")" ::: "memory")
; #define PG8_BAR __builtin_amdgcn_s_barrier()
; #define PG8_SCHED __builtin_amdgcn_sched_barrier(0)
; template <class Epi, class Sched, bool ALIGN_EPI = false, bool SP2 = false, bool ACHUNK = false>
; __device__ __forceinline__ void gemm_phase(PG8_LAS unsigned char* lds, const Gemm g, const Sched& S, const Epi& E) {
;     ...
;             PG8_WAIT_V(8); PG8_WAIT_L(0); PG8_BAR; PG8_MMA(1, 0, At, B0); PG8_MMA(1, 1, At, B1); PG8_BAR; PG8_SCHED;
;             PG8_LDB(B0, 1, 0); PG8_LDB(B1, 1, 1); PG8_SCHED; PG8_LDA(At, 1, 0); PG8_STAGE(PG8_SA(0, 1), a2 + hstepA, voffA);
;             PG8_WAIT_V(8); PG8_WAIT_L(0); PG8_BAR; PG8_MMA(0, 0, At, B0); PG8_MMA(0, 1, At, B1); PG8_BAR; PG8_SCHED;
	s_setprio 1
	v_mfma_f32_16x16x32_bf16 v[60:63], v[146:149], v[184:187], v[60:63]
	v_mfma_f32_16x16x32_bf16 v[52:55], v[154:157], v[184:187], v[52:55]
	v_mfma_f32_16x16x32_bf16 v[44:47], v[146:149], v[198:201], v[44:47]
	v_mfma_f32_16x16x32_bf16 v[36:39], v[154:157], v[198:201], v[36:39]
	v_mfma_f32_16x16x32_bf16 v[28:31], v[146:149], v[206:209], v[28:31]
	v_mfma_f32_16x16x32_bf16 v[20:23], v[154:157], v[206:209], v[20:23]
	v_mfma_f32_16x16x32_bf16 v[12:15], v[146:149], v[214:217], v[12:15]
	v_mfma_f32_16x16x32_bf16 v[4:7], v[154:157], v[214:217], v[4:7]
	v_mfma_f32_16x16x32_bf16 v[60:63], v[150:153], v[188:191], v[60:63]
	v_mfma_f32_16x16x32_bf16 v[52:55], v[158:161], v[188:191], v[52:55]
	v_mfma_f32_16x16x32_bf16 v[44:47], v[150:153], v[202:205], v[44:47]
	v_mfma_f32_16x16x32_bf16 v[36:39], v[158:161], v[202:205], v[36:39]
	v_mfma_f32_16x16x32_bf16 v[28:31], v[150:153], v[210:213], v[28:31]
	v_mfma_f32_16x16x32_bf16 v[20:23], v[158:161], v[210:213], v[20:23]
	v_mfma_f32_16x16x32_bf16 v[12:15], v[150:153], v[218:221], v[12:15]
	v_mfma_f32_16x16x32_bf16 v[4:7], v[158:161], v[218:221], v[4:7]
	s_setprio 0
	s_setprio 1
	v_mfma_f32_16x16x32_bf16 v[64:67], v[162:165], v[184:187], v[64:67]
	v_mfma_f32_16x16x32_bf16 v[56:59], v[170:173], v[184:187], v[56:59]
	v_mfma_f32_16x16x32_bf16 v[48:51], v[162:165], v[198:201], v[48:51]
	v_mfma_f32_16x16x32_bf16 v[40:43], v[170:173], v[198:201], v[40:43]
	v_mfma_f32_16x16x32_bf16 v[32:35], v[162:165], v[206:209], v[32:35]
	v_mfma_f32_16x16x32_bf16 v[24:27], v[170:173], v[206:209], v[24:27]
	v_mfma_f32_16x16x32_bf16 v[16:19], v[162:165], v[214:217], v[16:19]
	v_mfma_f32_16x16x32_bf16 v[8:11], v[170:173], v[214:217], v[8:11]
	v_mfma_f32_16x16x32_bf16 v[64:67], v[166:169], v[188:191], v[64:67]
	v_mfma_f32_16x16x32_bf16 v[56:59], v[180:183], v[188:191], v[56:59]
	v_mfma_f32_16x16x32_bf16 v[48:51], v[166:169], v[202:205], v[48:51]
	v_mfma_f32_16x16x32_bf16 v[40:43], v[180:183], v[202:205], v[40:43]
	v_mfma_f32_16x16x32_bf16 v[32:35], v[166:169], v[210:213], v[32:35]
	v_mfma_f32_16x16x32_bf16 v[24:27], v[180:183], v[210:213], v[24:27]
	v_mfma_f32_16x16x32_bf16 v[16:19], v[166:169], v[218:221], v[16:19]
	v_mfma_f32_16x16x32_bf16 v[8:11], v[180:183], v[218:221], v[8:11]
	s_setprio 0
	s_barrier
	s_add_i32 s49, 0, 0x18000
	v_add_u32_e32 v2, s49, v175
	s_add_i32 s50, 0, 0x1c000
	ds_read_b128 v[146:149], v2
	ds_read_b128 v[150:153], v2 offset:1024
	ds_read_b128 v[154:157], v2 offset:2048
	ds_read_b128 v[158:161], v2 offset:3072
	v_add_u32_e32 v2, s50, v175
	ds_read_b128 v[162:165], v2
	ds_read_b128 v[166:169], v2 offset:1024
	ds_read_b128 v[170:173], v2 offset:2048
	ds_read_b128 v[180:183], v2 offset:3072
	s_add_u32 s6, s6, s18
	s_addc_u32 s7, s7, s19
	s_mov_b32 m0, s22
	v_lshl_add_u64 v[238:239], s[6:7], 0, v[132:133]
	ds_read_b128 v[184:187], v179 offset:32768
	ds_read_b128 v[188:191], v179 offset:33792
	ds_read_b128 v[198:201], v179 offset:34816
	ds_read_b128 v[202:205], v179 offset:35840
	ds_read_b128 v[206:209], v179 offset:36864
	ds_read_b128 v[210:213], v179 offset:37888
	ds_read_b128 v[214:217], v179 offset:38912
	ds_read_b128 v[218:221], v179 offset:39936
	global_load_lds_dwordx4 v[238:239], off
	v_lshl_add_u64 v[238:239], s[6:7], 0, v[136:137]
	s_mov_b32 m0, s23
	s_nop 0
	global_load_lds_dwordx4 v[238:239], off
	s_waitcnt vmcnt(8)
	s_waitcnt lgkmcnt(0)
	s_barrier
	s_setprio 1
	v_mfma_f32_16x16x32_bf16 v[124:127], v[146:149], v[184:187], v[124:127]
	v_mfma_f32_16x16x32_bf16 v[116:119], v[154:157], v[184:187], v[116:119]
	v_mfma_f32_16x16x32_bf16 v[108:111], v[146:149], v[198:201], v[108:111]
	v_mfma_f32_16x16x32_bf16 v[100:103], v[154:157], v[198:201], v[100:103]
	v_mfma_f32_16x16x32_bf16 v[92:95], v[146:149], v[206:209], v[92:95]
	v_mfma_f32_16x16x32_bf16 v[84:87], v[154:157], v[206:209], v[84:87]
	v_mfma_f32_16x16x32_bf16 v[76:79], v[146:149], v[214:217], v[76:79]
	v_mfma_f32_16x16x32_bf16 v[68:71], v[154:157], v[214:217], v[68:71]
	v_mfma_f32_16x16x32_bf16 v[124:127], v[150:153], v[188:191], v[124:127]
	v_mfma_f32_16x16x32_bf16 v[116:119], v[158:161], v[188:191], v[116:119]
	v_mfma_f32_16x16x32_bf16 v[108:111], v[150:153], v[202:205], v[108:111]
	v_mfma_f32_16x16x32_bf16 v[100:103], v[158:161], v[202:205], v[100:103]
	v_mfma_f32_16x16x32_bf16 v[92:95], v[150:153], v[210:213], v[92:95]
	v_mfma_f32_16x16x32_bf16 v[84:87], v[158:161], v[210:213], v[84:87]
	v_mfma_f32_16x16x32_bf16 v[76:79], v[150:153], v[218:221], v[76:79]
	v_mfma_f32_16x16x32_bf16 v[68:71], v[158:161], v[218:221], v[68:71]
	s_setprio 0
	s_setprio 1
	v_mfma_f32_16x16x32_bf16 v[128:131], v[162:165], v[184:187], v[128:131]
	v_mfma_f32_16x16x32_bf16 v[120:123], v[170:173], v[184:187], v[120:123]
	v_mfma_f32_16x16x32_bf16 v[112:115], v[162:165], v[198:201], v[112:115]
	v_mfma_f32_16x16x32_bf16 v[104:107], v[170:173], v[198:201], v[104:107]
	v_mfma_f32_16x16x32_bf16 v[96:99], v[162:165], v[206:209], v[96:99]
	v_mfma_f32_16x16x32_bf16 v[88:91], v[170:173], v[206:209], v[88:91]
	v_mfma_f32_16x16x32_bf16 v[80:83], v[162:165], v[214:217], v[80:83]
	v_mfma_f32_16x16x32_bf16 v[72:75], v[170:173], v[214:217], v[72:75]
	v_mfma_f32_16x16x32_bf16 v[128:131], v[166:169], v[188:191], v[128:131]
	v_mfma_f32_16x16x32_bf16 v[120:123], v[180:183], v[188:191], v[120:123]
	v_mfma_f32_16x16x32_bf16 v[112:115], v[166:169], v[202:205], v[112:115]
	v_mfma_f32_16x16x32_bf16 v[104:107], v[180:183], v[202:205], v[104:107]
	v_mfma_f32_16x16x32_bf16 v[96:99], v[166:169], v[210:213], v[96:99]
	v_mfma_f32_16x16x32_bf16 v[88:91], v[180:183], v[210:213], v[88:91]
	v_mfma_f32_16x16x32_bf16 v[80:83], v[166:169], v[218:221], v[80:83]
	v_mfma_f32_16x16x32_bf16 v[72:75], v[180:183], v[218:221], v[72:75]
	s_setprio 0
	s_barrier
; #define PG8_STAGE(bufoff, gbase, voff) do { _Pragma("unroll") for (int _i = 0; _i < 2; ++_i) \
;         __builtin_amdgcn_global_load_lds((const unsigned*)((const char*)(gbase) + (voff)[_i]), (PG8_LAS unsigned*)(lds + (bufoff) + ldsw + _i * 8192), 16, 0, 0); } while (0)
; #define PG8_LDA(dst, b, h) do { _Pragma("unroll") for (int m = 0; m < 4; ++m) _Pragma("unroll") for (int k = 0; k < 2; ++k) dst[m][k] = *(const PG8_LAS bf16x8*)(lds + PG8_SA(b, h) + aoff + m * 2048 + k * 1024); } while (0)
; #define PG8_MMA(ai, bj, At, Bt) do { __builtin_amdgcn_s_setprio(1); _Pragma("unroll") for (int m = 0; m < 4; ++m) _Pragma("unroll") for (int n = 0; n < 2; ++n) _Pragma("unroll") for (int k = 0; k < 2; ++k) \
;         acc[ai][bj][m][n] = __builtin_amdgcn_mfma_f32_16x16x32_bf16(Bt[n][k], At[m][k], acc[ai][bj][m][n], 0, 0, 0); __builtin_amdgcn_s_setprio(0); } while (0)
; #define PG8_WAIT_V(n) asm volatile("s_waitcnt vmcnt(" #n ")" ::: "memory")
; #define PG8_WAIT_L(n) asm volatile("s_waitcnt lgkmcnt(" #n ")" ::: "memory")
; #define PG8_BAR __builtin_amdgcn_s_barrier()
; #define PG8_SCHED __builtin_amdgcn_sched_barrier(0)
; template <class Epi, class Sched, bool ALIGN_EPI = false, bool SP2 = false, bool ACHUNK = false>
; __device__ __forceinline__ void gemm_phase(PG8_LAS unsigned char* lds, const Gemm g, const Sched& S, const Epi& E) {
;     ...
;         for (int t = 0; t < nt; t += 2) {
;     ...
;             PG8_LDA(At, 1, 1); PG8_STAGE(PG8_SB(1, 0), b3, voffB); PG8_STAGE(PG8_SB(1, 1), b3 + hstepB, voffB); PG8_STAGE(PG8_SA(1, 0), a3, voffA);
;             PG8_WAIT_V(8); PG8_WAIT_L(0); PG8_BAR; PG8_MMA(1, 0, At, B0); PG8_MMA(1, 1, At, B1); PG8_BAR; PG8_SCHED;
	s_add_i32 s6, s49, s13
	v_lshl_add_u64 v[192:193], v[192:193], 0, s[10:11]
	s_mov_b32 m0, s6
	ds_read_b128 v[184:187], v179 offset:49152
	ds_read_b128 v[188:191], v179 offset:50176
	ds_read_b128 v[198:201], v179 offset:51200
	ds_read_b128 v[202:205], v179 offset:52224
	ds_read_b128 v[206:209], v179 offset:53248
	ds_read_b128 v[210:213], v179 offset:54272
	ds_read_b128 v[214:217], v179 offset:55296
	ds_read_b128 v[218:221], v179 offset:56320
	global_load_lds_dwordx4 v[192:193], off
	v_lshl_add_u64 v[192:193], v[222:223], 0, s[10:11]
	s_add_i32 m0, s6, 0x2000
	s_add_i32 s6, s50, s13
	global_load_lds_dwordx4 v[192:193], off
	v_lshl_add_u64 v[192:193], v[224:225], 0, s[10:11]
	s_mov_b32 m0, s6
	s_nop 0
	global_load_lds_dwordx4 v[192:193], off
	v_lshl_add_u64 v[192:193], v[232:233], 0, s[10:11]
	s_add_i32 m0, s6, 0x2000
	s_nop 0
	global_load_lds_dwordx4 v[192:193], off
	v_lshl_add_u64 v[192:193], v[234:235], 0, s[10:11]
	s_mov_b32 m0, s25
	s_nop 0
	global_load_lds_dwordx4 v[192:193], off
	v_lshl_add_u64 v[192:193], v[236:237], 0, s[10:11]
	s_mov_b32 m0, s26
	s_nop 0
	global_load_lds_dwordx4 v[192:193], off
	s_waitcnt vmcnt(8)
	s_waitcnt lgkmcnt(0)
	s_barrier
	s_setprio 1
	v_mfma_f32_16x16x32_bf16 v[60:63], v[146:149], v[184:187], v[60:63]
	v_mfma_f32_16x16x32_bf16 v[52:55], v[154:157], v[184:187], v[52:55]
	v_mfma_f32_16x16x32_bf16 v[44:47], v[146:149], v[198:201], v[44:47]
	v_mfma_f32_16x16x32_bf16 v[36:39], v[154:157], v[198:201], v[36:39]
	v_mfma_f32_16x16x32_bf16 v[28:31], v[146:149], v[206:209], v[28:31]
	v_mfma_f32_16x16x32_bf16 v[20:23], v[154:157], v[206:209], v[20:23]
	v_mfma_f32_16x16x32_bf16 v[12:15], v[146:149], v[214:217], v[12:15]
	v_mfma_f32_16x16x32_bf16 v[4:7], v[154:157], v[214:217], v[4:7]
	v_mfma_f32_16x16x32_bf16 v[60:63], v[150:153], v[188:191], v[60:63]
	v_mfma_f32_16x16x32_bf16 v[52:55], v[158:161], v[188:191], v[52:55]
	v_mfma_f32_16x16x32_bf16 v[44:47], v[150:153], v[202:205], v[44:47]
	v_mfma_f32_16x16x32_bf16 v[36:39], v[158:161], v[202:205], v[36:39]
	v_mfma_f32_16x16x32_bf16 v[28:31], v[150:153], v[210:213], v[28:31]
	v_mfma_f32_16x16x32_bf16 v[20:23], v[158:161], v[210:213], v[20:23]
	v_mfma_f32_16x16x32_bf16 v[12:15], v[150:153], v[218:221], v[12:15]
	v_mfma_f32_16x16x32_bf16 v[4:7], v[158:161], v[218:221], v[4:7]
	s_setprio 0
	s_setprio 1
	v_mfma_f32_16x16x32_bf16 v[64:67], v[162:165], v[184:187], v[64:67]
	v_mfma_f32_16x16x32_bf16 v[56:59], v[170:173], v[184:187], v[56:59]
	v_mfma_f32_16x16x32_bf16 v[48:51], v[162:165], v[198:201], v[48:51]
	v_mfma_f32_16x16x32_bf16 v[40:43], v[170:173], v[198:201], v[40:43]
	v_mfma_f32_16x16x32_bf16 v[32:35], v[162:165], v[206:209], v[32:35]
	v_mfma_f32_16x16x32_bf16 v[24:27], v[170:173], v[206:209], v[24:27]
	v_mfma_f32_16x16x32_bf16 v[16:19], v[162:165], v[214:217], v[16:19]
	v_mfma_f32_16x16x32_bf16 v[8:11], v[170:173], v[214:217], v[8:11]
	v_mfma_f32_16x16x32_bf16 v[64:67], v[166:169], v[188:191], v[64:67]
	v_mfma_f32_16x16x32_bf16 v[56:59], v[180:183], v[188:191], v[56:59]
	v_mfma_f32_16x16x32_bf16 v[48:51], v[166:169], v[202:205], v[48:51]
	v_mfma_f32_16x16x32_bf16 v[40:43], v[180:183], v[202:205], v[40:43]
	v_mfma_f32_16x16x32_bf16 v[32:35], v[166:169], v[210:213], v[32:35]
	v_mfma_f32_16x16x32_bf16 v[24:27], v[180:183], v[210:213], v[24:27]
	v_mfma_f32_16x16x32_bf16 v[16:19], v[166:169], v[218:221], v[16:19]
	v_mfma_f32_16x16x32_bf16 v[8:11], v[180:183], v[218:221], v[8:11]
	s_setprio 0
	s_barrier
	s_add_u32 s4, s4, 0x100
	s_addc_u32 s5, s5, 0
	s_add_u32 s8, s8, 0x100
	s_addc_u32 s9, s9, 0
	s_cmp_ge_i32 s48, s24
	s_mov_b32 s6, s48
	s_cbranch_scc0 .LBB0_377
	v_readlane_b32 s52, v254, 27
	v_readlane_b32 s53, v254, 28
	s_mov_b32 s50, s94

; #define PG8_STAGE(bufoff, gbase, voff) do { _Pragma("unroll") for (int _i = 0; _i < 2; ++_i) \
;         __builtin_amdgcn_global_load_lds((const unsigned*)((const char*)(gbase) + (voff)[_i]), (PG8_LAS unsigned*)(lds + (bufoff) + ldsw + _i * 8192), 16, 0, 0); } while (0)
; #define PG8_LDA(dst, b, h) do { _Pragma("unroll") for (int m = 0; m < 4; ++m) _Pragma("unroll") for (int k = 0; k < 2; ++k) dst[m][k] = *(const PG8_LAS bf16x8*)(lds + PG8_SA(b, h) + aoff + m * 2048 + k * 1024); } while (0)
; #define PG8_LDB(dst, b, h) do { _Pragma("unroll") for (int n = 0; n < 2; ++n) _Pragma("unroll") for (int k = 0; k < 2; ++k) dst[n][k] = *(const PG8_LAS bf16x8*)(lds + PG8_SB(b, h) + boff + n * 2048 + k * 1024); } while (0)
; #define PG8_MMA(ai, bj, At, Bt) do { __builtin_amdgcn_s_setprio(1); _Pragma("unroll") for (int m = 0; m < 4; ++m) _Pragma("unroll") for (int n = 0; n < 2; ++n) _Pragma("unroll") for (int k = 0; k < 2; ++k) \
;         acc[ai][bj][m][n] = __builtin_amdgcn_mfma_f32_16x16x32_bf16(Bt[n][k], At[m][k], acc[ai][bj][m][n], 0, 0, 0); __builtin_amdgcn_s_setprio(0); } while (0)
; #define PG8_WAIT_V(n) asm volatile("s_waitcnt vmcnt(" #n ")" ::: "memory")
; #define PG8_WAIT_L(n) asm volatile("s_waitcnt lgkmcnt(" #n ")" ::: "memory")
; #define PG8_BAR __builtin_amdgcn_s_barrier()
; #define PG8_SCHED __builtin_amdgcn_sched_barrier(0)
; template <class Epi, class Sched, bool ALIGN_EPI = false, bool SP2 = false, bool ACHUNK = false>
; __device__ __forceinline__ void gemm_phase(PG8_LAS unsigned char* lds, const Gemm g, const Sched& S, const Epi& E) {
;     ...
;             PG8_LDB(B0, 0, 0); PG8_LDB(B1, 0, 1); PG8_SCHED; PG8_LDA(At, 0, 0); PG8_STAGE(PG8_SA(1, 1), a1 + hstepA, voffA);
;             PG8_WAIT_V(8); PG8_WAIT_L(0); PG8_BAR; PG8_MMA(0, 0, At, B0); PG8_MMA(0, 1, At, B1); PG8_BAR; PG8_SCHED;
;             PG8_LDA(At, 0, 1); PG8_STAGE(PG8_SB(0, 0), b2, voffB); PG8_STAGE(PG8_SB(0, 1), b2 + hstepB, voffB); PG8_STAGE(PG8_SA(0, 0), a2, voffA);
;             PG8_WAIT_V(8); PG8_WAIT_L(0); PG8_BAR; PG8_MMA(1, 0, At, B0); PG8_MMA(1, 1, At, B1); PG8_BAR; PG8_SCHED;
.Lnl_pl:
	s_add_i32 s9, 0, 0x14000
	v_add_u32_e32 v144, s15, v221
	v_add_u32_e32 v160, s9, v221
	ds_read_b128 v[132:135], v144
	ds_read_b128 v[136:139], v144 offset:1024
	ds_read_b128 v[140:143], v144 offset:2048
	ds_read_b128 v[144:147], v144 offset:3072
	ds_read_b128 v[148:151], v160
	ds_read_b128 v[152:155], v160 offset:1024
	ds_read_b128 v[156:159], v160 offset:2048
	ds_read_b128 v[160:163], v160 offset:3072
	v_lshl_add_u64 v[214:215], s[0:1], 0, v[174:175]
	s_add_i32 m0, s27, 0xc000
	ds_read_b128 v[178:181], v223
	ds_read_b128 v[182:185], v223 offset:1024
	ds_read_b128 v[186:189], v223 offset:2048
	ds_read_b128 v[190:193], v223 offset:3072
	ds_read_b128 v[198:201], v223 offset:4096
	ds_read_b128 v[202:205], v223 offset:5120
	ds_read_b128 v[206:209], v223 offset:6144
	ds_read_b128 v[210:213], v223 offset:7168
	global_load_lds_dwordx4 v[214:215], off
	v_lshl_add_u64 v[214:215], s[0:1], 0, v[176:177]
	s_add_i32 m0, s27, 0xe000
	s_nop 0
	global_load_lds_dwordx4 v[214:215], off
	s_waitcnt vmcnt(8)
	s_waitcnt lgkmcnt(0)
	s_barrier
	s_setprio 1
	v_mfma_f32_16x16x32_bf16 v[128:131], v[132:135], v[178:181], v[128:131]
	v_mfma_f32_16x16x32_bf16 v[124:127], v[140:143], v[178:181], v[124:127]
	v_mfma_f32_16x16x32_bf16 v[112:115], v[132:135], v[186:189], v[112:115]
	v_mfma_f32_16x16x32_bf16 v[108:111], v[140:143], v[186:189], v[108:111]
	v_mfma_f32_16x16x32_bf16 v[96:99], v[132:135], v[198:201], v[96:99]
	v_mfma_f32_16x16x32_bf16 v[92:95], v[140:143], v[198:201], v[92:95]
	v_mfma_f32_16x16x32_bf16 v[80:83], v[132:135], v[206:209], v[80:83]
	v_mfma_f32_16x16x32_bf16 v[76:79], v[140:143], v[206:209], v[76:79]
	v_mfma_f32_16x16x32_bf16 v[128:131], v[136:139], v[182:185], v[128:131]
	v_mfma_f32_16x16x32_bf16 v[124:127], v[144:147], v[182:185], v[124:127]
	v_mfma_f32_16x16x32_bf16 v[112:115], v[136:139], v[190:193], v[112:115]
	v_mfma_f32_16x16x32_bf16 v[108:111], v[144:147], v[190:193], v[108:111]
	v_mfma_f32_16x16x32_bf16 v[96:99], v[136:139], v[202:205], v[96:99]
	v_mfma_f32_16x16x32_bf16 v[92:95], v[144:147], v[202:205], v[92:95]
	v_mfma_f32_16x16x32_bf16 v[80:83], v[136:139], v[210:213], v[80:83]
	v_mfma_f32_16x16x32_bf16 v[76:79], v[144:147], v[210:213], v[76:79]
	s_setprio 0
	s_setprio 1
	v_mfma_f32_16x16x32_bf16 v[120:123], v[148:151], v[178:181], v[120:123]
	v_mfma_f32_16x16x32_bf16 v[116:119], v[156:159], v[178:181], v[116:119]
	v_mfma_f32_16x16x32_bf16 v[104:107], v[148:151], v[186:189], v[104:107]
	v_mfma_f32_16x16x32_bf16 v[100:103], v[156:159], v[186:189], v[100:103]
	v_mfma_f32_16x16x32_bf16 v[88:91], v[148:151], v[198:201], v[88:91]
	v_mfma_f32_16x16x32_bf16 v[84:87], v[156:159], v[198:201], v[84:87]
	v_mfma_f32_16x16x32_bf16 v[72:75], v[148:151], v[206:209], v[72:75]
	v_mfma_f32_16x16x32_bf16 v[68:71], v[156:159], v[206:209], v[68:71]
	v_mfma_f32_16x16x32_bf16 v[120:123], v[152:155], v[182:185], v[120:123]
	v_mfma_f32_16x16x32_bf16 v[116:119], v[160:163], v[182:185], v[116:119]
	v_mfma_f32_16x16x32_bf16 v[104:107], v[152:155], v[190:193], v[104:107]
	v_mfma_f32_16x16x32_bf16 v[100:103], v[160:163], v[190:193], v[100:103]
	v_mfma_f32_16x16x32_bf16 v[88:91], v[152:155], v[202:205], v[88:91]
	v_mfma_f32_16x16x32_bf16 v[84:87], v[160:163], v[202:205], v[84:87]
	v_mfma_f32_16x16x32_bf16 v[72:75], v[152:155], v[210:213], v[72:75]
	v_mfma_f32_16x16x32_bf16 v[68:71], v[160:163], v[210:213], v[68:71]
	s_setprio 0
	s_barrier
	s_add_i32 s15, s15, s26
	v_lshl_add_u64 v[214:215], s[16:17], 0, v[2:3]
	s_mov_b32 m0, s15
	ds_read_b128 v[178:181], v223 offset:16384
	ds_read_b128 v[182:185], v223 offset:17408
	ds_read_b128 v[186:189], v223 offset:18432
	ds_read_b128 v[190:193], v223 offset:19456
	ds_read_b128 v[198:201], v223 offset:20480
	ds_read_b128 v[202:205], v223 offset:21504
	ds_read_b128 v[206:209], v223 offset:22528
	ds_read_b128 v[210:213], v223 offset:23552
	global_load_lds_dwordx4 v[214:215], off
	s_add_i32 m0, s15, 0x2000
	v_lshl_add_u64 v[216:217], s[16:17], 0, v[168:169]
	s_add_u32 s16, s16, s18
	s_addc_u32 s17, s17, s19
	s_add_i32 s9, s9, s26
	global_load_lds_dwordx4 v[216:217], off
	v_lshl_add_u64 v[218:219], s[16:17], 0, v[2:3]
	s_mov_b32 m0, s9
	v_lshl_add_u64 v[232:233], s[16:17], 0, v[168:169]
	global_load_lds_dwordx4 v[218:219], off
	s_add_i32 m0, s9, 0x2000
	v_lshl_add_u64 v[234:235], s[4:5], 0, v[164:165]
	global_load_lds_dwordx4 v[232:233], off
	s_mov_b32 m0, s27
	v_lshl_add_u64 v[236:237], s[4:5], 0, v[166:167]
	global_load_lds_dwordx4 v[234:235], off
	s_mov_b32 m0, s36
	s_nop 0
	global_load_lds_dwordx4 v[236:237], off
	s_waitcnt vmcnt(8)
	s_waitcnt lgkmcnt(0)
	s_barrier
; #define PG8_STAGE(bufoff, gbase, voff) do { _Pragma("unroll") for (int _i = 0; _i < 2; ++_i) \
;         __builtin_amdgcn_global_load_lds((const unsigned*)((const char*)(gbase) + (voff)[_i]), (PG8_LAS unsigned*)(lds + (bufoff) + ldsw + _i * 8192), 16, 0, 0); } while (0)
; #define PG8_LDA(dst, b, h) do { _Pragma("unroll") for (int m = 0; m < 4; ++m) _Pragma("unroll") for (int k = 0; k < 2; ++k) dst[m][k] = *(const PG8_LAS bf16x8*)(lds + PG8_SA(b, h) + aoff + m * 2048 + k * 1024); } while (0)
; #define PG8_LDB(dst, b, h) do { _Pragma("unroll") for (int n = 0; n < 2; ++n) _Pragma("unroll") for (int k = 0; k < 2; ++k) dst[n][k] = *(const PG8_LAS bf16x8*)(lds + PG8_SB(b, h) + boff + n * 2048 + k * 1024); } while (0)
; #define PG8_MMA(ai, bj, At, Bt) do { __builtin_amdgcn_s_setprio(1); _Pragma("unroll") for (int m = 0; m < 4; ++m) _Pragma("unroll") for (int n = 0; n < 2; ++n) _Pragma("unroll") for (int k = 0; k < 2; ++k) \
;         acc[ai][bj][m][n] = __builtin_amdgcn_mfma_f32_16x16x32_bf16(Bt[n][k], At[m][k], acc[ai][bj][m][n], 0, 0, 0); __builtin_amdgcn_s_setprio(0); } while (0)
; #define PG8_WAIT_V(n) asm volatile("s_waitcnt vmcnt(" #n ")" ::: "memory")
; #define PG8_WAIT_L(n) asm volatile("s_waitcnt lgkmcnt(" #n ")" ::: "memory")
; #define PG8_BAR __builtin_amdgcn_s_barrier()
; #define PG8_SCHED __builtin_amdgcn_sched_barrier(0)
; template <class Epi, class Sched, bool ALIGN_EPI = false, bool SP2 = false, bool ACHUNK = false>
; __device__ __forceinline__ void gemm_phase(PG8_LAS unsigned char* lds, const Gemm g, const Sched& S, const Epi& E) {
;     ...
;             PG8_WAIT_V(8); PG8_WAIT_L(0); PG8_BAR; PG8_MMA(1, 0, At, B0); PG8_MMA(1, 1, At, B1); PG8_BAR; PG8_SCHED;
;             PG8_LDB(B0, 1, 0); PG8_LDB(B1, 1, 1); PG8_SCHED; PG8_LDA(At, 1, 0); PG8_STAGE(PG8_SA(0, 1), a2 + hstepA, voffA);
;             PG8_WAIT_V(8); PG8_WAIT_L(0); PG8_BAR; PG8_MMA(0, 0, At, B0); PG8_MMA(0, 1, At, B1); PG8_BAR; PG8_SCHED;
	s_setprio 1
	v_mfma_f32_16x16x32_bf16 v[64:67], v[132:135], v[178:181], v[64:67]
	v_mfma_f32_16x16x32_bf16 v[60:63], v[140:143], v[178:181], v[60:63]
	v_mfma_f32_16x16x32_bf16 v[48:51], v[132:135], v[186:189], v[48:51]
	v_mfma_f32_16x16x32_bf16 v[44:47], v[140:143], v[186:189], v[44:47]
	v_mfma_f32_16x16x32_bf16 v[32:35], v[132:135], v[198:201], v[32:35]
	v_mfma_f32_16x16x32_bf16 v[28:31], v[140:143], v[198:201], v[28:31]
	v_mfma_f32_16x16x32_bf16 v[16:19], v[132:135], v[206:209], v[16:19]
	v_mfma_f32_16x16x32_bf16 v[12:15], v[140:143], v[206:209], v[12:15]
	v_mfma_f32_16x16x32_bf16 v[64:67], v[136:139], v[182:185], v[64:67]
	v_mfma_f32_16x16x32_bf16 v[60:63], v[144:147], v[182:185], v[60:63]
	v_mfma_f32_16x16x32_bf16 v[48:51], v[136:139], v[190:193], v[48:51]
	v_mfma_f32_16x16x32_bf16 v[44:47], v[144:147], v[190:193], v[44:47]
	v_mfma_f32_16x16x32_bf16 v[32:35], v[136:139], v[202:205], v[32:35]
	v_mfma_f32_16x16x32_bf16 v[28:31], v[144:147], v[202:205], v[28:31]
	v_mfma_f32_16x16x32_bf16 v[16:19], v[136:139], v[210:213], v[16:19]
	v_mfma_f32_16x16x32_bf16 v[12:15], v[144:147], v[210:213], v[12:15]
	s_setprio 0
	s_setprio 1
	v_mfma_f32_16x16x32_bf16 v[56:59], v[148:151], v[178:181], v[56:59]
	v_mfma_f32_16x16x32_bf16 v[52:55], v[156:159], v[178:181], v[52:55]
	v_mfma_f32_16x16x32_bf16 v[40:43], v[148:151], v[186:189], v[40:43]
	v_mfma_f32_16x16x32_bf16 v[36:39], v[156:159], v[186:189], v[36:39]
	v_mfma_f32_16x16x32_bf16 v[24:27], v[148:151], v[198:201], v[24:27]
	v_mfma_f32_16x16x32_bf16 v[20:23], v[156:159], v[198:201], v[20:23]
	v_mfma_f32_16x16x32_bf16 v[8:11], v[148:151], v[206:209], v[8:11]
	v_mfma_f32_16x16x32_bf16 v[4:7], v[156:159], v[206:209], v[4:7]
	v_mfma_f32_16x16x32_bf16 v[56:59], v[152:155], v[182:185], v[56:59]
	v_mfma_f32_16x16x32_bf16 v[52:55], v[160:163], v[182:185], v[52:55]
	v_mfma_f32_16x16x32_bf16 v[40:43], v[152:155], v[190:193], v[40:43]
	v_mfma_f32_16x16x32_bf16 v[36:39], v[160:163], v[190:193], v[36:39]
	v_mfma_f32_16x16x32_bf16 v[24:27], v[152:155], v[202:205], v[24:27]
	v_mfma_f32_16x16x32_bf16 v[20:23], v[160:163], v[202:205], v[20:23]
	v_mfma_f32_16x16x32_bf16 v[8:11], v[152:155], v[210:213], v[8:11]
	v_mfma_f32_16x16x32_bf16 v[4:7], v[160:163], v[210:213], v[4:7]
	s_setprio 0
	s_barrier
	s_add_i32 s9, 0, 0x18000
	s_add_i32 s15, 0, 0x1c000
	v_add_u32_e32 v144, s9, v221
	v_add_u32_e32 v160, s15, v221
	ds_read_b128 v[132:135], v144
	ds_read_b128 v[136:139], v144 offset:1024
	ds_read_b128 v[140:143], v144 offset:2048
	ds_read_b128 v[144:147], v144 offset:3072
	ds_read_b128 v[148:151], v160
	ds_read_b128 v[152:155], v160 offset:1024
	ds_read_b128 v[156:159], v160 offset:2048
	ds_read_b128 v[160:163], v160 offset:3072
	s_add_u32 s4, s4, s18
	s_addc_u32 s5, s5, s19
	s_mov_b32 m0, s37
	v_lshl_add_u64 v[238:239], s[4:5], 0, v[164:165]
	ds_read_b128 v[178:181], v223 offset:32768
	ds_read_b128 v[182:185], v223 offset:33792
	ds_read_b128 v[186:189], v223 offset:34816
	ds_read_b128 v[190:193], v223 offset:35840
	ds_read_b128 v[198:201], v223 offset:36864
	ds_read_b128 v[202:205], v223 offset:37888
	ds_read_b128 v[206:209], v223 offset:38912
	ds_read_b128 v[210:213], v223 offset:39936
	global_load_lds_dwordx4 v[238:239], off
	v_lshl_add_u64 v[238:239], s[4:5], 0, v[166:167]
	s_mov_b32 m0, s76
	s_nop 0
	global_load_lds_dwordx4 v[238:239], off
	s_waitcnt vmcnt(8)
	s_waitcnt lgkmcnt(0)
	s_barrier
	s_setprio 1
	v_mfma_f32_16x16x32_bf16 v[128:131], v[132:135], v[178:181], v[128:131]
	v_mfma_f32_16x16x32_bf16 v[124:127], v[140:143], v[178:181], v[124:127]
	v_mfma_f32_16x16x32_bf16 v[112:115], v[132:135], v[186:189], v[112:115]
	v_mfma_f32_16x16x32_bf16 v[108:111], v[140:143], v[186:189], v[108:111]
	v_mfma_f32_16x16x32_bf16 v[96:99], v[132:135], v[198:201], v[96:99]
	v_mfma_f32_16x16x32_bf16 v[92:95], v[140:143], v[198:201], v[92:95]
	v_mfma_f32_16x16x32_bf16 v[80:83], v[132:135], v[206:209], v[80:83]
	v_mfma_f32_16x16x32_bf16 v[76:79], v[140:143], v[206:209], v[76:79]
	v_mfma_f32_16x16x32_bf16 v[128:131], v[136:139], v[182:185], v[128:131]
	v_mfma_f32_16x16x32_bf16 v[124:127], v[144:147], v[182:185], v[124:127]
	v_mfma_f32_16x16x32_bf16 v[112:115], v[136:139], v[190:193], v[112:115]
	v_mfma_f32_16x16x32_bf16 v[108:111], v[144:147], v[190:193], v[108:111]
	v_mfma_f32_16x16x32_bf16 v[96:99], v[136:139], v[202:205], v[96:99]
	v_mfma_f32_16x16x32_bf16 v[92:95], v[144:147], v[202:205], v[92:95]
	v_mfma_f32_16x16x32_bf16 v[80:83], v[136:139], v[210:213], v[80:83]
	v_mfma_f32_16x16x32_bf16 v[76:79], v[144:147], v[210:213], v[76:79]
	s_setprio 0
	s_setprio 1
	v_mfma_f32_16x16x32_bf16 v[120:123], v[148:151], v[178:181], v[120:123]
	v_mfma_f32_16x16x32_bf16 v[116:119], v[156:159], v[178:181], v[116:119]
	v_mfma_f32_16x16x32_bf16 v[104:107], v[148:151], v[186:189], v[104:107]
	v_mfma_f32_16x16x32_bf16 v[100:103], v[156:159], v[186:189], v[100:103]
	v_mfma_f32_16x16x32_bf16 v[88:91], v[148:151], v[198:201], v[88:91]
	v_mfma_f32_16x16x32_bf16 v[84:87], v[156:159], v[198:201], v[84:87]
	v_mfma_f32_16x16x32_bf16 v[72:75], v[148:151], v[206:209], v[72:75]
	v_mfma_f32_16x16x32_bf16 v[68:71], v[156:159], v[206:209], v[68:71]
	v_mfma_f32_16x16x32_bf16 v[120:123], v[152:155], v[182:185], v[120:123]
	v_mfma_f32_16x16x32_bf16 v[116:119], v[160:163], v[182:185], v[116:119]
	v_mfma_f32_16x16x32_bf16 v[104:107], v[152:155], v[190:193], v[104:107]
	v_mfma_f32_16x16x32_bf16 v[100:103], v[160:163], v[190:193], v[100:103]
	v_mfma_f32_16x16x32_bf16 v[88:91], v[152:155], v[202:205], v[88:91]
	v_mfma_f32_16x16x32_bf16 v[84:87], v[160:163], v[202:205], v[84:87]
	v_mfma_f32_16x16x32_bf16 v[72:75], v[152:155], v[210:213], v[72:75]
	v_mfma_f32_16x16x32_bf16 v[68:71], v[160:163], v[210:213], v[68:71]
	s_setprio 0
	s_barrier
; #define PG8_STAGE(bufoff, gbase, voff) do { _Pragma("unroll") for (int _i = 0; _i < 2; ++_i) \
;         __builtin_amdgcn_global_load_lds((const unsigned*)((const char*)(gbase) + (voff)[_i]), (PG8_LAS unsigned*)(lds + (bufoff) + ldsw + _i * 8192), 16, 0, 0); } while (0)
; #define PG8_LDA(dst, b, h) do { _Pragma("unroll") for (int m = 0; m < 4; ++m) _Pragma("unroll") for (int k = 0; k < 2; ++k) dst[m][k] = *(const PG8_LAS bf16x8*)(lds + PG8_SA(b, h) + aoff + m * 2048 + k * 1024); } while (0)
; #define PG8_MMA(ai, bj, At, Bt) do { __builtin_amdgcn_s_setprio(1); _Pragma("unroll") for (int m = 0; m < 4; ++m) _Pragma("unroll") for (int n = 0; n < 2; ++n) _Pragma("unroll") for (int k = 0; k < 2; ++k) \
;         acc[ai][bj][m][n] = __builtin_amdgcn_mfma_f32_16x16x32_bf16(Bt[n][k], At[m][k], acc[ai][bj][m][n], 0, 0, 0); __builtin_amdgcn_s_setprio(0); } while (0)
; #define PG8_WAIT_V(n) asm volatile("s_waitcnt vmcnt(" #n ")" ::: "memory")
; #define PG8_WAIT_L(n) asm volatile("s_waitcnt lgkmcnt(" #n ")" ::: "memory")
; #define PG8_BAR __builtin_amdgcn_s_barrier()
; #define PG8_SCHED __builtin_amdgcn_sched_barrier(0)
; template <class Epi, class Sched, bool ALIGN_EPI = false, bool SP2 = false, bool ACHUNK = false>
; __device__ __forceinline__ void gemm_phase(PG8_LAS unsigned char* lds, const Gemm g, const Sched& S, const Epi& E) {
;     ...
;         for (int t = 0; t < nt; t += 2) {
;     ...
;             PG8_LDA(At, 1, 1); PG8_STAGE(PG8_SB(1, 0), b3, voffB); PG8_STAGE(PG8_SB(1, 1), b3 + hstepB, voffB); PG8_STAGE(PG8_SA(1, 0), a3, voffA);
;             PG8_WAIT_V(8); PG8_WAIT_L(0); PG8_BAR; PG8_MMA(1, 0, At, B0); PG8_MMA(1, 1, At, B1); PG8_BAR; PG8_SCHED;
	s_add_i32 s4, s9, s26
	v_lshl_add_u64 v[214:215], v[214:215], 0, s[10:11]
	s_mov_b32 m0, s4
	ds_read_b128 v[178:181], v223 offset:49152
	ds_read_b128 v[182:185], v223 offset:50176
	ds_read_b128 v[186:189], v223 offset:51200
	ds_read_b128 v[190:193], v223 offset:52224
	ds_read_b128 v[198:201], v223 offset:53248
	ds_read_b128 v[202:205], v223 offset:54272
	ds_read_b128 v[206:209], v223 offset:55296
	ds_read_b128 v[210:213], v223 offset:56320
	global_load_lds_dwordx4 v[214:215], off
	v_lshl_add_u64 v[214:215], v[216:217], 0, s[10:11]
	s_add_i32 m0, s4, 0x2000
	s_add_i32 s4, s15, s26
	global_load_lds_dwordx4 v[214:215], off
	v_lshl_add_u64 v[214:215], v[218:219], 0, s[10:11]
	s_mov_b32 m0, s4
	s_nop 0
	global_load_lds_dwordx4 v[214:215], off
	v_lshl_add_u64 v[214:215], v[232:233], 0, s[10:11]
	s_add_i32 m0, s4, 0x2000
	s_nop 0
	global_load_lds_dwordx4 v[214:215], off
	v_lshl_add_u64 v[214:215], v[234:235], 0, s[10:11]
	s_mov_b32 m0, s77
	s_nop 0
	global_load_lds_dwordx4 v[214:215], off
	v_lshl_add_u64 v[214:215], v[236:237], 0, s[10:11]
	s_mov_b32 m0, s78
	s_nop 0
	global_load_lds_dwordx4 v[214:215], off
	s_waitcnt vmcnt(8)
	s_waitcnt lgkmcnt(0)
	s_barrier
	s_setprio 1
	v_mfma_f32_16x16x32_bf16 v[64:67], v[132:135], v[178:181], v[64:67]
	v_mfma_f32_16x16x32_bf16 v[60:63], v[140:143], v[178:181], v[60:63]
	v_mfma_f32_16x16x32_bf16 v[48:51], v[132:135], v[186:189], v[48:51]
	v_mfma_f32_16x16x32_bf16 v[44:47], v[140:143], v[186:189], v[44:47]
	v_mfma_f32_16x16x32_bf16 v[32:35], v[132:135], v[198:201], v[32:35]
	v_mfma_f32_16x16x32_bf16 v[28:31], v[140:143], v[198:201], v[28:31]
	v_mfma_f32_16x16x32_bf16 v[16:19], v[132:135], v[206:209], v[16:19]
	v_mfma_f32_16x16x32_bf16 v[12:15], v[140:143], v[206:209], v[12:15]
	v_mfma_f32_16x16x32_bf16 v[64:67], v[136:139], v[182:185], v[64:67]
	v_mfma_f32_16x16x32_bf16 v[60:63], v[144:147], v[182:185], v[60:63]
	v_mfma_f32_16x16x32_bf16 v[48:51], v[136:139], v[190:193], v[48:51]
	v_mfma_f32_16x16x32_bf16 v[44:47], v[144:147], v[190:193], v[44:47]
	v_mfma_f32_16x16x32_bf16 v[32:35], v[136:139], v[202:205], v[32:35]
	v_mfma_f32_16x16x32_bf16 v[28:31], v[144:147], v[202:205], v[28:31]
	v_mfma_f32_16x16x32_bf16 v[16:19], v[136:139], v[210:213], v[16:19]
	v_mfma_f32_16x16x32_bf16 v[12:15], v[144:147], v[210:213], v[12:15]
	s_setprio 0
	s_setprio 1
	v_mfma_f32_16x16x32_bf16 v[56:59], v[148:151], v[178:181], v[56:59]
	v_mfma_f32_16x16x32_bf16 v[52:55], v[156:159], v[178:181], v[52:55]
	v_mfma_f32_16x16x32_bf16 v[40:43], v[148:151], v[186:189], v[40:43]
	v_mfma_f32_16x16x32_bf16 v[36:39], v[156:159], v[186:189], v[36:39]
	v_mfma_f32_16x16x32_bf16 v[24:27], v[148:151], v[198:201], v[24:27]
	v_mfma_f32_16x16x32_bf16 v[20:23], v[156:159], v[198:201], v[20:23]
	v_mfma_f32_16x16x32_bf16 v[8:11], v[148:151], v[206:209], v[8:11]
	v_mfma_f32_16x16x32_bf16 v[4:7], v[156:159], v[206:209], v[4:7]
	v_mfma_f32_16x16x32_bf16 v[56:59], v[152:155], v[182:185], v[56:59]
	v_mfma_f32_16x16x32_bf16 v[52:55], v[160:163], v[182:185], v[52:55]
	v_mfma_f32_16x16x32_bf16 v[40:43], v[152:155], v[190:193], v[40:43]
	v_mfma_f32_16x16x32_bf16 v[36:39], v[160:163], v[190:193], v[36:39]
	v_mfma_f32_16x16x32_bf16 v[24:27], v[152:155], v[202:205], v[24:27]
	v_mfma_f32_16x16x32_bf16 v[20:23], v[160:163], v[202:205], v[20:23]
	v_mfma_f32_16x16x32_bf16 v[8:11], v[152:155], v[210:213], v[8:11]
	v_mfma_f32_16x16x32_bf16 v[4:7], v[160:163], v[210:213], v[4:7]
	s_setprio 0
	s_barrier
	s_add_u32 s0, s0, 0x100
	s_addc_u32 s1, s1, 0
	s_add_u32 s6, s6, 0x100
	s_addc_u32 s7, s7, 0
	s_cmp_ge_i32 s8, s80
	s_mov_b32 s4, s8
	s_cbranch_scc0 .LBB0_431
